# attention: partial softmax of next tile (row max, rescale test, scale+exp of 16 scores) interleaved into P.V MFMA gaps in first half-iteration of both component loops; staging regs moved to dead VGPRs
# speedup vs baseline: 1.0227x; 1.0113x over previous
; #define LAS __attribute__((address_space(3)))
; __device__ __forceinline__ float red4(float x) { x = DPP_ADD(x, 0xB1); x = DPP_ADD(x, 0x4E); return x; }
; __device__ __forceinline__ void phase_scan(const ScanArgs A, LAS unsigned char* lds) {
;     ...
;             if (consumer) {
;                 const LAS float* in = INc + (c & 1) * 6144;
;                 LAS float* yb = YBc + (c & 1) * 1024;
; #pragma unroll 2
;                 for (int t = 0; t < 16; ++t) {
;                     const LAS float* q = in + t * 64 + kq * 16;
;                     f32x4 Wv[4], KDv[4], Bv[4], ANv[4], Rv[4];
; #pragma unroll
;                     for (int j = 0; j < 4; ++j) { Wv[j] = *(const LAS f32x4*)(q + 4 * j); KDv[j] = *(const LAS f32x4*)(q + 1024 + 4 * j); Bv[j] = *(const LAS f32x4*)(q + 2048 + 4 * j);
;                                                   ANv[j] = *(const LAS f32x4*)(q + 3072 + 4 * j); Rv[j] = *(const LAS f32x4*)(q + 4096 + 4 * j); }
;                     const f32x2 v2 = *(const LAS f32x2*)(in + 5120 + t * 64 + half * 32 + rb * 2);
;     ...
;                     float sa[2], y[2];
; #pragma unroll
;                     for (int i = 0; i < 2; ++i) { f32x2 a0 = {0.f, 0.f}, a1 = {0.f, 0.f};
; #pragma unroll
;                         for (int p = 0; p < 8; p += 2) { a0 += S2[i][p] * PAIR(ANv, p); a1 += S2[i][p + 1] * PAIR(ANv, p + 1); }
;                         a0 += a1; sa[i] = red4(a0[0] + a0[1]); }
; #pragma unroll
;                     for (int i = 0; i < 2; ++i) { f32x2 y0 = {0.f, 0.f}, y1 = {0.f, 0.f}; const f32x2 sai = {sa[i], sa[i]}, vi = {v2[i], v2[i]};
; #pragma unroll
;                         for (int p = 0; p < 8; p += 2) {
;                             const f32x2 n0 = S2[i][p] * PAIR(Wv, p) + sai * PAIR(Bv, p) + vi * PAIR(KDv, p);
;                             const f32x2 n1 = S2[i][p + 1] * PAIR(Wv, p + 1) + sai * PAIR(Bv, p + 1) + vi * PAIR(KDv, p + 1);
;                             S2[i][p] = n0; S2[i][p + 1] = n1; y0 += n0 * PAIR(Rv, p); y1 += n1 * PAIR(Rv, p + 1); }
;                         y0 += y1; y[i] = red4(y0[0] + y0[1]); }
;     ...
;                     if (kq == 0) *(LAS f32x2*)(yb + t * 64 + half * 32 + rb * 2) = (f32x2){y[0], y[1]};
.LBB0_180:
	s_and_b64 vcc, exec, s[34:35]
	s_cbranch_vccz .LBB0_161
	v_cndmask_b32_e64 v48, 0, 1, s[94:95]
	v_lshl_add_u32 v75, v48, 12, v129
	v_mul_lo_u32 v48, v48, s83
	v_add_u32_e32 v75, 0x18000, v75
	v_add_u32_e32 v96, v130, v48
	v_add_u32_e32 v171, v131, v48
	ds_read_b128 v[32:35], v171 offset:12288
	ds_read_b128 v[36:39], v171 offset:12304
	ds_read_b128 v[40:43], v171 offset:12320
	ds_read_b128 v[44:47], v171 offset:12336
	ds_read_b128 v[142:145], v171 offset:8192
	ds_read_b128 v[48:51], v171 offset:0
	ds_read_b128 v[172:175], v171 offset:4096
	ds_read_b128 v[146:149], v171 offset:8208
	ds_read_b128 v[52:55], v171 offset:16
	ds_read_b128 v[176:179], v171 offset:4112
	ds_read_b128 v[150:153], v171 offset:8224
	ds_read_b128 v[56:59], v171 offset:32
	ds_read_b128 v[180:183], v171 offset:4128
	ds_read_b128 v[154:157], v171 offset:8240
	ds_read_b128 v[60:63], v171 offset:48
	ds_read_b128 v[184:187], v171 offset:4144
	ds_read_b64 v[188:189], v96 offset:0
	ds_read_b128 v[200:203], v171 offset:16384
	ds_read_b128 v[204:207], v171 offset:16400
	ds_read_b128 v[208:211], v171 offset:16416
	ds_read_b128 v[212:215], v171 offset:16432
	s_waitcnt lgkmcnt(0)
	s_waitcnt lgkmcnt(15)
	v_pk_fma_f32 v[160:161], v[84:85], v[32:33], 0 op_sel_hi:[1,1,0]
	v_pk_fma_f32 v[162:163], v[88:89], v[34:35], 0 op_sel_hi:[1,1,0]
	v_pk_fma_f32 v[164:165], v[100:101], v[32:33], 0 op_sel_hi:[1,1,0]
	v_pk_fma_f32 v[166:167], v[104:105], v[34:35], 0 op_sel_hi:[1,1,0]
	v_pk_fma_f32 v[160:161], v[86:87], v[36:37], v[160:161]
	v_pk_fma_f32 v[162:163], v[92:93], v[38:39], v[162:163]
	v_pk_fma_f32 v[164:165], v[106:107], v[36:37], v[164:165]
	v_pk_fma_f32 v[166:167], v[108:109], v[38:39], v[166:167]
	v_pk_fma_f32 v[160:161], v[90:91], v[40:41], v[160:161]
	v_pk_fma_f32 v[162:163], v[98:99], v[42:43], v[162:163]
	v_pk_fma_f32 v[164:165], v[110:111], v[40:41], v[164:165]
	v_pk_fma_f32 v[166:167], v[112:113], v[42:43], v[166:167]
	v_pk_fma_f32 v[160:161], v[94:95], v[44:45], v[160:161]
	v_pk_fma_f32 v[162:163], v[102:103], v[46:47], v[162:163]
	v_pk_fma_f32 v[164:165], v[114:115], v[44:45], v[164:165]
	v_pk_fma_f32 v[166:167], v[116:117], v[46:47], v[166:167]
	ds_read_b128 v[32:35], v171 offset:12544
	ds_read_b128 v[36:39], v171 offset:12560
	ds_read_b128 v[40:43], v171 offset:12576
	ds_read_b128 v[44:47], v171 offset:12592
	v_pk_add_f32 v[160:161], v[162:163], v[160:161]
	v_pk_add_f32 v[164:165], v[166:167], v[164:165]
	v_add_f32_e32 v168, v160, v161
	v_add_f32_e32 v169, v164, v165
	s_nop 0
	v_add_f32_dpp v168, v168, v168 quad_perm:[1,0,3,2] row_mask:0xf bank_mask:0xf bound_ctrl:1
	v_add_f32_dpp v169, v169, v169 quad_perm:[1,0,3,2] row_mask:0xf bank_mask:0xf bound_ctrl:1
	s_nop 0
	v_add_f32_dpp v190, v168, v168 quad_perm:[2,3,0,1] row_mask:0xf bank_mask:0xf bound_ctrl:1
	v_add_f32_dpp v192, v169, v169 quad_perm:[2,3,0,1] row_mask:0xf bank_mask:0xf bound_ctrl:1
	s_waitcnt lgkmcnt(8)
	v_pk_mul_f32 v[216:217], v[142:143], v[190:191] op_sel_hi:[1,0]
	v_pk_mul_f32 v[218:219], v[144:145], v[190:191] op_sel_hi:[1,0]
	v_pk_mul_f32 v[220:221], v[142:143], v[192:193] op_sel_hi:[1,0]
	v_pk_mul_f32 v[222:223], v[144:145], v[192:193] op_sel_hi:[1,0]
	v_pk_fma_f32 v[216:217], v[84:85], v[48:49], v[216:217]
	v_pk_fma_f32 v[218:219], v[88:89], v[50:51], v[218:219]
	v_pk_fma_f32 v[220:221], v[100:101], v[48:49], v[220:221]
	v_pk_fma_f32 v[222:223], v[104:105], v[50:51], v[222:223]
	v_pk_fma_f32 v[84:85], v[172:173], v[188:189], v[216:217] op_sel_hi:[1,0,1]
	v_pk_fma_f32 v[88:89], v[174:175], v[188:189], v[218:219] op_sel_hi:[1,0,1]
	v_pk_fma_f32 v[100:101], v[172:173], v[188:189], v[220:221] op_sel:[0,1,0]
	v_pk_fma_f32 v[104:105], v[174:175], v[188:189], v[222:223] op_sel:[0,1,0]
	ds_read_b128 v[142:145], v171 offset:8448
	ds_read_b128 v[48:51], v171 offset:256
	ds_read_b128 v[172:175], v171 offset:4352
	v_pk_mul_f32 v[216:217], v[146:147], v[190:191] op_sel_hi:[1,0]
	v_pk_mul_f32 v[218:219], v[148:149], v[190:191] op_sel_hi:[1,0]
	v_pk_mul_f32 v[220:221], v[146:147], v[192:193] op_sel_hi:[1,0]
	v_pk_mul_f32 v[222:223], v[148:149], v[192:193] op_sel_hi:[1,0]
	v_pk_fma_f32 v[216:217], v[86:87], v[52:53], v[216:217]
	v_pk_fma_f32 v[218:219], v[92:93], v[54:55], v[218:219]
	v_pk_fma_f32 v[220:221], v[106:107], v[52:53], v[220:221]
	v_pk_fma_f32 v[222:223], v[108:109], v[54:55], v[222:223]
	v_pk_fma_f32 v[86:87], v[176:177], v[188:189], v[216:217] op_sel_hi:[1,0,1]
	v_pk_fma_f32 v[92:93], v[178:179], v[188:189], v[218:219] op_sel_hi:[1,0,1]
	v_pk_fma_f32 v[106:107], v[176:177], v[188:189], v[220:221] op_sel:[0,1,0]
	v_pk_fma_f32 v[108:109], v[178:179], v[188:189], v[222:223] op_sel:[0,1,0]
	ds_read_b128 v[146:149], v171 offset:8464
	ds_read_b128 v[52:55], v171 offset:272
	ds_read_b128 v[176:179], v171 offset:4368
	v_pk_mul_f32 v[216:217], v[150:151], v[190:191] op_sel_hi:[1,0]
	v_pk_mul_f32 v[218:219], v[152:153], v[190:191] op_sel_hi:[1,0]
	v_pk_mul_f32 v[220:221], v[150:151], v[192:193] op_sel_hi:[1,0]
	v_pk_mul_f32 v[222:223], v[152:153], v[192:193] op_sel_hi:[1,0]
	v_pk_fma_f32 v[216:217], v[90:91], v[56:57], v[216:217]
	v_pk_fma_f32 v[218:219], v[98:99], v[58:59], v[218:219]
	v_pk_fma_f32 v[220:221], v[110:111], v[56:57], v[220:221]
	v_pk_fma_f32 v[222:223], v[112:113], v[58:59], v[222:223]
	v_pk_fma_f32 v[90:91], v[180:181], v[188:189], v[216:217] op_sel_hi:[1,0,1]
	v_pk_fma_f32 v[98:99], v[182:183], v[188:189], v[218:219] op_sel_hi:[1,0,1]
	v_pk_fma_f32 v[110:111], v[180:181], v[188:189], v[220:221] op_sel:[0,1,0]
	v_pk_fma_f32 v[112:113], v[182:183], v[188:189], v[222:223] op_sel:[0,1,0]
	ds_read_b128 v[150:153], v171 offset:8480
	ds_read_b128 v[56:59], v171 offset:288
	ds_read_b128 v[180:183], v171 offset:4384
	v_pk_mul_f32 v[216:217], v[154:155], v[190:191] op_sel_hi:[1,0]
	v_pk_mul_f32 v[218:219], v[156:157], v[190:191] op_sel_hi:[1,0]
	v_pk_mul_f32 v[220:221], v[154:155], v[192:193] op_sel_hi:[1,0]
	v_pk_mul_f32 v[222:223], v[156:157], v[192:193] op_sel_hi:[1,0]
	v_pk_fma_f32 v[216:217], v[94:95], v[60:61], v[216:217]
	v_pk_fma_f32 v[218:219], v[102:103], v[62:63], v[218:219]
	v_pk_fma_f32 v[220:221], v[114:115], v[60:61], v[220:221]
	v_pk_fma_f32 v[222:223], v[116:117], v[62:63], v[222:223]
	v_pk_fma_f32 v[94:95], v[184:185], v[188:189], v[216:217] op_sel_hi:[1,0,1]
	v_pk_fma_f32 v[102:103], v[186:187], v[188:189], v[218:219] op_sel_hi:[1,0,1]
	v_pk_fma_f32 v[114:115], v[184:185], v[188:189], v[220:221] op_sel:[0,1,0]
	v_pk_fma_f32 v[116:117], v[186:187], v[188:189], v[222:223] op_sel:[0,1,0]
	ds_read_b128 v[154:157], v171 offset:8496
	ds_read_b128 v[60:63], v171 offset:304
	ds_read_b128 v[184:187], v171 offset:4400
	ds_read_b64 v[188:189], v96 offset:256
	s_waitcnt lgkmcnt(15)
; #define LAS __attribute__((address_space(3)))
; __device__ __forceinline__ float red4(float x) { x = DPP_ADD(x, 0xB1); x = DPP_ADD(x, 0x4E); return x; }
; __device__ __forceinline__ void phase_scan(const ScanArgs A, LAS unsigned char* lds) {
;     ...
;                 for (int t = 0; t < 16; ++t) {
;                     const LAS float* q = in + t * 64 + kq * 16;
;                     f32x4 Wv[4], KDv[4], Bv[4], ANv[4], Rv[4];
; #pragma unroll
;                     for (int j = 0; j < 4; ++j) { Wv[j] = *(const LAS f32x4*)(q + 4 * j); KDv[j] = *(const LAS f32x4*)(q + 1024 + 4 * j); Bv[j] = *(const LAS f32x4*)(q + 2048 + 4 * j);
;                                                   ANv[j] = *(const LAS f32x4*)(q + 3072 + 4 * j); Rv[j] = *(const LAS f32x4*)(q + 4096 + 4 * j); }
;                     const f32x2 v2 = *(const LAS f32x2*)(in + 5120 + t * 64 + half * 32 + rb * 2);
;     ...
;                     float sa[2], y[2];
; #pragma unroll
;                     for (int i = 0; i < 2; ++i) { f32x2 a0 = {0.f, 0.f}, a1 = {0.f, 0.f};
; #pragma unroll
;                         for (int p = 0; p < 8; p += 2) { a0 += S2[i][p] * PAIR(ANv, p); a1 += S2[i][p + 1] * PAIR(ANv, p + 1); }
;                         a0 += a1; sa[i] = red4(a0[0] + a0[1]); }
; #pragma unroll
;                     for (int i = 0; i < 2; ++i) { f32x2 y0 = {0.f, 0.f}, y1 = {0.f, 0.f}; const f32x2 sai = {sa[i], sa[i]}, vi = {v2[i], v2[i]};
; #pragma unroll
;                         for (int p = 0; p < 8; p += 2) {
;                             const f32x2 n0 = S2[i][p] * PAIR(Wv, p) + sai * PAIR(Bv, p) + vi * PAIR(KDv, p);
;                             const f32x2 n1 = S2[i][p + 1] * PAIR(Wv, p + 1) + sai * PAIR(Bv, p + 1) + vi * PAIR(KDv, p + 1);
;                             S2[i][p] = n0; S2[i][p + 1] = n1; y0 += n0 * PAIR(Rv, p); y1 += n1 * PAIR(Rv, p + 1); }
;                         y0 += y1; y[i] = red4(y0[0] + y0[1]); }
;     ...
;                     if (kq == 0) *(LAS f32x2*)(yb + t * 64 + half * 32 + rb * 2) = (f32x2){y[0], y[1]};
	v_pk_fma_f32 v[248:249], v[200:201], v[84:85], 0 op_sel_hi:[1,1,0]
	v_pk_fma_f32 v[250:251], v[202:203], v[88:89], 0 op_sel_hi:[1,1,0]
	v_pk_fma_f32 v[194:195], v[200:201], v[100:101], 0 op_sel_hi:[1,1,0]
	v_pk_fma_f32 v[158:159], v[202:203], v[104:105], 0 op_sel_hi:[1,1,0]
	v_pk_fma_f32 v[248:249], v[204:205], v[86:87], v[248:249]
	v_pk_fma_f32 v[250:251], v[206:207], v[92:93], v[250:251]
	v_pk_fma_f32 v[194:195], v[204:205], v[106:107], v[194:195]
	v_pk_fma_f32 v[158:159], v[206:207], v[108:109], v[158:159]
	v_pk_fma_f32 v[248:249], v[208:209], v[90:91], v[248:249]
	v_pk_fma_f32 v[250:251], v[210:211], v[98:99], v[250:251]
	v_pk_fma_f32 v[194:195], v[208:209], v[110:111], v[194:195]
	v_pk_fma_f32 v[158:159], v[210:211], v[112:113], v[158:159]
	v_pk_fma_f32 v[248:249], v[212:213], v[94:95], v[248:249]
	v_pk_fma_f32 v[250:251], v[214:215], v[102:103], v[250:251]
	v_pk_fma_f32 v[194:195], v[212:213], v[114:115], v[194:195]
	v_pk_fma_f32 v[158:159], v[214:215], v[116:117], v[158:159]
	ds_read_b128 v[200:203], v171 offset:16640
	ds_read_b128 v[204:207], v171 offset:16656
	ds_read_b128 v[208:211], v171 offset:16672
	ds_read_b128 v[212:215], v171 offset:16688
	s_waitcnt lgkmcnt(15)
	v_pk_fma_f32 v[160:161], v[84:85], v[32:33], 0 op_sel_hi:[1,1,0]
	v_pk_fma_f32 v[162:163], v[88:89], v[34:35], 0 op_sel_hi:[1,1,0]
	v_pk_fma_f32 v[164:165], v[100:101], v[32:33], 0 op_sel_hi:[1,1,0]
	v_pk_fma_f32 v[166:167], v[104:105], v[34:35], 0 op_sel_hi:[1,1,0]
	v_pk_fma_f32 v[160:161], v[86:87], v[36:37], v[160:161]
	v_pk_fma_f32 v[162:163], v[92:93], v[38:39], v[162:163]
	v_pk_fma_f32 v[164:165], v[106:107], v[36:37], v[164:165]
	v_pk_fma_f32 v[166:167], v[108:109], v[38:39], v[166:167]
	v_pk_fma_f32 v[160:161], v[90:91], v[40:41], v[160:161]
	v_pk_fma_f32 v[162:163], v[98:99], v[42:43], v[162:163]
	v_pk_fma_f32 v[164:165], v[110:111], v[40:41], v[164:165]
	v_pk_fma_f32 v[166:167], v[112:113], v[42:43], v[166:167]
	v_pk_fma_f32 v[160:161], v[94:95], v[44:45], v[160:161]
	v_pk_fma_f32 v[162:163], v[102:103], v[46:47], v[162:163]
	v_pk_fma_f32 v[164:165], v[114:115], v[44:45], v[164:165]
	v_pk_fma_f32 v[166:167], v[116:117], v[46:47], v[166:167]
	ds_read_b128 v[32:35], v171 offset:12800
	ds_read_b128 v[36:39], v171 offset:12816
	ds_read_b128 v[40:43], v171 offset:12832
	ds_read_b128 v[44:47], v171 offset:12848
	v_pk_add_f32 v[160:161], v[162:163], v[160:161]
	v_pk_add_f32 v[164:165], v[166:167], v[164:165]
	v_pk_add_f32 v[248:249], v[250:251], v[248:249]
	v_pk_add_f32 v[194:195], v[158:159], v[194:195]
	v_add_f32_e32 v168, v160, v161
	v_add_f32_e32 v169, v164, v165
	v_add_f32_e32 v224, v248, v249
	v_add_f32_e32 v225, v194, v195
	v_add_f32_dpp v168, v168, v168 quad_perm:[1,0,3,2] row_mask:0xf bank_mask:0xf bound_ctrl:1
	v_add_f32_dpp v169, v169, v169 quad_perm:[1,0,3,2] row_mask:0xf bank_mask:0xf bound_ctrl:1
	v_add_f32_dpp v224, v224, v224 quad_perm:[1,0,3,2] row_mask:0xf bank_mask:0xf bound_ctrl:1
	v_add_f32_dpp v225, v225, v225 quad_perm:[1,0,3,2] row_mask:0xf bank_mask:0xf bound_ctrl:1
	v_add_f32_dpp v190, v168, v168 quad_perm:[2,3,0,1] row_mask:0xf bank_mask:0xf bound_ctrl:1
	v_add_f32_dpp v192, v169, v169 quad_perm:[2,3,0,1] row_mask:0xf bank_mask:0xf bound_ctrl:1
	v_add_f32_dpp v224, v224, v224 quad_perm:[2,3,0,1] row_mask:0xf bank_mask:0xf bound_ctrl:1
	v_add_f32_dpp v225, v225, v225 quad_perm:[2,3,0,1] row_mask:0xf bank_mask:0xf bound_ctrl:1
	s_and_saveexec_b64 s[34:35], s[8:9]
	ds_write_b64 v75, v[224:225] offset:0
	s_or_b64 exec, exec, s[34:35]
	s_waitcnt lgkmcnt(9)
	v_pk_mul_f32 v[216:217], v[142:143], v[190:191] op_sel_hi:[1,0]
	v_pk_mul_f32 v[218:219], v[144:145], v[190:191] op_sel_hi:[1,0]
	v_pk_mul_f32 v[220:221], v[142:143], v[192:193] op_sel_hi:[1,0]
	v_pk_mul_f32 v[222:223], v[144:145], v[192:193] op_sel_hi:[1,0]
	v_pk_fma_f32 v[216:217], v[84:85], v[48:49], v[216:217]
	v_pk_fma_f32 v[218:219], v[88:89], v[50:51], v[218:219]
	v_pk_fma_f32 v[220:221], v[100:101], v[48:49], v[220:221]
	v_pk_fma_f32 v[222:223], v[104:105], v[50:51], v[222:223]
	v_pk_fma_f32 v[84:85], v[172:173], v[188:189], v[216:217] op_sel_hi:[1,0,1]
	v_pk_fma_f32 v[88:89], v[174:175], v[188:189], v[218:219] op_sel_hi:[1,0,1]
	v_pk_fma_f32 v[100:101], v[172:173], v[188:189], v[220:221] op_sel:[0,1,0]
	v_pk_fma_f32 v[104:105], v[174:175], v[188:189], v[222:223] op_sel:[0,1,0]
	ds_read_b128 v[142:145], v171 offset:8704
	ds_read_b128 v[48:51], v171 offset:512
	ds_read_b128 v[172:175], v171 offset:4608
	v_pk_mul_f32 v[216:217], v[146:147], v[190:191] op_sel_hi:[1,0]
	v_pk_mul_f32 v[218:219], v[148:149], v[190:191] op_sel_hi:[1,0]
	v_pk_mul_f32 v[220:221], v[146:147], v[192:193] op_sel_hi:[1,0]
	v_pk_mul_f32 v[222:223], v[148:149], v[192:193] op_sel_hi:[1,0]
	v_pk_fma_f32 v[216:217], v[86:87], v[52:53], v[216:217]
	v_pk_fma_f32 v[218:219], v[92:93], v[54:55], v[218:219]
	v_pk_fma_f32 v[220:221], v[106:107], v[52:53], v[220:221]
	v_pk_fma_f32 v[222:223], v[108:109], v[54:55], v[222:223]
	v_pk_fma_f32 v[86:87], v[176:177], v[188:189], v[216:217] op_sel_hi:[1,0,1]
	v_pk_fma_f32 v[92:93], v[178:179], v[188:189], v[218:219] op_sel_hi:[1,0,1]
	v_pk_fma_f32 v[106:107], v[176:177], v[188:189], v[220:221] op_sel:[0,1,0]
	v_pk_fma_f32 v[108:109], v[178:179], v[188:189], v[222:223] op_sel:[0,1,0]
	ds_read_b128 v[146:149], v171 offset:8720
	ds_read_b128 v[52:55], v171 offset:528
	ds_read_b128 v[176:179], v171 offset:4624
	v_pk_mul_f32 v[216:217], v[150:151], v[190:191] op_sel_hi:[1,0]
	v_pk_mul_f32 v[218:219], v[152:153], v[190:191] op_sel_hi:[1,0]
	v_pk_mul_f32 v[220:221], v[150:151], v[192:193] op_sel_hi:[1,0]
	v_pk_mul_f32 v[222:223], v[152:153], v[192:193] op_sel_hi:[1,0]
; #define LAS __attribute__((address_space(3)))
; __device__ __forceinline__ float red4(float x) { x = DPP_ADD(x, 0xB1); x = DPP_ADD(x, 0x4E); return x; }
; __device__ __forceinline__ void phase_scan(const ScanArgs A, LAS unsigned char* lds) {
;     ...
;                 for (int t = 0; t < 16; ++t) {
;                     const LAS float* q = in + t * 64 + kq * 16;
;                     f32x4 Wv[4], KDv[4], Bv[4], ANv[4], Rv[4];
; #pragma unroll
;                     for (int j = 0; j < 4; ++j) { Wv[j] = *(const LAS f32x4*)(q + 4 * j); KDv[j] = *(const LAS f32x4*)(q + 1024 + 4 * j); Bv[j] = *(const LAS f32x4*)(q + 2048 + 4 * j);
;                                                   ANv[j] = *(const LAS f32x4*)(q + 3072 + 4 * j); Rv[j] = *(const LAS f32x4*)(q + 4096 + 4 * j); }
;                     const f32x2 v2 = *(const LAS f32x2*)(in + 5120 + t * 64 + half * 32 + rb * 2);
;     ...
;                     float sa[2], y[2];
; #pragma unroll
;                     for (int i = 0; i < 2; ++i) { f32x2 a0 = {0.f, 0.f}, a1 = {0.f, 0.f};
; #pragma unroll
;                         for (int p = 0; p < 8; p += 2) { a0 += S2[i][p] * PAIR(ANv, p); a1 += S2[i][p + 1] * PAIR(ANv, p + 1); }
;                         a0 += a1; sa[i] = red4(a0[0] + a0[1]); }
; #pragma unroll
;                     for (int i = 0; i < 2; ++i) { f32x2 y0 = {0.f, 0.f}, y1 = {0.f, 0.f}; const f32x2 sai = {sa[i], sa[i]}, vi = {v2[i], v2[i]};
; #pragma unroll
;                         for (int p = 0; p < 8; p += 2) {
;                             const f32x2 n0 = S2[i][p] * PAIR(Wv, p) + sai * PAIR(Bv, p) + vi * PAIR(KDv, p);
;                             const f32x2 n1 = S2[i][p + 1] * PAIR(Wv, p + 1) + sai * PAIR(Bv, p + 1) + vi * PAIR(KDv, p + 1);
;                             S2[i][p] = n0; S2[i][p + 1] = n1; y0 += n0 * PAIR(Rv, p); y1 += n1 * PAIR(Rv, p + 1); }
;                         y0 += y1; y[i] = red4(y0[0] + y0[1]); }
;     ...
;                     if (kq == 0) *(LAS f32x2*)(yb + t * 64 + half * 32 + rb * 2) = (f32x2){y[0], y[1]};
	v_pk_fma_f32 v[216:217], v[90:91], v[56:57], v[216:217]
	v_pk_fma_f32 v[218:219], v[98:99], v[58:59], v[218:219]
	v_pk_fma_f32 v[220:221], v[110:111], v[56:57], v[220:221]
	v_pk_fma_f32 v[222:223], v[112:113], v[58:59], v[222:223]
	v_pk_fma_f32 v[90:91], v[180:181], v[188:189], v[216:217] op_sel_hi:[1,0,1]
	v_pk_fma_f32 v[98:99], v[182:183], v[188:189], v[218:219] op_sel_hi:[1,0,1]
	v_pk_fma_f32 v[110:111], v[180:181], v[188:189], v[220:221] op_sel:[0,1,0]
	v_pk_fma_f32 v[112:113], v[182:183], v[188:189], v[222:223] op_sel:[0,1,0]
	ds_read_b128 v[150:153], v171 offset:8736
	ds_read_b128 v[56:59], v171 offset:544
	ds_read_b128 v[180:183], v171 offset:4640
	v_pk_mul_f32 v[216:217], v[154:155], v[190:191] op_sel_hi:[1,0]
	v_pk_mul_f32 v[218:219], v[156:157], v[190:191] op_sel_hi:[1,0]
	v_pk_mul_f32 v[220:221], v[154:155], v[192:193] op_sel_hi:[1,0]
	v_pk_mul_f32 v[222:223], v[156:157], v[192:193] op_sel_hi:[1,0]
	v_pk_fma_f32 v[216:217], v[94:95], v[60:61], v[216:217]
	v_pk_fma_f32 v[218:219], v[102:103], v[62:63], v[218:219]
	v_pk_fma_f32 v[220:221], v[114:115], v[60:61], v[220:221]
	v_pk_fma_f32 v[222:223], v[116:117], v[62:63], v[222:223]
	v_pk_fma_f32 v[94:95], v[184:185], v[188:189], v[216:217] op_sel_hi:[1,0,1]
	v_pk_fma_f32 v[102:103], v[186:187], v[188:189], v[218:219] op_sel_hi:[1,0,1]
	v_pk_fma_f32 v[114:115], v[184:185], v[188:189], v[220:221] op_sel:[0,1,0]
	v_pk_fma_f32 v[116:117], v[186:187], v[188:189], v[222:223] op_sel:[0,1,0]
	ds_read_b128 v[154:157], v171 offset:8752
	ds_read_b128 v[60:63], v171 offset:560
	ds_read_b128 v[184:187], v171 offset:4656
	ds_read_b64 v[188:189], v96 offset:512
	s_waitcnt lgkmcnt(15)
	v_pk_fma_f32 v[248:249], v[200:201], v[84:85], 0 op_sel_hi:[1,1,0]
	v_pk_fma_f32 v[250:251], v[202:203], v[88:89], 0 op_sel_hi:[1,1,0]
	v_pk_fma_f32 v[194:195], v[200:201], v[100:101], 0 op_sel_hi:[1,1,0]
	v_pk_fma_f32 v[158:159], v[202:203], v[104:105], 0 op_sel_hi:[1,1,0]
	v_pk_fma_f32 v[248:249], v[204:205], v[86:87], v[248:249]
	v_pk_fma_f32 v[250:251], v[206:207], v[92:93], v[250:251]
	v_pk_fma_f32 v[194:195], v[204:205], v[106:107], v[194:195]
	v_pk_fma_f32 v[158:159], v[206:207], v[108:109], v[158:159]
	v_pk_fma_f32 v[248:249], v[208:209], v[90:91], v[248:249]
	v_pk_fma_f32 v[250:251], v[210:211], v[98:99], v[250:251]
	v_pk_fma_f32 v[194:195], v[208:209], v[110:111], v[194:195]
	v_pk_fma_f32 v[158:159], v[210:211], v[112:113], v[158:159]
	v_pk_fma_f32 v[248:249], v[212:213], v[94:95], v[248:249]
	v_pk_fma_f32 v[250:251], v[214:215], v[102:103], v[250:251]
	v_pk_fma_f32 v[194:195], v[212:213], v[114:115], v[194:195]
	v_pk_fma_f32 v[158:159], v[214:215], v[116:117], v[158:159]
	ds_read_b128 v[200:203], v171 offset:16896
	ds_read_b128 v[204:207], v171 offset:16912
	ds_read_b128 v[208:211], v171 offset:16928
	ds_read_b128 v[212:215], v171 offset:16944
	s_waitcnt lgkmcnt(15)
	v_pk_fma_f32 v[160:161], v[84:85], v[32:33], 0 op_sel_hi:[1,1,0]
	v_pk_fma_f32 v[162:163], v[88:89], v[34:35], 0 op_sel_hi:[1,1,0]
	v_pk_fma_f32 v[164:165], v[100:101], v[32:33], 0 op_sel_hi:[1,1,0]
	v_pk_fma_f32 v[166:167], v[104:105], v[34:35], 0 op_sel_hi:[1,1,0]
	v_pk_fma_f32 v[160:161], v[86:87], v[36:37], v[160:161]
	v_pk_fma_f32 v[162:163], v[92:93], v[38:39], v[162:163]
	v_pk_fma_f32 v[164:165], v[106:107], v[36:37], v[164:165]
	v_pk_fma_f32 v[166:167], v[108:109], v[38:39], v[166:167]
	v_pk_fma_f32 v[160:161], v[90:91], v[40:41], v[160:161]
	v_pk_fma_f32 v[162:163], v[98:99], v[42:43], v[162:163]
	v_pk_fma_f32 v[164:165], v[110:111], v[40:41], v[164:165]
	v_pk_fma_f32 v[166:167], v[112:113], v[42:43], v[166:167]
	v_pk_fma_f32 v[160:161], v[94:95], v[44:45], v[160:161]
	v_pk_fma_f32 v[162:163], v[102:103], v[46:47], v[162:163]
	v_pk_fma_f32 v[164:165], v[114:115], v[44:45], v[164:165]
	v_pk_fma_f32 v[166:167], v[116:117], v[46:47], v[166:167]
	ds_read_b128 v[32:35], v171 offset:13056
	ds_read_b128 v[36:39], v171 offset:13072
	ds_read_b128 v[40:43], v171 offset:13088
	ds_read_b128 v[44:47], v171 offset:13104
	v_pk_add_f32 v[160:161], v[162:163], v[160:161]
	v_pk_add_f32 v[164:165], v[166:167], v[164:165]
	v_pk_add_f32 v[248:249], v[250:251], v[248:249]
	v_pk_add_f32 v[194:195], v[158:159], v[194:195]
	v_add_f32_e32 v168, v160, v161
	v_add_f32_e32 v169, v164, v165
	v_add_f32_e32 v224, v248, v249
	v_add_f32_e32 v225, v194, v195
	v_add_f32_dpp v168, v168, v168 quad_perm:[1,0,3,2] row_mask:0xf bank_mask:0xf bound_ctrl:1
	v_add_f32_dpp v169, v169, v169 quad_perm:[1,0,3,2] row_mask:0xf bank_mask:0xf bound_ctrl:1
	v_add_f32_dpp v224, v224, v224 quad_perm:[1,0,3,2] row_mask:0xf bank_mask:0xf bound_ctrl:1
	v_add_f32_dpp v225, v225, v225 quad_perm:[1,0,3,2] row_mask:0xf bank_mask:0xf bound_ctrl:1
	v_add_f32_dpp v190, v168, v168 quad_perm:[2,3,0,1] row_mask:0xf bank_mask:0xf bound_ctrl:1
	v_add_f32_dpp v192, v169, v169 quad_perm:[2,3,0,1] row_mask:0xf bank_mask:0xf bound_ctrl:1
	v_add_f32_dpp v224, v224, v224 quad_perm:[2,3,0,1] row_mask:0xf bank_mask:0xf bound_ctrl:1
	v_add_f32_dpp v225, v225, v225 quad_perm:[2,3,0,1] row_mask:0xf bank_mask:0xf bound_ctrl:1
	s_and_saveexec_b64 s[34:35], s[8:9]
	ds_write_b64 v75, v[224:225] offset:256
	s_or_b64 exec, exec, s[34:35]
	s_waitcnt lgkmcnt(9)
; #define LAS __attribute__((address_space(3)))
; __device__ __forceinline__ float red4(float x) { x = DPP_ADD(x, 0xB1); x = DPP_ADD(x, 0x4E); return x; }
; __device__ __forceinline__ void phase_scan(const ScanArgs A, LAS unsigned char* lds) {
;     ...
;                 for (int t = 0; t < 16; ++t) {
;                     const LAS float* q = in + t * 64 + kq * 16;
;                     f32x4 Wv[4], KDv[4], Bv[4], ANv[4], Rv[4];
; #pragma unroll
;                     for (int j = 0; j < 4; ++j) { Wv[j] = *(const LAS f32x4*)(q + 4 * j); KDv[j] = *(const LAS f32x4*)(q + 1024 + 4 * j); Bv[j] = *(const LAS f32x4*)(q + 2048 + 4 * j);
;                                                   ANv[j] = *(const LAS f32x4*)(q + 3072 + 4 * j); Rv[j] = *(const LAS f32x4*)(q + 4096 + 4 * j); }
;                     const f32x2 v2 = *(const LAS f32x2*)(in + 5120 + t * 64 + half * 32 + rb * 2);
;     ...
;                     float sa[2], y[2];
; #pragma unroll
;                     for (int i = 0; i < 2; ++i) { f32x2 a0 = {0.f, 0.f}, a1 = {0.f, 0.f};
; #pragma unroll
;                         for (int p = 0; p < 8; p += 2) { a0 += S2[i][p] * PAIR(ANv, p); a1 += S2[i][p + 1] * PAIR(ANv, p + 1); }
;                         a0 += a1; sa[i] = red4(a0[0] + a0[1]); }
; #pragma unroll
;                     for (int i = 0; i < 2; ++i) { f32x2 y0 = {0.f, 0.f}, y1 = {0.f, 0.f}; const f32x2 sai = {sa[i], sa[i]}, vi = {v2[i], v2[i]};
; #pragma unroll
;                         for (int p = 0; p < 8; p += 2) {
;                             const f32x2 n0 = S2[i][p] * PAIR(Wv, p) + sai * PAIR(Bv, p) + vi * PAIR(KDv, p);
;                             const f32x2 n1 = S2[i][p + 1] * PAIR(Wv, p + 1) + sai * PAIR(Bv, p + 1) + vi * PAIR(KDv, p + 1);
;                             S2[i][p] = n0; S2[i][p + 1] = n1; y0 += n0 * PAIR(Rv, p); y1 += n1 * PAIR(Rv, p + 1); }
;                         y0 += y1; y[i] = red4(y0[0] + y0[1]); }
;     ...
;                     if (kq == 0) *(LAS f32x2*)(yb + t * 64 + half * 32 + rb * 2) = (f32x2){y[0], y[1]};
	v_pk_mul_f32 v[216:217], v[142:143], v[190:191] op_sel_hi:[1,0]
	v_pk_mul_f32 v[218:219], v[144:145], v[190:191] op_sel_hi:[1,0]
	v_pk_mul_f32 v[220:221], v[142:143], v[192:193] op_sel_hi:[1,0]
	v_pk_mul_f32 v[222:223], v[144:145], v[192:193] op_sel_hi:[1,0]
	v_pk_fma_f32 v[216:217], v[84:85], v[48:49], v[216:217]
	v_pk_fma_f32 v[218:219], v[88:89], v[50:51], v[218:219]
	v_pk_fma_f32 v[220:221], v[100:101], v[48:49], v[220:221]
	v_pk_fma_f32 v[222:223], v[104:105], v[50:51], v[222:223]
	v_pk_fma_f32 v[84:85], v[172:173], v[188:189], v[216:217] op_sel_hi:[1,0,1]
	v_pk_fma_f32 v[88:89], v[174:175], v[188:189], v[218:219] op_sel_hi:[1,0,1]
	v_pk_fma_f32 v[100:101], v[172:173], v[188:189], v[220:221] op_sel:[0,1,0]
	v_pk_fma_f32 v[104:105], v[174:175], v[188:189], v[222:223] op_sel:[0,1,0]
	ds_read_b128 v[142:145], v171 offset:8960
	ds_read_b128 v[48:51], v171 offset:768
	ds_read_b128 v[172:175], v171 offset:4864
	v_pk_mul_f32 v[216:217], v[146:147], v[190:191] op_sel_hi:[1,0]
	v_pk_mul_f32 v[218:219], v[148:149], v[190:191] op_sel_hi:[1,0]
	v_pk_mul_f32 v[220:221], v[146:147], v[192:193] op_sel_hi:[1,0]
	v_pk_mul_f32 v[222:223], v[148:149], v[192:193] op_sel_hi:[1,0]
	v_pk_fma_f32 v[216:217], v[86:87], v[52:53], v[216:217]
	v_pk_fma_f32 v[218:219], v[92:93], v[54:55], v[218:219]
	v_pk_fma_f32 v[220:221], v[106:107], v[52:53], v[220:221]
	v_pk_fma_f32 v[222:223], v[108:109], v[54:55], v[222:223]
	v_pk_fma_f32 v[86:87], v[176:177], v[188:189], v[216:217] op_sel_hi:[1,0,1]
	v_pk_fma_f32 v[92:93], v[178:179], v[188:189], v[218:219] op_sel_hi:[1,0,1]
	v_pk_fma_f32 v[106:107], v[176:177], v[188:189], v[220:221] op_sel:[0,1,0]
	v_pk_fma_f32 v[108:109], v[178:179], v[188:189], v[222:223] op_sel:[0,1,0]
	ds_read_b128 v[146:149], v171 offset:8976
	ds_read_b128 v[52:55], v171 offset:784
	ds_read_b128 v[176:179], v171 offset:4880
	v_pk_mul_f32 v[216:217], v[150:151], v[190:191] op_sel_hi:[1,0]
	v_pk_mul_f32 v[218:219], v[152:153], v[190:191] op_sel_hi:[1,0]
	v_pk_mul_f32 v[220:221], v[150:151], v[192:193] op_sel_hi:[1,0]
	v_pk_mul_f32 v[222:223], v[152:153], v[192:193] op_sel_hi:[1,0]
	v_pk_fma_f32 v[216:217], v[90:91], v[56:57], v[216:217]
	v_pk_fma_f32 v[218:219], v[98:99], v[58:59], v[218:219]
	v_pk_fma_f32 v[220:221], v[110:111], v[56:57], v[220:221]
	v_pk_fma_f32 v[222:223], v[112:113], v[58:59], v[222:223]
	v_pk_fma_f32 v[90:91], v[180:181], v[188:189], v[216:217] op_sel_hi:[1,0,1]
	v_pk_fma_f32 v[98:99], v[182:183], v[188:189], v[218:219] op_sel_hi:[1,0,1]
	v_pk_fma_f32 v[110:111], v[180:181], v[188:189], v[220:221] op_sel:[0,1,0]
	v_pk_fma_f32 v[112:113], v[182:183], v[188:189], v[222:223] op_sel:[0,1,0]
	ds_read_b128 v[150:153], v171 offset:8992
	ds_read_b128 v[56:59], v171 offset:800
	ds_read_b128 v[180:183], v171 offset:4896
	v_pk_mul_f32 v[216:217], v[154:155], v[190:191] op_sel_hi:[1,0]
	v_pk_mul_f32 v[218:219], v[156:157], v[190:191] op_sel_hi:[1,0]
	v_pk_mul_f32 v[220:221], v[154:155], v[192:193] op_sel_hi:[1,0]
	v_pk_mul_f32 v[222:223], v[156:157], v[192:193] op_sel_hi:[1,0]
	v_pk_fma_f32 v[216:217], v[94:95], v[60:61], v[216:217]
	v_pk_fma_f32 v[218:219], v[102:103], v[62:63], v[218:219]
	v_pk_fma_f32 v[220:221], v[114:115], v[60:61], v[220:221]
	v_pk_fma_f32 v[222:223], v[116:117], v[62:63], v[222:223]
	v_pk_fma_f32 v[94:95], v[184:185], v[188:189], v[216:217] op_sel_hi:[1,0,1]
	v_pk_fma_f32 v[102:103], v[186:187], v[188:189], v[218:219] op_sel_hi:[1,0,1]
	v_pk_fma_f32 v[114:115], v[184:185], v[188:189], v[220:221] op_sel:[0,1,0]
	v_pk_fma_f32 v[116:117], v[186:187], v[188:189], v[222:223] op_sel:[0,1,0]
	ds_read_b128 v[154:157], v171 offset:9008
	ds_read_b128 v[60:63], v171 offset:816
	ds_read_b128 v[184:187], v171 offset:4912
	ds_read_b64 v[188:189], v96 offset:768
	s_waitcnt lgkmcnt(15)
	v_pk_fma_f32 v[248:249], v[200:201], v[84:85], 0 op_sel_hi:[1,1,0]
	v_pk_fma_f32 v[250:251], v[202:203], v[88:89], 0 op_sel_hi:[1,1,0]
	v_pk_fma_f32 v[194:195], v[200:201], v[100:101], 0 op_sel_hi:[1,1,0]
	v_pk_fma_f32 v[158:159], v[202:203], v[104:105], 0 op_sel_hi:[1,1,0]
	v_pk_fma_f32 v[248:249], v[204:205], v[86:87], v[248:249]
	v_pk_fma_f32 v[250:251], v[206:207], v[92:93], v[250:251]
	v_pk_fma_f32 v[194:195], v[204:205], v[106:107], v[194:195]
	v_pk_fma_f32 v[158:159], v[206:207], v[108:109], v[158:159]
	v_pk_fma_f32 v[248:249], v[208:209], v[90:91], v[248:249]
	v_pk_fma_f32 v[250:251], v[210:211], v[98:99], v[250:251]
	v_pk_fma_f32 v[194:195], v[208:209], v[110:111], v[194:195]
	v_pk_fma_f32 v[158:159], v[210:211], v[112:113], v[158:159]
	v_pk_fma_f32 v[248:249], v[212:213], v[94:95], v[248:249]
	v_pk_fma_f32 v[250:251], v[214:215], v[102:103], v[250:251]
	v_pk_fma_f32 v[194:195], v[212:213], v[114:115], v[194:195]
	v_pk_fma_f32 v[158:159], v[214:215], v[116:117], v[158:159]
	ds_read_b128 v[200:203], v171 offset:17152
	ds_read_b128 v[204:207], v171 offset:17168
	ds_read_b128 v[208:211], v171 offset:17184
	ds_read_b128 v[212:215], v171 offset:17200
	s_waitcnt lgkmcnt(15)
; #define LAS __attribute__((address_space(3)))
; __device__ __forceinline__ float red4(float x) { x = DPP_ADD(x, 0xB1); x = DPP_ADD(x, 0x4E); return x; }
; __device__ __forceinline__ void phase_scan(const ScanArgs A, LAS unsigned char* lds) {
;     ...
;                 for (int t = 0; t < 16; ++t) {
;                     const LAS float* q = in + t * 64 + kq * 16;
;                     f32x4 Wv[4], KDv[4], Bv[4], ANv[4], Rv[4];
; #pragma unroll
;                     for (int j = 0; j < 4; ++j) { Wv[j] = *(const LAS f32x4*)(q + 4 * j); KDv[j] = *(const LAS f32x4*)(q + 1024 + 4 * j); Bv[j] = *(const LAS f32x4*)(q + 2048 + 4 * j);
;                                                   ANv[j] = *(const LAS f32x4*)(q + 3072 + 4 * j); Rv[j] = *(const LAS f32x4*)(q + 4096 + 4 * j); }
;                     const f32x2 v2 = *(const LAS f32x2*)(in + 5120 + t * 64 + half * 32 + rb * 2);
;     ...
;                     float sa[2], y[2];
; #pragma unroll
;                     for (int i = 0; i < 2; ++i) { f32x2 a0 = {0.f, 0.f}, a1 = {0.f, 0.f};
; #pragma unroll
;                         for (int p = 0; p < 8; p += 2) { a0 += S2[i][p] * PAIR(ANv, p); a1 += S2[i][p + 1] * PAIR(ANv, p + 1); }
;                         a0 += a1; sa[i] = red4(a0[0] + a0[1]); }
; #pragma unroll
;                     for (int i = 0; i < 2; ++i) { f32x2 y0 = {0.f, 0.f}, y1 = {0.f, 0.f}; const f32x2 sai = {sa[i], sa[i]}, vi = {v2[i], v2[i]};
; #pragma unroll
;                         for (int p = 0; p < 8; p += 2) {
;                             const f32x2 n0 = S2[i][p] * PAIR(Wv, p) + sai * PAIR(Bv, p) + vi * PAIR(KDv, p);
;                             const f32x2 n1 = S2[i][p + 1] * PAIR(Wv, p + 1) + sai * PAIR(Bv, p + 1) + vi * PAIR(KDv, p + 1);
;                             S2[i][p] = n0; S2[i][p + 1] = n1; y0 += n0 * PAIR(Rv, p); y1 += n1 * PAIR(Rv, p + 1); }
;                         y0 += y1; y[i] = red4(y0[0] + y0[1]); }
;     ...
;                     if (kq == 0) *(LAS f32x2*)(yb + t * 64 + half * 32 + rb * 2) = (f32x2){y[0], y[1]};
	v_pk_fma_f32 v[160:161], v[84:85], v[32:33], 0 op_sel_hi:[1,1,0]
	v_pk_fma_f32 v[162:163], v[88:89], v[34:35], 0 op_sel_hi:[1,1,0]
	v_pk_fma_f32 v[164:165], v[100:101], v[32:33], 0 op_sel_hi:[1,1,0]
	v_pk_fma_f32 v[166:167], v[104:105], v[34:35], 0 op_sel_hi:[1,1,0]
	v_pk_fma_f32 v[160:161], v[86:87], v[36:37], v[160:161]
	v_pk_fma_f32 v[162:163], v[92:93], v[38:39], v[162:163]
	v_pk_fma_f32 v[164:165], v[106:107], v[36:37], v[164:165]
	v_pk_fma_f32 v[166:167], v[108:109], v[38:39], v[166:167]
	v_pk_fma_f32 v[160:161], v[90:91], v[40:41], v[160:161]
	v_pk_fma_f32 v[162:163], v[98:99], v[42:43], v[162:163]
	v_pk_fma_f32 v[164:165], v[110:111], v[40:41], v[164:165]
	v_pk_fma_f32 v[166:167], v[112:113], v[42:43], v[166:167]
	v_pk_fma_f32 v[160:161], v[94:95], v[44:45], v[160:161]
	v_pk_fma_f32 v[162:163], v[102:103], v[46:47], v[162:163]
	v_pk_fma_f32 v[164:165], v[114:115], v[44:45], v[164:165]
	v_pk_fma_f32 v[166:167], v[116:117], v[46:47], v[166:167]
	ds_read_b128 v[32:35], v171 offset:13312
	ds_read_b128 v[36:39], v171 offset:13328
	ds_read_b128 v[40:43], v171 offset:13344
	ds_read_b128 v[44:47], v171 offset:13360
	v_pk_add_f32 v[160:161], v[162:163], v[160:161]
	v_pk_add_f32 v[164:165], v[166:167], v[164:165]
	v_pk_add_f32 v[248:249], v[250:251], v[248:249]
	v_pk_add_f32 v[194:195], v[158:159], v[194:195]
	v_add_f32_e32 v168, v160, v161
	v_add_f32_e32 v169, v164, v165
	v_add_f32_e32 v224, v248, v249
	v_add_f32_e32 v225, v194, v195
	v_add_f32_dpp v168, v168, v168 quad_perm:[1,0,3,2] row_mask:0xf bank_mask:0xf bound_ctrl:1
	v_add_f32_dpp v169, v169, v169 quad_perm:[1,0,3,2] row_mask:0xf bank_mask:0xf bound_ctrl:1
	v_add_f32_dpp v224, v224, v224 quad_perm:[1,0,3,2] row_mask:0xf bank_mask:0xf bound_ctrl:1
	v_add_f32_dpp v225, v225, v225 quad_perm:[1,0,3,2] row_mask:0xf bank_mask:0xf bound_ctrl:1
	v_add_f32_dpp v190, v168, v168 quad_perm:[2,3,0,1] row_mask:0xf bank_mask:0xf bound_ctrl:1
	v_add_f32_dpp v192, v169, v169 quad_perm:[2,3,0,1] row_mask:0xf bank_mask:0xf bound_ctrl:1
	v_add_f32_dpp v224, v224, v224 quad_perm:[2,3,0,1] row_mask:0xf bank_mask:0xf bound_ctrl:1
	v_add_f32_dpp v225, v225, v225 quad_perm:[2,3,0,1] row_mask:0xf bank_mask:0xf bound_ctrl:1
	s_and_saveexec_b64 s[34:35], s[8:9]
	ds_write_b64 v75, v[224:225] offset:512
	s_or_b64 exec, exec, s[34:35]
	s_waitcnt lgkmcnt(9)
	v_pk_mul_f32 v[216:217], v[142:143], v[190:191] op_sel_hi:[1,0]
	v_pk_mul_f32 v[218:219], v[144:145], v[190:191] op_sel_hi:[1,0]
	v_pk_mul_f32 v[220:221], v[142:143], v[192:193] op_sel_hi:[1,0]
	v_pk_mul_f32 v[222:223], v[144:145], v[192:193] op_sel_hi:[1,0]
	v_pk_fma_f32 v[216:217], v[84:85], v[48:49], v[216:217]
	v_pk_fma_f32 v[218:219], v[88:89], v[50:51], v[218:219]
	v_pk_fma_f32 v[220:221], v[100:101], v[48:49], v[220:221]
	v_pk_fma_f32 v[222:223], v[104:105], v[50:51], v[222:223]
	v_pk_fma_f32 v[84:85], v[172:173], v[188:189], v[216:217] op_sel_hi:[1,0,1]
	v_pk_fma_f32 v[88:89], v[174:175], v[188:189], v[218:219] op_sel_hi:[1,0,1]
	v_pk_fma_f32 v[100:101], v[172:173], v[188:189], v[220:221] op_sel:[0,1,0]
	v_pk_fma_f32 v[104:105], v[174:175], v[188:189], v[222:223] op_sel:[0,1,0]
	ds_read_b128 v[142:145], v171 offset:9216
	ds_read_b128 v[48:51], v171 offset:1024
	ds_read_b128 v[172:175], v171 offset:5120
	v_pk_mul_f32 v[216:217], v[146:147], v[190:191] op_sel_hi:[1,0]
	v_pk_mul_f32 v[218:219], v[148:149], v[190:191] op_sel_hi:[1,0]
	v_pk_mul_f32 v[220:221], v[146:147], v[192:193] op_sel_hi:[1,0]
	v_pk_mul_f32 v[222:223], v[148:149], v[192:193] op_sel_hi:[1,0]
	v_pk_fma_f32 v[216:217], v[86:87], v[52:53], v[216:217]
	v_pk_fma_f32 v[218:219], v[92:93], v[54:55], v[218:219]
	v_pk_fma_f32 v[220:221], v[106:107], v[52:53], v[220:221]
	v_pk_fma_f32 v[222:223], v[108:109], v[54:55], v[222:223]
	v_pk_fma_f32 v[86:87], v[176:177], v[188:189], v[216:217] op_sel_hi:[1,0,1]
	v_pk_fma_f32 v[92:93], v[178:179], v[188:189], v[218:219] op_sel_hi:[1,0,1]
	v_pk_fma_f32 v[106:107], v[176:177], v[188:189], v[220:221] op_sel:[0,1,0]
	v_pk_fma_f32 v[108:109], v[178:179], v[188:189], v[222:223] op_sel:[0,1,0]
	ds_read_b128 v[146:149], v171 offset:9232
	ds_read_b128 v[52:55], v171 offset:1040
	ds_read_b128 v[176:179], v171 offset:5136
	v_pk_mul_f32 v[216:217], v[150:151], v[190:191] op_sel_hi:[1,0]
	v_pk_mul_f32 v[218:219], v[152:153], v[190:191] op_sel_hi:[1,0]
	v_pk_mul_f32 v[220:221], v[150:151], v[192:193] op_sel_hi:[1,0]
	v_pk_mul_f32 v[222:223], v[152:153], v[192:193] op_sel_hi:[1,0]
	v_pk_fma_f32 v[216:217], v[90:91], v[56:57], v[216:217]
	v_pk_fma_f32 v[218:219], v[98:99], v[58:59], v[218:219]
	v_pk_fma_f32 v[220:221], v[110:111], v[56:57], v[220:221]
	v_pk_fma_f32 v[222:223], v[112:113], v[58:59], v[222:223]
	v_pk_fma_f32 v[90:91], v[180:181], v[188:189], v[216:217] op_sel_hi:[1,0,1]
	v_pk_fma_f32 v[98:99], v[182:183], v[188:189], v[218:219] op_sel_hi:[1,0,1]
	v_pk_fma_f32 v[110:111], v[180:181], v[188:189], v[220:221] op_sel:[0,1,0]
	v_pk_fma_f32 v[112:113], v[182:183], v[188:189], v[222:223] op_sel:[0,1,0]
	ds_read_b128 v[150:153], v171 offset:9248
	ds_read_b128 v[56:59], v171 offset:1056
	ds_read_b128 v[180:183], v171 offset:5152
	v_pk_mul_f32 v[216:217], v[154:155], v[190:191] op_sel_hi:[1,0]
	v_pk_mul_f32 v[218:219], v[156:157], v[190:191] op_sel_hi:[1,0]
	v_pk_mul_f32 v[220:221], v[154:155], v[192:193] op_sel_hi:[1,0]
	v_pk_mul_f32 v[222:223], v[156:157], v[192:193] op_sel_hi:[1,0]
	v_pk_fma_f32 v[216:217], v[94:95], v[60:61], v[216:217]
	v_pk_fma_f32 v[218:219], v[102:103], v[62:63], v[218:219]
	v_pk_fma_f32 v[220:221], v[114:115], v[60:61], v[220:221]
	v_pk_fma_f32 v[222:223], v[116:117], v[62:63], v[222:223]
	v_pk_fma_f32 v[94:95], v[184:185], v[188:189], v[216:217] op_sel_hi:[1,0,1]
	v_pk_fma_f32 v[102:103], v[186:187], v[188:189], v[218:219] op_sel_hi:[1,0,1]
	v_pk_fma_f32 v[114:115], v[184:185], v[188:189], v[220:221] op_sel:[0,1,0]
	v_pk_fma_f32 v[116:117], v[186:187], v[188:189], v[222:223] op_sel:[0,1,0]
	ds_read_b128 v[154:157], v171 offset:9264
	ds_read_b128 v[60:63], v171 offset:1072
	ds_read_b128 v[184:187], v171 offset:5168
	ds_read_b64 v[188:189], v96 offset:1024
	s_waitcnt lgkmcnt(15)
; #define LAS __attribute__((address_space(3)))
; __device__ __forceinline__ float red4(float x) { x = DPP_ADD(x, 0xB1); x = DPP_ADD(x, 0x4E); return x; }
; __device__ __forceinline__ void phase_scan(const ScanArgs A, LAS unsigned char* lds) {
;     ...
;                 for (int t = 0; t < 16; ++t) {
;                     const LAS float* q = in + t * 64 + kq * 16;
;                     f32x4 Wv[4], KDv[4], Bv[4], ANv[4], Rv[4];
; #pragma unroll
;                     for (int j = 0; j < 4; ++j) { Wv[j] = *(const LAS f32x4*)(q + 4 * j); KDv[j] = *(const LAS f32x4*)(q + 1024 + 4 * j); Bv[j] = *(const LAS f32x4*)(q + 2048 + 4 * j);
;                                                   ANv[j] = *(const LAS f32x4*)(q + 3072 + 4 * j); Rv[j] = *(const LAS f32x4*)(q + 4096 + 4 * j); }
;                     const f32x2 v2 = *(const LAS f32x2*)(in + 5120 + t * 64 + half * 32 + rb * 2);
;     ...
;                     float sa[2], y[2];
; #pragma unroll
;                     for (int i = 0; i < 2; ++i) { f32x2 a0 = {0.f, 0.f}, a1 = {0.f, 0.f};
; #pragma unroll
;                         for (int p = 0; p < 8; p += 2) { a0 += S2[i][p] * PAIR(ANv, p); a1 += S2[i][p + 1] * PAIR(ANv, p + 1); }
;                         a0 += a1; sa[i] = red4(a0[0] + a0[1]); }
; #pragma unroll
;                     for (int i = 0; i < 2; ++i) { f32x2 y0 = {0.f, 0.f}, y1 = {0.f, 0.f}; const f32x2 sai = {sa[i], sa[i]}, vi = {v2[i], v2[i]};
; #pragma unroll
;                         for (int p = 0; p < 8; p += 2) {
;                             const f32x2 n0 = S2[i][p] * PAIR(Wv, p) + sai * PAIR(Bv, p) + vi * PAIR(KDv, p);
;                             const f32x2 n1 = S2[i][p + 1] * PAIR(Wv, p + 1) + sai * PAIR(Bv, p + 1) + vi * PAIR(KDv, p + 1);
;                             S2[i][p] = n0; S2[i][p + 1] = n1; y0 += n0 * PAIR(Rv, p); y1 += n1 * PAIR(Rv, p + 1); }
;                         y0 += y1; y[i] = red4(y0[0] + y0[1]); }
;     ...
;                     if (kq == 0) *(LAS f32x2*)(yb + t * 64 + half * 32 + rb * 2) = (f32x2){y[0], y[1]};
	v_pk_fma_f32 v[248:249], v[200:201], v[84:85], 0 op_sel_hi:[1,1,0]
	v_pk_fma_f32 v[250:251], v[202:203], v[88:89], 0 op_sel_hi:[1,1,0]
	v_pk_fma_f32 v[194:195], v[200:201], v[100:101], 0 op_sel_hi:[1,1,0]
	v_pk_fma_f32 v[158:159], v[202:203], v[104:105], 0 op_sel_hi:[1,1,0]
	v_pk_fma_f32 v[248:249], v[204:205], v[86:87], v[248:249]
	v_pk_fma_f32 v[250:251], v[206:207], v[92:93], v[250:251]
	v_pk_fma_f32 v[194:195], v[204:205], v[106:107], v[194:195]
	v_pk_fma_f32 v[158:159], v[206:207], v[108:109], v[158:159]
	v_pk_fma_f32 v[248:249], v[208:209], v[90:91], v[248:249]
	v_pk_fma_f32 v[250:251], v[210:211], v[98:99], v[250:251]
	v_pk_fma_f32 v[194:195], v[208:209], v[110:111], v[194:195]
	v_pk_fma_f32 v[158:159], v[210:211], v[112:113], v[158:159]
	v_pk_fma_f32 v[248:249], v[212:213], v[94:95], v[248:249]
	v_pk_fma_f32 v[250:251], v[214:215], v[102:103], v[250:251]
	v_pk_fma_f32 v[194:195], v[212:213], v[114:115], v[194:195]
	v_pk_fma_f32 v[158:159], v[214:215], v[116:117], v[158:159]
	ds_read_b128 v[200:203], v171 offset:17408
	ds_read_b128 v[204:207], v171 offset:17424
	ds_read_b128 v[208:211], v171 offset:17440
	ds_read_b128 v[212:215], v171 offset:17456
	s_waitcnt lgkmcnt(15)
	v_pk_fma_f32 v[160:161], v[84:85], v[32:33], 0 op_sel_hi:[1,1,0]
	v_pk_fma_f32 v[162:163], v[88:89], v[34:35], 0 op_sel_hi:[1,1,0]
	v_pk_fma_f32 v[164:165], v[100:101], v[32:33], 0 op_sel_hi:[1,1,0]
	v_pk_fma_f32 v[166:167], v[104:105], v[34:35], 0 op_sel_hi:[1,1,0]
	v_pk_fma_f32 v[160:161], v[86:87], v[36:37], v[160:161]
	v_pk_fma_f32 v[162:163], v[92:93], v[38:39], v[162:163]
	v_pk_fma_f32 v[164:165], v[106:107], v[36:37], v[164:165]
	v_pk_fma_f32 v[166:167], v[108:109], v[38:39], v[166:167]
	v_pk_fma_f32 v[160:161], v[90:91], v[40:41], v[160:161]
	v_pk_fma_f32 v[162:163], v[98:99], v[42:43], v[162:163]
	v_pk_fma_f32 v[164:165], v[110:111], v[40:41], v[164:165]
	v_pk_fma_f32 v[166:167], v[112:113], v[42:43], v[166:167]
	v_pk_fma_f32 v[160:161], v[94:95], v[44:45], v[160:161]
	v_pk_fma_f32 v[162:163], v[102:103], v[46:47], v[162:163]
	v_pk_fma_f32 v[164:165], v[114:115], v[44:45], v[164:165]
	v_pk_fma_f32 v[166:167], v[116:117], v[46:47], v[166:167]
	ds_read_b128 v[32:35], v171 offset:13568
	ds_read_b128 v[36:39], v171 offset:13584
	ds_read_b128 v[40:43], v171 offset:13600
	ds_read_b128 v[44:47], v171 offset:13616
	v_pk_add_f32 v[160:161], v[162:163], v[160:161]
	v_pk_add_f32 v[164:165], v[166:167], v[164:165]
	v_pk_add_f32 v[248:249], v[250:251], v[248:249]
	v_pk_add_f32 v[194:195], v[158:159], v[194:195]
	v_add_f32_e32 v168, v160, v161
	v_add_f32_e32 v169, v164, v165
	v_add_f32_e32 v224, v248, v249
	v_add_f32_e32 v225, v194, v195
	v_add_f32_dpp v168, v168, v168 quad_perm:[1,0,3,2] row_mask:0xf bank_mask:0xf bound_ctrl:1
	v_add_f32_dpp v169, v169, v169 quad_perm:[1,0,3,2] row_mask:0xf bank_mask:0xf bound_ctrl:1
	v_add_f32_dpp v224, v224, v224 quad_perm:[1,0,3,2] row_mask:0xf bank_mask:0xf bound_ctrl:1
	v_add_f32_dpp v225, v225, v225 quad_perm:[1,0,3,2] row_mask:0xf bank_mask:0xf bound_ctrl:1
	v_add_f32_dpp v190, v168, v168 quad_perm:[2,3,0,1] row_mask:0xf bank_mask:0xf bound_ctrl:1
	v_add_f32_dpp v192, v169, v169 quad_perm:[2,3,0,1] row_mask:0xf bank_mask:0xf bound_ctrl:1
	v_add_f32_dpp v224, v224, v224 quad_perm:[2,3,0,1] row_mask:0xf bank_mask:0xf bound_ctrl:1
	v_add_f32_dpp v225, v225, v225 quad_perm:[2,3,0,1] row_mask:0xf bank_mask:0xf bound_ctrl:1
	s_and_saveexec_b64 s[34:35], s[8:9]
	ds_write_b64 v75, v[224:225] offset:768
	s_or_b64 exec, exec, s[34:35]
	s_waitcnt lgkmcnt(9)
	v_pk_mul_f32 v[216:217], v[142:143], v[190:191] op_sel_hi:[1,0]
	v_pk_mul_f32 v[218:219], v[144:145], v[190:191] op_sel_hi:[1,0]
	v_pk_mul_f32 v[220:221], v[142:143], v[192:193] op_sel_hi:[1,0]
	v_pk_mul_f32 v[222:223], v[144:145], v[192:193] op_sel_hi:[1,0]
	v_pk_fma_f32 v[216:217], v[84:85], v[48:49], v[216:217]
	v_pk_fma_f32 v[218:219], v[88:89], v[50:51], v[218:219]
	v_pk_fma_f32 v[220:221], v[100:101], v[48:49], v[220:221]
	v_pk_fma_f32 v[222:223], v[104:105], v[50:51], v[222:223]
	v_pk_fma_f32 v[84:85], v[172:173], v[188:189], v[216:217] op_sel_hi:[1,0,1]
	v_pk_fma_f32 v[88:89], v[174:175], v[188:189], v[218:219] op_sel_hi:[1,0,1]
	v_pk_fma_f32 v[100:101], v[172:173], v[188:189], v[220:221] op_sel:[0,1,0]
	v_pk_fma_f32 v[104:105], v[174:175], v[188:189], v[222:223] op_sel:[0,1,0]
	ds_read_b128 v[142:145], v171 offset:9472
	ds_read_b128 v[48:51], v171 offset:1280
	ds_read_b128 v[172:175], v171 offset:5376
	v_pk_mul_f32 v[216:217], v[146:147], v[190:191] op_sel_hi:[1,0]
	v_pk_mul_f32 v[218:219], v[148:149], v[190:191] op_sel_hi:[1,0]
	v_pk_mul_f32 v[220:221], v[146:147], v[192:193] op_sel_hi:[1,0]
	v_pk_mul_f32 v[222:223], v[148:149], v[192:193] op_sel_hi:[1,0]
	v_pk_fma_f32 v[216:217], v[86:87], v[52:53], v[216:217]
	v_pk_fma_f32 v[218:219], v[92:93], v[54:55], v[218:219]
	v_pk_fma_f32 v[220:221], v[106:107], v[52:53], v[220:221]
	v_pk_fma_f32 v[222:223], v[108:109], v[54:55], v[222:223]
	v_pk_fma_f32 v[86:87], v[176:177], v[188:189], v[216:217] op_sel_hi:[1,0,1]
	v_pk_fma_f32 v[92:93], v[178:179], v[188:189], v[218:219] op_sel_hi:[1,0,1]
	v_pk_fma_f32 v[106:107], v[176:177], v[188:189], v[220:221] op_sel:[0,1,0]
	v_pk_fma_f32 v[108:109], v[178:179], v[188:189], v[222:223] op_sel:[0,1,0]
	ds_read_b128 v[146:149], v171 offset:9488
	ds_read_b128 v[52:55], v171 offset:1296
	ds_read_b128 v[176:179], v171 offset:5392
	v_pk_mul_f32 v[216:217], v[150:151], v[190:191] op_sel_hi:[1,0]
	v_pk_mul_f32 v[218:219], v[152:153], v[190:191] op_sel_hi:[1,0]
	v_pk_mul_f32 v[220:221], v[150:151], v[192:193] op_sel_hi:[1,0]
	v_pk_mul_f32 v[222:223], v[152:153], v[192:193] op_sel_hi:[1,0]
; #define LAS __attribute__((address_space(3)))
; __device__ __forceinline__ float red4(float x) { x = DPP_ADD(x, 0xB1); x = DPP_ADD(x, 0x4E); return x; }
; __device__ __forceinline__ void phase_scan(const ScanArgs A, LAS unsigned char* lds) {
;     ...
;                 for (int t = 0; t < 16; ++t) {
;                     const LAS float* q = in + t * 64 + kq * 16;
;                     f32x4 Wv[4], KDv[4], Bv[4], ANv[4], Rv[4];
; #pragma unroll
;                     for (int j = 0; j < 4; ++j) { Wv[j] = *(const LAS f32x4*)(q + 4 * j); KDv[j] = *(const LAS f32x4*)(q + 1024 + 4 * j); Bv[j] = *(const LAS f32x4*)(q + 2048 + 4 * j);
;                                                   ANv[j] = *(const LAS f32x4*)(q + 3072 + 4 * j); Rv[j] = *(const LAS f32x4*)(q + 4096 + 4 * j); }
;                     const f32x2 v2 = *(const LAS f32x2*)(in + 5120 + t * 64 + half * 32 + rb * 2);
;     ...
;                     float sa[2], y[2];
; #pragma unroll
;                     for (int i = 0; i < 2; ++i) { f32x2 a0 = {0.f, 0.f}, a1 = {0.f, 0.f};
; #pragma unroll
;                         for (int p = 0; p < 8; p += 2) { a0 += S2[i][p] * PAIR(ANv, p); a1 += S2[i][p + 1] * PAIR(ANv, p + 1); }
;                         a0 += a1; sa[i] = red4(a0[0] + a0[1]); }
; #pragma unroll
;                     for (int i = 0; i < 2; ++i) { f32x2 y0 = {0.f, 0.f}, y1 = {0.f, 0.f}; const f32x2 sai = {sa[i], sa[i]}, vi = {v2[i], v2[i]};
; #pragma unroll
;                         for (int p = 0; p < 8; p += 2) {
;                             const f32x2 n0 = S2[i][p] * PAIR(Wv, p) + sai * PAIR(Bv, p) + vi * PAIR(KDv, p);
;                             const f32x2 n1 = S2[i][p + 1] * PAIR(Wv, p + 1) + sai * PAIR(Bv, p + 1) + vi * PAIR(KDv, p + 1);
;                             S2[i][p] = n0; S2[i][p + 1] = n1; y0 += n0 * PAIR(Rv, p); y1 += n1 * PAIR(Rv, p + 1); }
;                         y0 += y1; y[i] = red4(y0[0] + y0[1]); }
;     ...
;                     if (kq == 0) *(LAS f32x2*)(yb + t * 64 + half * 32 + rb * 2) = (f32x2){y[0], y[1]};
	v_pk_fma_f32 v[216:217], v[90:91], v[56:57], v[216:217]
	v_pk_fma_f32 v[218:219], v[98:99], v[58:59], v[218:219]
	v_pk_fma_f32 v[220:221], v[110:111], v[56:57], v[220:221]
	v_pk_fma_f32 v[222:223], v[112:113], v[58:59], v[222:223]
	v_pk_fma_f32 v[90:91], v[180:181], v[188:189], v[216:217] op_sel_hi:[1,0,1]
	v_pk_fma_f32 v[98:99], v[182:183], v[188:189], v[218:219] op_sel_hi:[1,0,1]
	v_pk_fma_f32 v[110:111], v[180:181], v[188:189], v[220:221] op_sel:[0,1,0]
	v_pk_fma_f32 v[112:113], v[182:183], v[188:189], v[222:223] op_sel:[0,1,0]
	ds_read_b128 v[150:153], v171 offset:9504
	ds_read_b128 v[56:59], v171 offset:1312
	ds_read_b128 v[180:183], v171 offset:5408
	v_pk_mul_f32 v[216:217], v[154:155], v[190:191] op_sel_hi:[1,0]
	v_pk_mul_f32 v[218:219], v[156:157], v[190:191] op_sel_hi:[1,0]
	v_pk_mul_f32 v[220:221], v[154:155], v[192:193] op_sel_hi:[1,0]
	v_pk_mul_f32 v[222:223], v[156:157], v[192:193] op_sel_hi:[1,0]
	v_pk_fma_f32 v[216:217], v[94:95], v[60:61], v[216:217]
	v_pk_fma_f32 v[218:219], v[102:103], v[62:63], v[218:219]
	v_pk_fma_f32 v[220:221], v[114:115], v[60:61], v[220:221]
	v_pk_fma_f32 v[222:223], v[116:117], v[62:63], v[222:223]
	v_pk_fma_f32 v[94:95], v[184:185], v[188:189], v[216:217] op_sel_hi:[1,0,1]
	v_pk_fma_f32 v[102:103], v[186:187], v[188:189], v[218:219] op_sel_hi:[1,0,1]
	v_pk_fma_f32 v[114:115], v[184:185], v[188:189], v[220:221] op_sel:[0,1,0]
	v_pk_fma_f32 v[116:117], v[186:187], v[188:189], v[222:223] op_sel:[0,1,0]
	ds_read_b128 v[154:157], v171 offset:9520
	ds_read_b128 v[60:63], v171 offset:1328
	ds_read_b128 v[184:187], v171 offset:5424
	ds_read_b64 v[188:189], v96 offset:1280
	s_waitcnt lgkmcnt(15)
	v_pk_fma_f32 v[248:249], v[200:201], v[84:85], 0 op_sel_hi:[1,1,0]
	v_pk_fma_f32 v[250:251], v[202:203], v[88:89], 0 op_sel_hi:[1,1,0]
	v_pk_fma_f32 v[194:195], v[200:201], v[100:101], 0 op_sel_hi:[1,1,0]
	v_pk_fma_f32 v[158:159], v[202:203], v[104:105], 0 op_sel_hi:[1,1,0]
	v_pk_fma_f32 v[248:249], v[204:205], v[86:87], v[248:249]
	v_pk_fma_f32 v[250:251], v[206:207], v[92:93], v[250:251]
	v_pk_fma_f32 v[194:195], v[204:205], v[106:107], v[194:195]
	v_pk_fma_f32 v[158:159], v[206:207], v[108:109], v[158:159]
	v_pk_fma_f32 v[248:249], v[208:209], v[90:91], v[248:249]
	v_pk_fma_f32 v[250:251], v[210:211], v[98:99], v[250:251]
	v_pk_fma_f32 v[194:195], v[208:209], v[110:111], v[194:195]
	v_pk_fma_f32 v[158:159], v[210:211], v[112:113], v[158:159]
	v_pk_fma_f32 v[248:249], v[212:213], v[94:95], v[248:249]
	v_pk_fma_f32 v[250:251], v[214:215], v[102:103], v[250:251]
	v_pk_fma_f32 v[194:195], v[212:213], v[114:115], v[194:195]
	v_pk_fma_f32 v[158:159], v[214:215], v[116:117], v[158:159]
	ds_read_b128 v[200:203], v171 offset:17664
	ds_read_b128 v[204:207], v171 offset:17680
	ds_read_b128 v[208:211], v171 offset:17696
	ds_read_b128 v[212:215], v171 offset:17712
	s_waitcnt lgkmcnt(15)
	v_pk_fma_f32 v[160:161], v[84:85], v[32:33], 0 op_sel_hi:[1,1,0]
	v_pk_fma_f32 v[162:163], v[88:89], v[34:35], 0 op_sel_hi:[1,1,0]
	v_pk_fma_f32 v[164:165], v[100:101], v[32:33], 0 op_sel_hi:[1,1,0]
	v_pk_fma_f32 v[166:167], v[104:105], v[34:35], 0 op_sel_hi:[1,1,0]
	v_pk_fma_f32 v[160:161], v[86:87], v[36:37], v[160:161]
	v_pk_fma_f32 v[162:163], v[92:93], v[38:39], v[162:163]
	v_pk_fma_f32 v[164:165], v[106:107], v[36:37], v[164:165]
	v_pk_fma_f32 v[166:167], v[108:109], v[38:39], v[166:167]
	v_pk_fma_f32 v[160:161], v[90:91], v[40:41], v[160:161]
	v_pk_fma_f32 v[162:163], v[98:99], v[42:43], v[162:163]
	v_pk_fma_f32 v[164:165], v[110:111], v[40:41], v[164:165]
	v_pk_fma_f32 v[166:167], v[112:113], v[42:43], v[166:167]
	v_pk_fma_f32 v[160:161], v[94:95], v[44:45], v[160:161]
	v_pk_fma_f32 v[162:163], v[102:103], v[46:47], v[162:163]
	v_pk_fma_f32 v[164:165], v[114:115], v[44:45], v[164:165]
	v_pk_fma_f32 v[166:167], v[116:117], v[46:47], v[166:167]
	ds_read_b128 v[32:35], v171 offset:13824
	ds_read_b128 v[36:39], v171 offset:13840
	ds_read_b128 v[40:43], v171 offset:13856
	ds_read_b128 v[44:47], v171 offset:13872
	v_pk_add_f32 v[160:161], v[162:163], v[160:161]
	v_pk_add_f32 v[164:165], v[166:167], v[164:165]
	v_pk_add_f32 v[248:249], v[250:251], v[248:249]
	v_pk_add_f32 v[194:195], v[158:159], v[194:195]
	v_add_f32_e32 v168, v160, v161
	v_add_f32_e32 v169, v164, v165
	v_add_f32_e32 v224, v248, v249
	v_add_f32_e32 v225, v194, v195
	v_add_f32_dpp v168, v168, v168 quad_perm:[1,0,3,2] row_mask:0xf bank_mask:0xf bound_ctrl:1
	v_add_f32_dpp v169, v169, v169 quad_perm:[1,0,3,2] row_mask:0xf bank_mask:0xf bound_ctrl:1
	v_add_f32_dpp v224, v224, v224 quad_perm:[1,0,3,2] row_mask:0xf bank_mask:0xf bound_ctrl:1
	v_add_f32_dpp v225, v225, v225 quad_perm:[1,0,3,2] row_mask:0xf bank_mask:0xf bound_ctrl:1
	v_add_f32_dpp v190, v168, v168 quad_perm:[2,3,0,1] row_mask:0xf bank_mask:0xf bound_ctrl:1
	v_add_f32_dpp v192, v169, v169 quad_perm:[2,3,0,1] row_mask:0xf bank_mask:0xf bound_ctrl:1
	v_add_f32_dpp v224, v224, v224 quad_perm:[2,3,0,1] row_mask:0xf bank_mask:0xf bound_ctrl:1
	v_add_f32_dpp v225, v225, v225 quad_perm:[2,3,0,1] row_mask:0xf bank_mask:0xf bound_ctrl:1
	s_and_saveexec_b64 s[34:35], s[8:9]
	ds_write_b64 v75, v[224:225] offset:1024
	s_or_b64 exec, exec, s[34:35]
	s_waitcnt lgkmcnt(9)
; #define LAS __attribute__((address_space(3)))
; __device__ __forceinline__ float red4(float x) { x = DPP_ADD(x, 0xB1); x = DPP_ADD(x, 0x4E); return x; }
; __device__ __forceinline__ void phase_scan(const ScanArgs A, LAS unsigned char* lds) {
;     ...
;                 for (int t = 0; t < 16; ++t) {
;                     const LAS float* q = in + t * 64 + kq * 16;
;                     f32x4 Wv[4], KDv[4], Bv[4], ANv[4], Rv[4];
; #pragma unroll
;                     for (int j = 0; j < 4; ++j) { Wv[j] = *(const LAS f32x4*)(q + 4 * j); KDv[j] = *(const LAS f32x4*)(q + 1024 + 4 * j); Bv[j] = *(const LAS f32x4*)(q + 2048 + 4 * j);
;                                                   ANv[j] = *(const LAS f32x4*)(q + 3072 + 4 * j); Rv[j] = *(const LAS f32x4*)(q + 4096 + 4 * j); }
;                     const f32x2 v2 = *(const LAS f32x2*)(in + 5120 + t * 64 + half * 32 + rb * 2);
;     ...
;                     float sa[2], y[2];
; #pragma unroll
;                     for (int i = 0; i < 2; ++i) { f32x2 a0 = {0.f, 0.f}, a1 = {0.f, 0.f};
; #pragma unroll
;                         for (int p = 0; p < 8; p += 2) { a0 += S2[i][p] * PAIR(ANv, p); a1 += S2[i][p + 1] * PAIR(ANv, p + 1); }
;                         a0 += a1; sa[i] = red4(a0[0] + a0[1]); }
; #pragma unroll
;                     for (int i = 0; i < 2; ++i) { f32x2 y0 = {0.f, 0.f}, y1 = {0.f, 0.f}; const f32x2 sai = {sa[i], sa[i]}, vi = {v2[i], v2[i]};
; #pragma unroll
;                         for (int p = 0; p < 8; p += 2) {
;                             const f32x2 n0 = S2[i][p] * PAIR(Wv, p) + sai * PAIR(Bv, p) + vi * PAIR(KDv, p);
;                             const f32x2 n1 = S2[i][p + 1] * PAIR(Wv, p + 1) + sai * PAIR(Bv, p + 1) + vi * PAIR(KDv, p + 1);
;                             S2[i][p] = n0; S2[i][p + 1] = n1; y0 += n0 * PAIR(Rv, p); y1 += n1 * PAIR(Rv, p + 1); }
;                         y0 += y1; y[i] = red4(y0[0] + y0[1]); }
;     ...
;                     if (kq == 0) *(LAS f32x2*)(yb + t * 64 + half * 32 + rb * 2) = (f32x2){y[0], y[1]};
	v_pk_mul_f32 v[216:217], v[142:143], v[190:191] op_sel_hi:[1,0]
	v_pk_mul_f32 v[218:219], v[144:145], v[190:191] op_sel_hi:[1,0]
	v_pk_mul_f32 v[220:221], v[142:143], v[192:193] op_sel_hi:[1,0]
	v_pk_mul_f32 v[222:223], v[144:145], v[192:193] op_sel_hi:[1,0]
	v_pk_fma_f32 v[216:217], v[84:85], v[48:49], v[216:217]
	v_pk_fma_f32 v[218:219], v[88:89], v[50:51], v[218:219]
	v_pk_fma_f32 v[220:221], v[100:101], v[48:49], v[220:221]
	v_pk_fma_f32 v[222:223], v[104:105], v[50:51], v[222:223]
	v_pk_fma_f32 v[84:85], v[172:173], v[188:189], v[216:217] op_sel_hi:[1,0,1]
	v_pk_fma_f32 v[88:89], v[174:175], v[188:189], v[218:219] op_sel_hi:[1,0,1]
	v_pk_fma_f32 v[100:101], v[172:173], v[188:189], v[220:221] op_sel:[0,1,0]
	v_pk_fma_f32 v[104:105], v[174:175], v[188:189], v[222:223] op_sel:[0,1,0]
	ds_read_b128 v[142:145], v171 offset:9728
	ds_read_b128 v[48:51], v171 offset:1536
	ds_read_b128 v[172:175], v171 offset:5632
	v_pk_mul_f32 v[216:217], v[146:147], v[190:191] op_sel_hi:[1,0]
	v_pk_mul_f32 v[218:219], v[148:149], v[190:191] op_sel_hi:[1,0]
	v_pk_mul_f32 v[220:221], v[146:147], v[192:193] op_sel_hi:[1,0]
	v_pk_mul_f32 v[222:223], v[148:149], v[192:193] op_sel_hi:[1,0]
	v_pk_fma_f32 v[216:217], v[86:87], v[52:53], v[216:217]
	v_pk_fma_f32 v[218:219], v[92:93], v[54:55], v[218:219]
	v_pk_fma_f32 v[220:221], v[106:107], v[52:53], v[220:221]
	v_pk_fma_f32 v[222:223], v[108:109], v[54:55], v[222:223]
	v_pk_fma_f32 v[86:87], v[176:177], v[188:189], v[216:217] op_sel_hi:[1,0,1]
	v_pk_fma_f32 v[92:93], v[178:179], v[188:189], v[218:219] op_sel_hi:[1,0,1]
	v_pk_fma_f32 v[106:107], v[176:177], v[188:189], v[220:221] op_sel:[0,1,0]
	v_pk_fma_f32 v[108:109], v[178:179], v[188:189], v[222:223] op_sel:[0,1,0]
	ds_read_b128 v[146:149], v171 offset:9744
	ds_read_b128 v[52:55], v171 offset:1552
	ds_read_b128 v[176:179], v171 offset:5648
	v_pk_mul_f32 v[216:217], v[150:151], v[190:191] op_sel_hi:[1,0]
	v_pk_mul_f32 v[218:219], v[152:153], v[190:191] op_sel_hi:[1,0]
	v_pk_mul_f32 v[220:221], v[150:151], v[192:193] op_sel_hi:[1,0]
	v_pk_mul_f32 v[222:223], v[152:153], v[192:193] op_sel_hi:[1,0]
	v_pk_fma_f32 v[216:217], v[90:91], v[56:57], v[216:217]
	v_pk_fma_f32 v[218:219], v[98:99], v[58:59], v[218:219]
	v_pk_fma_f32 v[220:221], v[110:111], v[56:57], v[220:221]
	v_pk_fma_f32 v[222:223], v[112:113], v[58:59], v[222:223]
	v_pk_fma_f32 v[90:91], v[180:181], v[188:189], v[216:217] op_sel_hi:[1,0,1]
	v_pk_fma_f32 v[98:99], v[182:183], v[188:189], v[218:219] op_sel_hi:[1,0,1]
	v_pk_fma_f32 v[110:111], v[180:181], v[188:189], v[220:221] op_sel:[0,1,0]
	v_pk_fma_f32 v[112:113], v[182:183], v[188:189], v[222:223] op_sel:[0,1,0]
	ds_read_b128 v[150:153], v171 offset:9760
	ds_read_b128 v[56:59], v171 offset:1568
	ds_read_b128 v[180:183], v171 offset:5664
	v_pk_mul_f32 v[216:217], v[154:155], v[190:191] op_sel_hi:[1,0]
	v_pk_mul_f32 v[218:219], v[156:157], v[190:191] op_sel_hi:[1,0]
	v_pk_mul_f32 v[220:221], v[154:155], v[192:193] op_sel_hi:[1,0]
	v_pk_mul_f32 v[222:223], v[156:157], v[192:193] op_sel_hi:[1,0]
	v_pk_fma_f32 v[216:217], v[94:95], v[60:61], v[216:217]
	v_pk_fma_f32 v[218:219], v[102:103], v[62:63], v[218:219]
	v_pk_fma_f32 v[220:221], v[114:115], v[60:61], v[220:221]
	v_pk_fma_f32 v[222:223], v[116:117], v[62:63], v[222:223]
	v_pk_fma_f32 v[94:95], v[184:185], v[188:189], v[216:217] op_sel_hi:[1,0,1]
	v_pk_fma_f32 v[102:103], v[186:187], v[188:189], v[218:219] op_sel_hi:[1,0,1]
	v_pk_fma_f32 v[114:115], v[184:185], v[188:189], v[220:221] op_sel:[0,1,0]
	v_pk_fma_f32 v[116:117], v[186:187], v[188:189], v[222:223] op_sel:[0,1,0]
	ds_read_b128 v[154:157], v171 offset:9776
	ds_read_b128 v[60:63], v171 offset:1584
	ds_read_b128 v[184:187], v171 offset:5680
	ds_read_b64 v[188:189], v96 offset:1536
	s_waitcnt lgkmcnt(15)
	v_pk_fma_f32 v[248:249], v[200:201], v[84:85], 0 op_sel_hi:[1,1,0]
	v_pk_fma_f32 v[250:251], v[202:203], v[88:89], 0 op_sel_hi:[1,1,0]
	v_pk_fma_f32 v[194:195], v[200:201], v[100:101], 0 op_sel_hi:[1,1,0]
	v_pk_fma_f32 v[158:159], v[202:203], v[104:105], 0 op_sel_hi:[1,1,0]
	v_pk_fma_f32 v[248:249], v[204:205], v[86:87], v[248:249]
	v_pk_fma_f32 v[250:251], v[206:207], v[92:93], v[250:251]
	v_pk_fma_f32 v[194:195], v[204:205], v[106:107], v[194:195]
	v_pk_fma_f32 v[158:159], v[206:207], v[108:109], v[158:159]
	v_pk_fma_f32 v[248:249], v[208:209], v[90:91], v[248:249]
	v_pk_fma_f32 v[250:251], v[210:211], v[98:99], v[250:251]
	v_pk_fma_f32 v[194:195], v[208:209], v[110:111], v[194:195]
	v_pk_fma_f32 v[158:159], v[210:211], v[112:113], v[158:159]
	v_pk_fma_f32 v[248:249], v[212:213], v[94:95], v[248:249]
	v_pk_fma_f32 v[250:251], v[214:215], v[102:103], v[250:251]
	v_pk_fma_f32 v[194:195], v[212:213], v[114:115], v[194:195]
	v_pk_fma_f32 v[158:159], v[214:215], v[116:117], v[158:159]
	ds_read_b128 v[200:203], v171 offset:17920
	ds_read_b128 v[204:207], v171 offset:17936
	ds_read_b128 v[208:211], v171 offset:17952
	ds_read_b128 v[212:215], v171 offset:17968
	s_waitcnt lgkmcnt(15)
; #define LAS __attribute__((address_space(3)))
; __device__ __forceinline__ float red4(float x) { x = DPP_ADD(x, 0xB1); x = DPP_ADD(x, 0x4E); return x; }
; __device__ __forceinline__ void phase_scan(const ScanArgs A, LAS unsigned char* lds) {
;     ...
;                 for (int t = 0; t < 16; ++t) {
;                     const LAS float* q = in + t * 64 + kq * 16;
;                     f32x4 Wv[4], KDv[4], Bv[4], ANv[4], Rv[4];
; #pragma unroll
;                     for (int j = 0; j < 4; ++j) { Wv[j] = *(const LAS f32x4*)(q + 4 * j); KDv[j] = *(const LAS f32x4*)(q + 1024 + 4 * j); Bv[j] = *(const LAS f32x4*)(q + 2048 + 4 * j);
;                                                   ANv[j] = *(const LAS f32x4*)(q + 3072 + 4 * j); Rv[j] = *(const LAS f32x4*)(q + 4096 + 4 * j); }
;                     const f32x2 v2 = *(const LAS f32x2*)(in + 5120 + t * 64 + half * 32 + rb * 2);
;     ...
;                     float sa[2], y[2];
; #pragma unroll
;                     for (int i = 0; i < 2; ++i) { f32x2 a0 = {0.f, 0.f}, a1 = {0.f, 0.f};
; #pragma unroll
;                         for (int p = 0; p < 8; p += 2) { a0 += S2[i][p] * PAIR(ANv, p); a1 += S2[i][p + 1] * PAIR(ANv, p + 1); }
;                         a0 += a1; sa[i] = red4(a0[0] + a0[1]); }
; #pragma unroll
;                     for (int i = 0; i < 2; ++i) { f32x2 y0 = {0.f, 0.f}, y1 = {0.f, 0.f}; const f32x2 sai = {sa[i], sa[i]}, vi = {v2[i], v2[i]};
; #pragma unroll
;                         for (int p = 0; p < 8; p += 2) {
;                             const f32x2 n0 = S2[i][p] * PAIR(Wv, p) + sai * PAIR(Bv, p) + vi * PAIR(KDv, p);
;                             const f32x2 n1 = S2[i][p + 1] * PAIR(Wv, p + 1) + sai * PAIR(Bv, p + 1) + vi * PAIR(KDv, p + 1);
;                             S2[i][p] = n0; S2[i][p + 1] = n1; y0 += n0 * PAIR(Rv, p); y1 += n1 * PAIR(Rv, p + 1); }
;                         y0 += y1; y[i] = red4(y0[0] + y0[1]); }
;     ...
;                     if (kq == 0) *(LAS f32x2*)(yb + t * 64 + half * 32 + rb * 2) = (f32x2){y[0], y[1]};
	v_pk_fma_f32 v[160:161], v[84:85], v[32:33], 0 op_sel_hi:[1,1,0]
	v_pk_fma_f32 v[162:163], v[88:89], v[34:35], 0 op_sel_hi:[1,1,0]
	v_pk_fma_f32 v[164:165], v[100:101], v[32:33], 0 op_sel_hi:[1,1,0]
	v_pk_fma_f32 v[166:167], v[104:105], v[34:35], 0 op_sel_hi:[1,1,0]
	v_pk_fma_f32 v[160:161], v[86:87], v[36:37], v[160:161]
	v_pk_fma_f32 v[162:163], v[92:93], v[38:39], v[162:163]
	v_pk_fma_f32 v[164:165], v[106:107], v[36:37], v[164:165]
	v_pk_fma_f32 v[166:167], v[108:109], v[38:39], v[166:167]
	v_pk_fma_f32 v[160:161], v[90:91], v[40:41], v[160:161]
	v_pk_fma_f32 v[162:163], v[98:99], v[42:43], v[162:163]
	v_pk_fma_f32 v[164:165], v[110:111], v[40:41], v[164:165]
	v_pk_fma_f32 v[166:167], v[112:113], v[42:43], v[166:167]
	v_pk_fma_f32 v[160:161], v[94:95], v[44:45], v[160:161]
	v_pk_fma_f32 v[162:163], v[102:103], v[46:47], v[162:163]
	v_pk_fma_f32 v[164:165], v[114:115], v[44:45], v[164:165]
	v_pk_fma_f32 v[166:167], v[116:117], v[46:47], v[166:167]
	ds_read_b128 v[32:35], v171 offset:14080
	ds_read_b128 v[36:39], v171 offset:14096
	ds_read_b128 v[40:43], v171 offset:14112
	ds_read_b128 v[44:47], v171 offset:14128
	v_pk_add_f32 v[160:161], v[162:163], v[160:161]
	v_pk_add_f32 v[164:165], v[166:167], v[164:165]
	v_pk_add_f32 v[248:249], v[250:251], v[248:249]
	v_pk_add_f32 v[194:195], v[158:159], v[194:195]
	v_add_f32_e32 v168, v160, v161
	v_add_f32_e32 v169, v164, v165
	v_add_f32_e32 v224, v248, v249
	v_add_f32_e32 v225, v194, v195
	v_add_f32_dpp v168, v168, v168 quad_perm:[1,0,3,2] row_mask:0xf bank_mask:0xf bound_ctrl:1
	v_add_f32_dpp v169, v169, v169 quad_perm:[1,0,3,2] row_mask:0xf bank_mask:0xf bound_ctrl:1
	v_add_f32_dpp v224, v224, v224 quad_perm:[1,0,3,2] row_mask:0xf bank_mask:0xf bound_ctrl:1
	v_add_f32_dpp v225, v225, v225 quad_perm:[1,0,3,2] row_mask:0xf bank_mask:0xf bound_ctrl:1
	v_add_f32_dpp v190, v168, v168 quad_perm:[2,3,0,1] row_mask:0xf bank_mask:0xf bound_ctrl:1
	v_add_f32_dpp v192, v169, v169 quad_perm:[2,3,0,1] row_mask:0xf bank_mask:0xf bound_ctrl:1
	v_add_f32_dpp v224, v224, v224 quad_perm:[2,3,0,1] row_mask:0xf bank_mask:0xf bound_ctrl:1
	v_add_f32_dpp v225, v225, v225 quad_perm:[2,3,0,1] row_mask:0xf bank_mask:0xf bound_ctrl:1
	s_and_saveexec_b64 s[34:35], s[8:9]
	ds_write_b64 v75, v[224:225] offset:1280
	s_or_b64 exec, exec, s[34:35]
	s_waitcnt lgkmcnt(9)
	v_pk_mul_f32 v[216:217], v[142:143], v[190:191] op_sel_hi:[1,0]
	v_pk_mul_f32 v[218:219], v[144:145], v[190:191] op_sel_hi:[1,0]
	v_pk_mul_f32 v[220:221], v[142:143], v[192:193] op_sel_hi:[1,0]
	v_pk_mul_f32 v[222:223], v[144:145], v[192:193] op_sel_hi:[1,0]
	v_pk_fma_f32 v[216:217], v[84:85], v[48:49], v[216:217]
	v_pk_fma_f32 v[218:219], v[88:89], v[50:51], v[218:219]
	v_pk_fma_f32 v[220:221], v[100:101], v[48:49], v[220:221]
	v_pk_fma_f32 v[222:223], v[104:105], v[50:51], v[222:223]
	v_pk_fma_f32 v[84:85], v[172:173], v[188:189], v[216:217] op_sel_hi:[1,0,1]
	v_pk_fma_f32 v[88:89], v[174:175], v[188:189], v[218:219] op_sel_hi:[1,0,1]
	v_pk_fma_f32 v[100:101], v[172:173], v[188:189], v[220:221] op_sel:[0,1,0]
	v_pk_fma_f32 v[104:105], v[174:175], v[188:189], v[222:223] op_sel:[0,1,0]
	ds_read_b128 v[142:145], v171 offset:9984
	ds_read_b128 v[48:51], v171 offset:1792
	ds_read_b128 v[172:175], v171 offset:5888
	v_pk_mul_f32 v[216:217], v[146:147], v[190:191] op_sel_hi:[1,0]
	v_pk_mul_f32 v[218:219], v[148:149], v[190:191] op_sel_hi:[1,0]
	v_pk_mul_f32 v[220:221], v[146:147], v[192:193] op_sel_hi:[1,0]
	v_pk_mul_f32 v[222:223], v[148:149], v[192:193] op_sel_hi:[1,0]
	v_pk_fma_f32 v[216:217], v[86:87], v[52:53], v[216:217]
	v_pk_fma_f32 v[218:219], v[92:93], v[54:55], v[218:219]
	v_pk_fma_f32 v[220:221], v[106:107], v[52:53], v[220:221]
	v_pk_fma_f32 v[222:223], v[108:109], v[54:55], v[222:223]
	v_pk_fma_f32 v[86:87], v[176:177], v[188:189], v[216:217] op_sel_hi:[1,0,1]
	v_pk_fma_f32 v[92:93], v[178:179], v[188:189], v[218:219] op_sel_hi:[1,0,1]
	v_pk_fma_f32 v[106:107], v[176:177], v[188:189], v[220:221] op_sel:[0,1,0]
	v_pk_fma_f32 v[108:109], v[178:179], v[188:189], v[222:223] op_sel:[0,1,0]
	ds_read_b128 v[146:149], v171 offset:10000
	ds_read_b128 v[52:55], v171 offset:1808
	ds_read_b128 v[176:179], v171 offset:5904
	v_pk_mul_f32 v[216:217], v[150:151], v[190:191] op_sel_hi:[1,0]
	v_pk_mul_f32 v[218:219], v[152:153], v[190:191] op_sel_hi:[1,0]
	v_pk_mul_f32 v[220:221], v[150:151], v[192:193] op_sel_hi:[1,0]
	v_pk_mul_f32 v[222:223], v[152:153], v[192:193] op_sel_hi:[1,0]
	v_pk_fma_f32 v[216:217], v[90:91], v[56:57], v[216:217]
	v_pk_fma_f32 v[218:219], v[98:99], v[58:59], v[218:219]
	v_pk_fma_f32 v[220:221], v[110:111], v[56:57], v[220:221]
	v_pk_fma_f32 v[222:223], v[112:113], v[58:59], v[222:223]
	v_pk_fma_f32 v[90:91], v[180:181], v[188:189], v[216:217] op_sel_hi:[1,0,1]
	v_pk_fma_f32 v[98:99], v[182:183], v[188:189], v[218:219] op_sel_hi:[1,0,1]
	v_pk_fma_f32 v[110:111], v[180:181], v[188:189], v[220:221] op_sel:[0,1,0]
	v_pk_fma_f32 v[112:113], v[182:183], v[188:189], v[222:223] op_sel:[0,1,0]
	ds_read_b128 v[150:153], v171 offset:10016
	ds_read_b128 v[56:59], v171 offset:1824
	ds_read_b128 v[180:183], v171 offset:5920
	v_pk_mul_f32 v[216:217], v[154:155], v[190:191] op_sel_hi:[1,0]
	v_pk_mul_f32 v[218:219], v[156:157], v[190:191] op_sel_hi:[1,0]
	v_pk_mul_f32 v[220:221], v[154:155], v[192:193] op_sel_hi:[1,0]
	v_pk_mul_f32 v[222:223], v[156:157], v[192:193] op_sel_hi:[1,0]
	v_pk_fma_f32 v[216:217], v[94:95], v[60:61], v[216:217]
	v_pk_fma_f32 v[218:219], v[102:103], v[62:63], v[218:219]
	v_pk_fma_f32 v[220:221], v[114:115], v[60:61], v[220:221]
	v_pk_fma_f32 v[222:223], v[116:117], v[62:63], v[222:223]
	v_pk_fma_f32 v[94:95], v[184:185], v[188:189], v[216:217] op_sel_hi:[1,0,1]
	v_pk_fma_f32 v[102:103], v[186:187], v[188:189], v[218:219] op_sel_hi:[1,0,1]
	v_pk_fma_f32 v[114:115], v[184:185], v[188:189], v[220:221] op_sel:[0,1,0]
	v_pk_fma_f32 v[116:117], v[186:187], v[188:189], v[222:223] op_sel:[0,1,0]
	ds_read_b128 v[154:157], v171 offset:10032
	ds_read_b128 v[60:63], v171 offset:1840
	ds_read_b128 v[184:187], v171 offset:5936
	ds_read_b64 v[188:189], v96 offset:1792
	s_waitcnt lgkmcnt(15)
; #define LAS __attribute__((address_space(3)))
; __device__ __forceinline__ float red4(float x) { x = DPP_ADD(x, 0xB1); x = DPP_ADD(x, 0x4E); return x; }
; __device__ __forceinline__ void phase_scan(const ScanArgs A, LAS unsigned char* lds) {
;     ...
;                 for (int t = 0; t < 16; ++t) {
;                     const LAS float* q = in + t * 64 + kq * 16;
;                     f32x4 Wv[4], KDv[4], Bv[4], ANv[4], Rv[4];
; #pragma unroll
;                     for (int j = 0; j < 4; ++j) { Wv[j] = *(const LAS f32x4*)(q + 4 * j); KDv[j] = *(const LAS f32x4*)(q + 1024 + 4 * j); Bv[j] = *(const LAS f32x4*)(q + 2048 + 4 * j);
;                                                   ANv[j] = *(const LAS f32x4*)(q + 3072 + 4 * j); Rv[j] = *(const LAS f32x4*)(q + 4096 + 4 * j); }
;                     const f32x2 v2 = *(const LAS f32x2*)(in + 5120 + t * 64 + half * 32 + rb * 2);
;     ...
;                     float sa[2], y[2];
; #pragma unroll
;                     for (int i = 0; i < 2; ++i) { f32x2 a0 = {0.f, 0.f}, a1 = {0.f, 0.f};
; #pragma unroll
;                         for (int p = 0; p < 8; p += 2) { a0 += S2[i][p] * PAIR(ANv, p); a1 += S2[i][p + 1] * PAIR(ANv, p + 1); }
;                         a0 += a1; sa[i] = red4(a0[0] + a0[1]); }
; #pragma unroll
;                     for (int i = 0; i < 2; ++i) { f32x2 y0 = {0.f, 0.f}, y1 = {0.f, 0.f}; const f32x2 sai = {sa[i], sa[i]}, vi = {v2[i], v2[i]};
; #pragma unroll
;                         for (int p = 0; p < 8; p += 2) {
;                             const f32x2 n0 = S2[i][p] * PAIR(Wv, p) + sai * PAIR(Bv, p) + vi * PAIR(KDv, p);
;                             const f32x2 n1 = S2[i][p + 1] * PAIR(Wv, p + 1) + sai * PAIR(Bv, p + 1) + vi * PAIR(KDv, p + 1);
;                             S2[i][p] = n0; S2[i][p + 1] = n1; y0 += n0 * PAIR(Rv, p); y1 += n1 * PAIR(Rv, p + 1); }
;                         y0 += y1; y[i] = red4(y0[0] + y0[1]); }
;     ...
;                     if (kq == 0) *(LAS f32x2*)(yb + t * 64 + half * 32 + rb * 2) = (f32x2){y[0], y[1]};
	v_pk_fma_f32 v[248:249], v[200:201], v[84:85], 0 op_sel_hi:[1,1,0]
	v_pk_fma_f32 v[250:251], v[202:203], v[88:89], 0 op_sel_hi:[1,1,0]
	v_pk_fma_f32 v[194:195], v[200:201], v[100:101], 0 op_sel_hi:[1,1,0]
	v_pk_fma_f32 v[158:159], v[202:203], v[104:105], 0 op_sel_hi:[1,1,0]
	v_pk_fma_f32 v[248:249], v[204:205], v[86:87], v[248:249]
	v_pk_fma_f32 v[250:251], v[206:207], v[92:93], v[250:251]
	v_pk_fma_f32 v[194:195], v[204:205], v[106:107], v[194:195]
	v_pk_fma_f32 v[158:159], v[206:207], v[108:109], v[158:159]
	v_pk_fma_f32 v[248:249], v[208:209], v[90:91], v[248:249]
	v_pk_fma_f32 v[250:251], v[210:211], v[98:99], v[250:251]
	v_pk_fma_f32 v[194:195], v[208:209], v[110:111], v[194:195]
	v_pk_fma_f32 v[158:159], v[210:211], v[112:113], v[158:159]
	v_pk_fma_f32 v[248:249], v[212:213], v[94:95], v[248:249]
	v_pk_fma_f32 v[250:251], v[214:215], v[102:103], v[250:251]
	v_pk_fma_f32 v[194:195], v[212:213], v[114:115], v[194:195]
	v_pk_fma_f32 v[158:159], v[214:215], v[116:117], v[158:159]
	ds_read_b128 v[200:203], v171 offset:18176
	ds_read_b128 v[204:207], v171 offset:18192
	ds_read_b128 v[208:211], v171 offset:18208
	ds_read_b128 v[212:215], v171 offset:18224
	s_waitcnt lgkmcnt(15)
	v_pk_fma_f32 v[160:161], v[84:85], v[32:33], 0 op_sel_hi:[1,1,0]
	v_pk_fma_f32 v[162:163], v[88:89], v[34:35], 0 op_sel_hi:[1,1,0]
	v_pk_fma_f32 v[164:165], v[100:101], v[32:33], 0 op_sel_hi:[1,1,0]
	v_pk_fma_f32 v[166:167], v[104:105], v[34:35], 0 op_sel_hi:[1,1,0]
	v_pk_fma_f32 v[160:161], v[86:87], v[36:37], v[160:161]
	v_pk_fma_f32 v[162:163], v[92:93], v[38:39], v[162:163]
	v_pk_fma_f32 v[164:165], v[106:107], v[36:37], v[164:165]
	v_pk_fma_f32 v[166:167], v[108:109], v[38:39], v[166:167]
	v_pk_fma_f32 v[160:161], v[90:91], v[40:41], v[160:161]
	v_pk_fma_f32 v[162:163], v[98:99], v[42:43], v[162:163]
	v_pk_fma_f32 v[164:165], v[110:111], v[40:41], v[164:165]
	v_pk_fma_f32 v[166:167], v[112:113], v[42:43], v[166:167]
	v_pk_fma_f32 v[160:161], v[94:95], v[44:45], v[160:161]
	v_pk_fma_f32 v[162:163], v[102:103], v[46:47], v[162:163]
	v_pk_fma_f32 v[164:165], v[114:115], v[44:45], v[164:165]
	v_pk_fma_f32 v[166:167], v[116:117], v[46:47], v[166:167]
	ds_read_b128 v[32:35], v171 offset:14336
	ds_read_b128 v[36:39], v171 offset:14352
	ds_read_b128 v[40:43], v171 offset:14368
	ds_read_b128 v[44:47], v171 offset:14384
	v_pk_add_f32 v[160:161], v[162:163], v[160:161]
	v_pk_add_f32 v[164:165], v[166:167], v[164:165]
	v_pk_add_f32 v[248:249], v[250:251], v[248:249]
	v_pk_add_f32 v[194:195], v[158:159], v[194:195]
	v_add_f32_e32 v168, v160, v161
	v_add_f32_e32 v169, v164, v165
	v_add_f32_e32 v224, v248, v249
	v_add_f32_e32 v225, v194, v195
	v_add_f32_dpp v168, v168, v168 quad_perm:[1,0,3,2] row_mask:0xf bank_mask:0xf bound_ctrl:1
	v_add_f32_dpp v169, v169, v169 quad_perm:[1,0,3,2] row_mask:0xf bank_mask:0xf bound_ctrl:1
	v_add_f32_dpp v224, v224, v224 quad_perm:[1,0,3,2] row_mask:0xf bank_mask:0xf bound_ctrl:1
	v_add_f32_dpp v225, v225, v225 quad_perm:[1,0,3,2] row_mask:0xf bank_mask:0xf bound_ctrl:1
	v_add_f32_dpp v190, v168, v168 quad_perm:[2,3,0,1] row_mask:0xf bank_mask:0xf bound_ctrl:1
	v_add_f32_dpp v192, v169, v169 quad_perm:[2,3,0,1] row_mask:0xf bank_mask:0xf bound_ctrl:1
	v_add_f32_dpp v224, v224, v224 quad_perm:[2,3,0,1] row_mask:0xf bank_mask:0xf bound_ctrl:1
	v_add_f32_dpp v225, v225, v225 quad_perm:[2,3,0,1] row_mask:0xf bank_mask:0xf bound_ctrl:1
	s_and_saveexec_b64 s[34:35], s[8:9]
	ds_write_b64 v75, v[224:225] offset:1536
	s_or_b64 exec, exec, s[34:35]
	s_waitcnt lgkmcnt(9)
	v_pk_mul_f32 v[216:217], v[142:143], v[190:191] op_sel_hi:[1,0]
	v_pk_mul_f32 v[218:219], v[144:145], v[190:191] op_sel_hi:[1,0]
	v_pk_mul_f32 v[220:221], v[142:143], v[192:193] op_sel_hi:[1,0]
	v_pk_mul_f32 v[222:223], v[144:145], v[192:193] op_sel_hi:[1,0]
	v_pk_fma_f32 v[216:217], v[84:85], v[48:49], v[216:217]
	v_pk_fma_f32 v[218:219], v[88:89], v[50:51], v[218:219]
	v_pk_fma_f32 v[220:221], v[100:101], v[48:49], v[220:221]
	v_pk_fma_f32 v[222:223], v[104:105], v[50:51], v[222:223]
	v_pk_fma_f32 v[84:85], v[172:173], v[188:189], v[216:217] op_sel_hi:[1,0,1]
	v_pk_fma_f32 v[88:89], v[174:175], v[188:189], v[218:219] op_sel_hi:[1,0,1]
	v_pk_fma_f32 v[100:101], v[172:173], v[188:189], v[220:221] op_sel:[0,1,0]
	v_pk_fma_f32 v[104:105], v[174:175], v[188:189], v[222:223] op_sel:[0,1,0]
	ds_read_b128 v[142:145], v171 offset:10240
	ds_read_b128 v[48:51], v171 offset:2048
	ds_read_b128 v[172:175], v171 offset:6144
	v_pk_mul_f32 v[216:217], v[146:147], v[190:191] op_sel_hi:[1,0]
	v_pk_mul_f32 v[218:219], v[148:149], v[190:191] op_sel_hi:[1,0]
	v_pk_mul_f32 v[220:221], v[146:147], v[192:193] op_sel_hi:[1,0]
	v_pk_mul_f32 v[222:223], v[148:149], v[192:193] op_sel_hi:[1,0]
	v_pk_fma_f32 v[216:217], v[86:87], v[52:53], v[216:217]
	v_pk_fma_f32 v[218:219], v[92:93], v[54:55], v[218:219]
	v_pk_fma_f32 v[220:221], v[106:107], v[52:53], v[220:221]
	v_pk_fma_f32 v[222:223], v[108:109], v[54:55], v[222:223]
	v_pk_fma_f32 v[86:87], v[176:177], v[188:189], v[216:217] op_sel_hi:[1,0,1]
	v_pk_fma_f32 v[92:93], v[178:179], v[188:189], v[218:219] op_sel_hi:[1,0,1]
	v_pk_fma_f32 v[106:107], v[176:177], v[188:189], v[220:221] op_sel:[0,1,0]
	v_pk_fma_f32 v[108:109], v[178:179], v[188:189], v[222:223] op_sel:[0,1,0]
	ds_read_b128 v[146:149], v171 offset:10256
	ds_read_b128 v[52:55], v171 offset:2064
	ds_read_b128 v[176:179], v171 offset:6160
	v_pk_mul_f32 v[216:217], v[150:151], v[190:191] op_sel_hi:[1,0]
	v_pk_mul_f32 v[218:219], v[152:153], v[190:191] op_sel_hi:[1,0]
	v_pk_mul_f32 v[220:221], v[150:151], v[192:193] op_sel_hi:[1,0]
	v_pk_mul_f32 v[222:223], v[152:153], v[192:193] op_sel_hi:[1,0]
; #define LAS __attribute__((address_space(3)))
; __device__ __forceinline__ float red4(float x) { x = DPP_ADD(x, 0xB1); x = DPP_ADD(x, 0x4E); return x; }
; __device__ __forceinline__ void phase_scan(const ScanArgs A, LAS unsigned char* lds) {
;     ...
;                 for (int t = 0; t < 16; ++t) {
;                     const LAS float* q = in + t * 64 + kq * 16;
;                     f32x4 Wv[4], KDv[4], Bv[4], ANv[4], Rv[4];
; #pragma unroll
;                     for (int j = 0; j < 4; ++j) { Wv[j] = *(const LAS f32x4*)(q + 4 * j); KDv[j] = *(const LAS f32x4*)(q + 1024 + 4 * j); Bv[j] = *(const LAS f32x4*)(q + 2048 + 4 * j);
;                                                   ANv[j] = *(const LAS f32x4*)(q + 3072 + 4 * j); Rv[j] = *(const LAS f32x4*)(q + 4096 + 4 * j); }
;                     const f32x2 v2 = *(const LAS f32x2*)(in + 5120 + t * 64 + half * 32 + rb * 2);
;     ...
;                     float sa[2], y[2];
; #pragma unroll
;                     for (int i = 0; i < 2; ++i) { f32x2 a0 = {0.f, 0.f}, a1 = {0.f, 0.f};
; #pragma unroll
;                         for (int p = 0; p < 8; p += 2) { a0 += S2[i][p] * PAIR(ANv, p); a1 += S2[i][p + 1] * PAIR(ANv, p + 1); }
;                         a0 += a1; sa[i] = red4(a0[0] + a0[1]); }
; #pragma unroll
;                     for (int i = 0; i < 2; ++i) { f32x2 y0 = {0.f, 0.f}, y1 = {0.f, 0.f}; const f32x2 sai = {sa[i], sa[i]}, vi = {v2[i], v2[i]};
; #pragma unroll
;                         for (int p = 0; p < 8; p += 2) {
;                             const f32x2 n0 = S2[i][p] * PAIR(Wv, p) + sai * PAIR(Bv, p) + vi * PAIR(KDv, p);
;                             const f32x2 n1 = S2[i][p + 1] * PAIR(Wv, p + 1) + sai * PAIR(Bv, p + 1) + vi * PAIR(KDv, p + 1);
;                             S2[i][p] = n0; S2[i][p + 1] = n1; y0 += n0 * PAIR(Rv, p); y1 += n1 * PAIR(Rv, p + 1); }
;                         y0 += y1; y[i] = red4(y0[0] + y0[1]); }
;     ...
;                     if (kq == 0) *(LAS f32x2*)(yb + t * 64 + half * 32 + rb * 2) = (f32x2){y[0], y[1]};
	v_pk_fma_f32 v[216:217], v[90:91], v[56:57], v[216:217]
	v_pk_fma_f32 v[218:219], v[98:99], v[58:59], v[218:219]
	v_pk_fma_f32 v[220:221], v[110:111], v[56:57], v[220:221]
	v_pk_fma_f32 v[222:223], v[112:113], v[58:59], v[222:223]
	v_pk_fma_f32 v[90:91], v[180:181], v[188:189], v[216:217] op_sel_hi:[1,0,1]
	v_pk_fma_f32 v[98:99], v[182:183], v[188:189], v[218:219] op_sel_hi:[1,0,1]
	v_pk_fma_f32 v[110:111], v[180:181], v[188:189], v[220:221] op_sel:[0,1,0]
	v_pk_fma_f32 v[112:113], v[182:183], v[188:189], v[222:223] op_sel:[0,1,0]
	ds_read_b128 v[150:153], v171 offset:10272
	ds_read_b128 v[56:59], v171 offset:2080
	ds_read_b128 v[180:183], v171 offset:6176
	v_pk_mul_f32 v[216:217], v[154:155], v[190:191] op_sel_hi:[1,0]
	v_pk_mul_f32 v[218:219], v[156:157], v[190:191] op_sel_hi:[1,0]
	v_pk_mul_f32 v[220:221], v[154:155], v[192:193] op_sel_hi:[1,0]
	v_pk_mul_f32 v[222:223], v[156:157], v[192:193] op_sel_hi:[1,0]
	v_pk_fma_f32 v[216:217], v[94:95], v[60:61], v[216:217]
	v_pk_fma_f32 v[218:219], v[102:103], v[62:63], v[218:219]
	v_pk_fma_f32 v[220:221], v[114:115], v[60:61], v[220:221]
	v_pk_fma_f32 v[222:223], v[116:117], v[62:63], v[222:223]
	v_pk_fma_f32 v[94:95], v[184:185], v[188:189], v[216:217] op_sel_hi:[1,0,1]
	v_pk_fma_f32 v[102:103], v[186:187], v[188:189], v[218:219] op_sel_hi:[1,0,1]
	v_pk_fma_f32 v[114:115], v[184:185], v[188:189], v[220:221] op_sel:[0,1,0]
	v_pk_fma_f32 v[116:117], v[186:187], v[188:189], v[222:223] op_sel:[0,1,0]
	ds_read_b128 v[154:157], v171 offset:10288
	ds_read_b128 v[60:63], v171 offset:2096
	ds_read_b128 v[184:187], v171 offset:6192
	ds_read_b64 v[188:189], v96 offset:2048
	s_waitcnt lgkmcnt(15)
	v_pk_fma_f32 v[248:249], v[200:201], v[84:85], 0 op_sel_hi:[1,1,0]
	v_pk_fma_f32 v[250:251], v[202:203], v[88:89], 0 op_sel_hi:[1,1,0]
	v_pk_fma_f32 v[194:195], v[200:201], v[100:101], 0 op_sel_hi:[1,1,0]
	v_pk_fma_f32 v[158:159], v[202:203], v[104:105], 0 op_sel_hi:[1,1,0]
	v_pk_fma_f32 v[248:249], v[204:205], v[86:87], v[248:249]
	v_pk_fma_f32 v[250:251], v[206:207], v[92:93], v[250:251]
	v_pk_fma_f32 v[194:195], v[204:205], v[106:107], v[194:195]
	v_pk_fma_f32 v[158:159], v[206:207], v[108:109], v[158:159]
	v_pk_fma_f32 v[248:249], v[208:209], v[90:91], v[248:249]
	v_pk_fma_f32 v[250:251], v[210:211], v[98:99], v[250:251]
	v_pk_fma_f32 v[194:195], v[208:209], v[110:111], v[194:195]
	v_pk_fma_f32 v[158:159], v[210:211], v[112:113], v[158:159]
	v_pk_fma_f32 v[248:249], v[212:213], v[94:95], v[248:249]
	v_pk_fma_f32 v[250:251], v[214:215], v[102:103], v[250:251]
	v_pk_fma_f32 v[194:195], v[212:213], v[114:115], v[194:195]
	v_pk_fma_f32 v[158:159], v[214:215], v[116:117], v[158:159]
	ds_read_b128 v[200:203], v171 offset:18432
	ds_read_b128 v[204:207], v171 offset:18448
	ds_read_b128 v[208:211], v171 offset:18464
	ds_read_b128 v[212:215], v171 offset:18480
	s_waitcnt lgkmcnt(15)
	v_pk_fma_f32 v[160:161], v[84:85], v[32:33], 0 op_sel_hi:[1,1,0]
	v_pk_fma_f32 v[162:163], v[88:89], v[34:35], 0 op_sel_hi:[1,1,0]
	v_pk_fma_f32 v[164:165], v[100:101], v[32:33], 0 op_sel_hi:[1,1,0]
	v_pk_fma_f32 v[166:167], v[104:105], v[34:35], 0 op_sel_hi:[1,1,0]
	v_pk_fma_f32 v[160:161], v[86:87], v[36:37], v[160:161]
	v_pk_fma_f32 v[162:163], v[92:93], v[38:39], v[162:163]
	v_pk_fma_f32 v[164:165], v[106:107], v[36:37], v[164:165]
	v_pk_fma_f32 v[166:167], v[108:109], v[38:39], v[166:167]
	v_pk_fma_f32 v[160:161], v[90:91], v[40:41], v[160:161]
	v_pk_fma_f32 v[162:163], v[98:99], v[42:43], v[162:163]
	v_pk_fma_f32 v[164:165], v[110:111], v[40:41], v[164:165]
	v_pk_fma_f32 v[166:167], v[112:113], v[42:43], v[166:167]
	v_pk_fma_f32 v[160:161], v[94:95], v[44:45], v[160:161]
	v_pk_fma_f32 v[162:163], v[102:103], v[46:47], v[162:163]
	v_pk_fma_f32 v[164:165], v[114:115], v[44:45], v[164:165]
	v_pk_fma_f32 v[166:167], v[116:117], v[46:47], v[166:167]
	ds_read_b128 v[32:35], v171 offset:14592
	ds_read_b128 v[36:39], v171 offset:14608
	ds_read_b128 v[40:43], v171 offset:14624
	ds_read_b128 v[44:47], v171 offset:14640
	v_pk_add_f32 v[160:161], v[162:163], v[160:161]
	v_pk_add_f32 v[164:165], v[166:167], v[164:165]
	v_pk_add_f32 v[248:249], v[250:251], v[248:249]
	v_pk_add_f32 v[194:195], v[158:159], v[194:195]
	v_add_f32_e32 v168, v160, v161
	v_add_f32_e32 v169, v164, v165
	v_add_f32_e32 v224, v248, v249
	v_add_f32_e32 v225, v194, v195
	v_add_f32_dpp v168, v168, v168 quad_perm:[1,0,3,2] row_mask:0xf bank_mask:0xf bound_ctrl:1
	v_add_f32_dpp v169, v169, v169 quad_perm:[1,0,3,2] row_mask:0xf bank_mask:0xf bound_ctrl:1
	v_add_f32_dpp v224, v224, v224 quad_perm:[1,0,3,2] row_mask:0xf bank_mask:0xf bound_ctrl:1
	v_add_f32_dpp v225, v225, v225 quad_perm:[1,0,3,2] row_mask:0xf bank_mask:0xf bound_ctrl:1
	v_add_f32_dpp v190, v168, v168 quad_perm:[2,3,0,1] row_mask:0xf bank_mask:0xf bound_ctrl:1
	v_add_f32_dpp v192, v169, v169 quad_perm:[2,3,0,1] row_mask:0xf bank_mask:0xf bound_ctrl:1
	v_add_f32_dpp v224, v224, v224 quad_perm:[2,3,0,1] row_mask:0xf bank_mask:0xf bound_ctrl:1
	v_add_f32_dpp v225, v225, v225 quad_perm:[2,3,0,1] row_mask:0xf bank_mask:0xf bound_ctrl:1
	s_and_saveexec_b64 s[34:35], s[8:9]
	ds_write_b64 v75, v[224:225] offset:1792
	s_or_b64 exec, exec, s[34:35]
	s_waitcnt lgkmcnt(9)
; #define LAS __attribute__((address_space(3)))
; __device__ __forceinline__ float red4(float x) { x = DPP_ADD(x, 0xB1); x = DPP_ADD(x, 0x4E); return x; }
; __device__ __forceinline__ void phase_scan(const ScanArgs A, LAS unsigned char* lds) {
;     ...
;                 for (int t = 0; t < 16; ++t) {
;                     const LAS float* q = in + t * 64 + kq * 16;
;                     f32x4 Wv[4], KDv[4], Bv[4], ANv[4], Rv[4];
; #pragma unroll
;                     for (int j = 0; j < 4; ++j) { Wv[j] = *(const LAS f32x4*)(q + 4 * j); KDv[j] = *(const LAS f32x4*)(q + 1024 + 4 * j); Bv[j] = *(const LAS f32x4*)(q + 2048 + 4 * j);
;                                                   ANv[j] = *(const LAS f32x4*)(q + 3072 + 4 * j); Rv[j] = *(const LAS f32x4*)(q + 4096 + 4 * j); }
;                     const f32x2 v2 = *(const LAS f32x2*)(in + 5120 + t * 64 + half * 32 + rb * 2);
;     ...
;                     float sa[2], y[2];
; #pragma unroll
;                     for (int i = 0; i < 2; ++i) { f32x2 a0 = {0.f, 0.f}, a1 = {0.f, 0.f};
; #pragma unroll
;                         for (int p = 0; p < 8; p += 2) { a0 += S2[i][p] * PAIR(ANv, p); a1 += S2[i][p + 1] * PAIR(ANv, p + 1); }
;                         a0 += a1; sa[i] = red4(a0[0] + a0[1]); }
; #pragma unroll
;                     for (int i = 0; i < 2; ++i) { f32x2 y0 = {0.f, 0.f}, y1 = {0.f, 0.f}; const f32x2 sai = {sa[i], sa[i]}, vi = {v2[i], v2[i]};
; #pragma unroll
;                         for (int p = 0; p < 8; p += 2) {
;                             const f32x2 n0 = S2[i][p] * PAIR(Wv, p) + sai * PAIR(Bv, p) + vi * PAIR(KDv, p);
;                             const f32x2 n1 = S2[i][p + 1] * PAIR(Wv, p + 1) + sai * PAIR(Bv, p + 1) + vi * PAIR(KDv, p + 1);
;                             S2[i][p] = n0; S2[i][p + 1] = n1; y0 += n0 * PAIR(Rv, p); y1 += n1 * PAIR(Rv, p + 1); }
;                         y0 += y1; y[i] = red4(y0[0] + y0[1]); }
;     ...
;                     if (kq == 0) *(LAS f32x2*)(yb + t * 64 + half * 32 + rb * 2) = (f32x2){y[0], y[1]};
	v_pk_mul_f32 v[216:217], v[142:143], v[190:191] op_sel_hi:[1,0]
	v_pk_mul_f32 v[218:219], v[144:145], v[190:191] op_sel_hi:[1,0]
	v_pk_mul_f32 v[220:221], v[142:143], v[192:193] op_sel_hi:[1,0]
	v_pk_mul_f32 v[222:223], v[144:145], v[192:193] op_sel_hi:[1,0]
	v_pk_fma_f32 v[216:217], v[84:85], v[48:49], v[216:217]
	v_pk_fma_f32 v[218:219], v[88:89], v[50:51], v[218:219]
	v_pk_fma_f32 v[220:221], v[100:101], v[48:49], v[220:221]
	v_pk_fma_f32 v[222:223], v[104:105], v[50:51], v[222:223]
	v_pk_fma_f32 v[84:85], v[172:173], v[188:189], v[216:217] op_sel_hi:[1,0,1]
	v_pk_fma_f32 v[88:89], v[174:175], v[188:189], v[218:219] op_sel_hi:[1,0,1]
	v_pk_fma_f32 v[100:101], v[172:173], v[188:189], v[220:221] op_sel:[0,1,0]
	v_pk_fma_f32 v[104:105], v[174:175], v[188:189], v[222:223] op_sel:[0,1,0]
	ds_read_b128 v[142:145], v171 offset:10496
	ds_read_b128 v[48:51], v171 offset:2304
	ds_read_b128 v[172:175], v171 offset:6400
	v_pk_mul_f32 v[216:217], v[146:147], v[190:191] op_sel_hi:[1,0]
	v_pk_mul_f32 v[218:219], v[148:149], v[190:191] op_sel_hi:[1,0]
	v_pk_mul_f32 v[220:221], v[146:147], v[192:193] op_sel_hi:[1,0]
	v_pk_mul_f32 v[222:223], v[148:149], v[192:193] op_sel_hi:[1,0]
	v_pk_fma_f32 v[216:217], v[86:87], v[52:53], v[216:217]
	v_pk_fma_f32 v[218:219], v[92:93], v[54:55], v[218:219]
	v_pk_fma_f32 v[220:221], v[106:107], v[52:53], v[220:221]
	v_pk_fma_f32 v[222:223], v[108:109], v[54:55], v[222:223]
	v_pk_fma_f32 v[86:87], v[176:177], v[188:189], v[216:217] op_sel_hi:[1,0,1]
	v_pk_fma_f32 v[92:93], v[178:179], v[188:189], v[218:219] op_sel_hi:[1,0,1]
	v_pk_fma_f32 v[106:107], v[176:177], v[188:189], v[220:221] op_sel:[0,1,0]
	v_pk_fma_f32 v[108:109], v[178:179], v[188:189], v[222:223] op_sel:[0,1,0]
	ds_read_b128 v[146:149], v171 offset:10512
	ds_read_b128 v[52:55], v171 offset:2320
	ds_read_b128 v[176:179], v171 offset:6416
	v_pk_mul_f32 v[216:217], v[150:151], v[190:191] op_sel_hi:[1,0]
	v_pk_mul_f32 v[218:219], v[152:153], v[190:191] op_sel_hi:[1,0]
	v_pk_mul_f32 v[220:221], v[150:151], v[192:193] op_sel_hi:[1,0]
	v_pk_mul_f32 v[222:223], v[152:153], v[192:193] op_sel_hi:[1,0]
	v_pk_fma_f32 v[216:217], v[90:91], v[56:57], v[216:217]
	v_pk_fma_f32 v[218:219], v[98:99], v[58:59], v[218:219]
	v_pk_fma_f32 v[220:221], v[110:111], v[56:57], v[220:221]
	v_pk_fma_f32 v[222:223], v[112:113], v[58:59], v[222:223]
	v_pk_fma_f32 v[90:91], v[180:181], v[188:189], v[216:217] op_sel_hi:[1,0,1]
	v_pk_fma_f32 v[98:99], v[182:183], v[188:189], v[218:219] op_sel_hi:[1,0,1]
	v_pk_fma_f32 v[110:111], v[180:181], v[188:189], v[220:221] op_sel:[0,1,0]
	v_pk_fma_f32 v[112:113], v[182:183], v[188:189], v[222:223] op_sel:[0,1,0]
	ds_read_b128 v[150:153], v171 offset:10528
	ds_read_b128 v[56:59], v171 offset:2336
	ds_read_b128 v[180:183], v171 offset:6432
	v_pk_mul_f32 v[216:217], v[154:155], v[190:191] op_sel_hi:[1,0]
	v_pk_mul_f32 v[218:219], v[156:157], v[190:191] op_sel_hi:[1,0]
	v_pk_mul_f32 v[220:221], v[154:155], v[192:193] op_sel_hi:[1,0]
	v_pk_mul_f32 v[222:223], v[156:157], v[192:193] op_sel_hi:[1,0]
	v_pk_fma_f32 v[216:217], v[94:95], v[60:61], v[216:217]
	v_pk_fma_f32 v[218:219], v[102:103], v[62:63], v[218:219]
	v_pk_fma_f32 v[220:221], v[114:115], v[60:61], v[220:221]
	v_pk_fma_f32 v[222:223], v[116:117], v[62:63], v[222:223]
	v_pk_fma_f32 v[94:95], v[184:185], v[188:189], v[216:217] op_sel_hi:[1,0,1]
	v_pk_fma_f32 v[102:103], v[186:187], v[188:189], v[218:219] op_sel_hi:[1,0,1]
	v_pk_fma_f32 v[114:115], v[184:185], v[188:189], v[220:221] op_sel:[0,1,0]
	v_pk_fma_f32 v[116:117], v[186:187], v[188:189], v[222:223] op_sel:[0,1,0]
	ds_read_b128 v[154:157], v171 offset:10544
	ds_read_b128 v[60:63], v171 offset:2352
	ds_read_b128 v[184:187], v171 offset:6448
	ds_read_b64 v[188:189], v96 offset:2304
	s_waitcnt lgkmcnt(15)
	v_pk_fma_f32 v[248:249], v[200:201], v[84:85], 0 op_sel_hi:[1,1,0]
	v_pk_fma_f32 v[250:251], v[202:203], v[88:89], 0 op_sel_hi:[1,1,0]
	v_pk_fma_f32 v[194:195], v[200:201], v[100:101], 0 op_sel_hi:[1,1,0]
	v_pk_fma_f32 v[158:159], v[202:203], v[104:105], 0 op_sel_hi:[1,1,0]
	v_pk_fma_f32 v[248:249], v[204:205], v[86:87], v[248:249]
	v_pk_fma_f32 v[250:251], v[206:207], v[92:93], v[250:251]
	v_pk_fma_f32 v[194:195], v[204:205], v[106:107], v[194:195]
	v_pk_fma_f32 v[158:159], v[206:207], v[108:109], v[158:159]
	v_pk_fma_f32 v[248:249], v[208:209], v[90:91], v[248:249]
	v_pk_fma_f32 v[250:251], v[210:211], v[98:99], v[250:251]
	v_pk_fma_f32 v[194:195], v[208:209], v[110:111], v[194:195]
	v_pk_fma_f32 v[158:159], v[210:211], v[112:113], v[158:159]
	v_pk_fma_f32 v[248:249], v[212:213], v[94:95], v[248:249]
	v_pk_fma_f32 v[250:251], v[214:215], v[102:103], v[250:251]
	v_pk_fma_f32 v[194:195], v[212:213], v[114:115], v[194:195]
	v_pk_fma_f32 v[158:159], v[214:215], v[116:117], v[158:159]
	ds_read_b128 v[200:203], v171 offset:18688
	ds_read_b128 v[204:207], v171 offset:18704
	ds_read_b128 v[208:211], v171 offset:18720
	ds_read_b128 v[212:215], v171 offset:18736
	s_waitcnt lgkmcnt(15)
; #define LAS __attribute__((address_space(3)))
; __device__ __forceinline__ float red4(float x) { x = DPP_ADD(x, 0xB1); x = DPP_ADD(x, 0x4E); return x; }
; __device__ __forceinline__ void phase_scan(const ScanArgs A, LAS unsigned char* lds) {
;     ...
;                 for (int t = 0; t < 16; ++t) {
;                     const LAS float* q = in + t * 64 + kq * 16;
;                     f32x4 Wv[4], KDv[4], Bv[4], ANv[4], Rv[4];
; #pragma unroll
;                     for (int j = 0; j < 4; ++j) { Wv[j] = *(const LAS f32x4*)(q + 4 * j); KDv[j] = *(const LAS f32x4*)(q + 1024 + 4 * j); Bv[j] = *(const LAS f32x4*)(q + 2048 + 4 * j);
;                                                   ANv[j] = *(const LAS f32x4*)(q + 3072 + 4 * j); Rv[j] = *(const LAS f32x4*)(q + 4096 + 4 * j); }
;                     const f32x2 v2 = *(const LAS f32x2*)(in + 5120 + t * 64 + half * 32 + rb * 2);
;     ...
;                     float sa[2], y[2];
; #pragma unroll
;                     for (int i = 0; i < 2; ++i) { f32x2 a0 = {0.f, 0.f}, a1 = {0.f, 0.f};
; #pragma unroll
;                         for (int p = 0; p < 8; p += 2) { a0 += S2[i][p] * PAIR(ANv, p); a1 += S2[i][p + 1] * PAIR(ANv, p + 1); }
;                         a0 += a1; sa[i] = red4(a0[0] + a0[1]); }
; #pragma unroll
;                     for (int i = 0; i < 2; ++i) { f32x2 y0 = {0.f, 0.f}, y1 = {0.f, 0.f}; const f32x2 sai = {sa[i], sa[i]}, vi = {v2[i], v2[i]};
; #pragma unroll
;                         for (int p = 0; p < 8; p += 2) {
;                             const f32x2 n0 = S2[i][p] * PAIR(Wv, p) + sai * PAIR(Bv, p) + vi * PAIR(KDv, p);
;                             const f32x2 n1 = S2[i][p + 1] * PAIR(Wv, p + 1) + sai * PAIR(Bv, p + 1) + vi * PAIR(KDv, p + 1);
;                             S2[i][p] = n0; S2[i][p + 1] = n1; y0 += n0 * PAIR(Rv, p); y1 += n1 * PAIR(Rv, p + 1); }
;                         y0 += y1; y[i] = red4(y0[0] + y0[1]); }
;     ...
;                     if (kq == 0) *(LAS f32x2*)(yb + t * 64 + half * 32 + rb * 2) = (f32x2){y[0], y[1]};
	v_pk_fma_f32 v[160:161], v[84:85], v[32:33], 0 op_sel_hi:[1,1,0]
	v_pk_fma_f32 v[162:163], v[88:89], v[34:35], 0 op_sel_hi:[1,1,0]
	v_pk_fma_f32 v[164:165], v[100:101], v[32:33], 0 op_sel_hi:[1,1,0]
	v_pk_fma_f32 v[166:167], v[104:105], v[34:35], 0 op_sel_hi:[1,1,0]
	v_pk_fma_f32 v[160:161], v[86:87], v[36:37], v[160:161]
	v_pk_fma_f32 v[162:163], v[92:93], v[38:39], v[162:163]
	v_pk_fma_f32 v[164:165], v[106:107], v[36:37], v[164:165]
	v_pk_fma_f32 v[166:167], v[108:109], v[38:39], v[166:167]
	v_pk_fma_f32 v[160:161], v[90:91], v[40:41], v[160:161]
	v_pk_fma_f32 v[162:163], v[98:99], v[42:43], v[162:163]
	v_pk_fma_f32 v[164:165], v[110:111], v[40:41], v[164:165]
	v_pk_fma_f32 v[166:167], v[112:113], v[42:43], v[166:167]
	v_pk_fma_f32 v[160:161], v[94:95], v[44:45], v[160:161]
	v_pk_fma_f32 v[162:163], v[102:103], v[46:47], v[162:163]
	v_pk_fma_f32 v[164:165], v[114:115], v[44:45], v[164:165]
	v_pk_fma_f32 v[166:167], v[116:117], v[46:47], v[166:167]
	ds_read_b128 v[32:35], v171 offset:14848
	ds_read_b128 v[36:39], v171 offset:14864
	ds_read_b128 v[40:43], v171 offset:14880
	ds_read_b128 v[44:47], v171 offset:14896
	v_pk_add_f32 v[160:161], v[162:163], v[160:161]
	v_pk_add_f32 v[164:165], v[166:167], v[164:165]
	v_pk_add_f32 v[248:249], v[250:251], v[248:249]
	v_pk_add_f32 v[194:195], v[158:159], v[194:195]
	v_add_f32_e32 v168, v160, v161
	v_add_f32_e32 v169, v164, v165
	v_add_f32_e32 v224, v248, v249
	v_add_f32_e32 v225, v194, v195
	v_add_f32_dpp v168, v168, v168 quad_perm:[1,0,3,2] row_mask:0xf bank_mask:0xf bound_ctrl:1
	v_add_f32_dpp v169, v169, v169 quad_perm:[1,0,3,2] row_mask:0xf bank_mask:0xf bound_ctrl:1
	v_add_f32_dpp v224, v224, v224 quad_perm:[1,0,3,2] row_mask:0xf bank_mask:0xf bound_ctrl:1
	v_add_f32_dpp v225, v225, v225 quad_perm:[1,0,3,2] row_mask:0xf bank_mask:0xf bound_ctrl:1
	v_add_f32_dpp v190, v168, v168 quad_perm:[2,3,0,1] row_mask:0xf bank_mask:0xf bound_ctrl:1
	v_add_f32_dpp v192, v169, v169 quad_perm:[2,3,0,1] row_mask:0xf bank_mask:0xf bound_ctrl:1
	v_add_f32_dpp v224, v224, v224 quad_perm:[2,3,0,1] row_mask:0xf bank_mask:0xf bound_ctrl:1
	v_add_f32_dpp v225, v225, v225 quad_perm:[2,3,0,1] row_mask:0xf bank_mask:0xf bound_ctrl:1
	s_and_saveexec_b64 s[34:35], s[8:9]
	ds_write_b64 v75, v[224:225] offset:2048
	s_or_b64 exec, exec, s[34:35]
	s_waitcnt lgkmcnt(9)
	v_pk_mul_f32 v[216:217], v[142:143], v[190:191] op_sel_hi:[1,0]
	v_pk_mul_f32 v[218:219], v[144:145], v[190:191] op_sel_hi:[1,0]
	v_pk_mul_f32 v[220:221], v[142:143], v[192:193] op_sel_hi:[1,0]
	v_pk_mul_f32 v[222:223], v[144:145], v[192:193] op_sel_hi:[1,0]
	v_pk_fma_f32 v[216:217], v[84:85], v[48:49], v[216:217]
	v_pk_fma_f32 v[218:219], v[88:89], v[50:51], v[218:219]
	v_pk_fma_f32 v[220:221], v[100:101], v[48:49], v[220:221]
	v_pk_fma_f32 v[222:223], v[104:105], v[50:51], v[222:223]
	v_pk_fma_f32 v[84:85], v[172:173], v[188:189], v[216:217] op_sel_hi:[1,0,1]
	v_pk_fma_f32 v[88:89], v[174:175], v[188:189], v[218:219] op_sel_hi:[1,0,1]
	v_pk_fma_f32 v[100:101], v[172:173], v[188:189], v[220:221] op_sel:[0,1,0]
	v_pk_fma_f32 v[104:105], v[174:175], v[188:189], v[222:223] op_sel:[0,1,0]
	ds_read_b128 v[142:145], v171 offset:10752
	ds_read_b128 v[48:51], v171 offset:2560
	ds_read_b128 v[172:175], v171 offset:6656
	v_pk_mul_f32 v[216:217], v[146:147], v[190:191] op_sel_hi:[1,0]
	v_pk_mul_f32 v[218:219], v[148:149], v[190:191] op_sel_hi:[1,0]
	v_pk_mul_f32 v[220:221], v[146:147], v[192:193] op_sel_hi:[1,0]
	v_pk_mul_f32 v[222:223], v[148:149], v[192:193] op_sel_hi:[1,0]
	v_pk_fma_f32 v[216:217], v[86:87], v[52:53], v[216:217]
	v_pk_fma_f32 v[218:219], v[92:93], v[54:55], v[218:219]
	v_pk_fma_f32 v[220:221], v[106:107], v[52:53], v[220:221]
	v_pk_fma_f32 v[222:223], v[108:109], v[54:55], v[222:223]
	v_pk_fma_f32 v[86:87], v[176:177], v[188:189], v[216:217] op_sel_hi:[1,0,1]
	v_pk_fma_f32 v[92:93], v[178:179], v[188:189], v[218:219] op_sel_hi:[1,0,1]
	v_pk_fma_f32 v[106:107], v[176:177], v[188:189], v[220:221] op_sel:[0,1,0]
	v_pk_fma_f32 v[108:109], v[178:179], v[188:189], v[222:223] op_sel:[0,1,0]
	ds_read_b128 v[146:149], v171 offset:10768
	ds_read_b128 v[52:55], v171 offset:2576
	ds_read_b128 v[176:179], v171 offset:6672
	v_pk_mul_f32 v[216:217], v[150:151], v[190:191] op_sel_hi:[1,0]
	v_pk_mul_f32 v[218:219], v[152:153], v[190:191] op_sel_hi:[1,0]
	v_pk_mul_f32 v[220:221], v[150:151], v[192:193] op_sel_hi:[1,0]
	v_pk_mul_f32 v[222:223], v[152:153], v[192:193] op_sel_hi:[1,0]
	v_pk_fma_f32 v[216:217], v[90:91], v[56:57], v[216:217]
	v_pk_fma_f32 v[218:219], v[98:99], v[58:59], v[218:219]
	v_pk_fma_f32 v[220:221], v[110:111], v[56:57], v[220:221]
	v_pk_fma_f32 v[222:223], v[112:113], v[58:59], v[222:223]
	v_pk_fma_f32 v[90:91], v[180:181], v[188:189], v[216:217] op_sel_hi:[1,0,1]
	v_pk_fma_f32 v[98:99], v[182:183], v[188:189], v[218:219] op_sel_hi:[1,0,1]
	v_pk_fma_f32 v[110:111], v[180:181], v[188:189], v[220:221] op_sel:[0,1,0]
	v_pk_fma_f32 v[112:113], v[182:183], v[188:189], v[222:223] op_sel:[0,1,0]
	ds_read_b128 v[150:153], v171 offset:10784
	ds_read_b128 v[56:59], v171 offset:2592
	ds_read_b128 v[180:183], v171 offset:6688
	v_pk_mul_f32 v[216:217], v[154:155], v[190:191] op_sel_hi:[1,0]
	v_pk_mul_f32 v[218:219], v[156:157], v[190:191] op_sel_hi:[1,0]
	v_pk_mul_f32 v[220:221], v[154:155], v[192:193] op_sel_hi:[1,0]
	v_pk_mul_f32 v[222:223], v[156:157], v[192:193] op_sel_hi:[1,0]
	v_pk_fma_f32 v[216:217], v[94:95], v[60:61], v[216:217]
	v_pk_fma_f32 v[218:219], v[102:103], v[62:63], v[218:219]
	v_pk_fma_f32 v[220:221], v[114:115], v[60:61], v[220:221]
	v_pk_fma_f32 v[222:223], v[116:117], v[62:63], v[222:223]
	v_pk_fma_f32 v[94:95], v[184:185], v[188:189], v[216:217] op_sel_hi:[1,0,1]
	v_pk_fma_f32 v[102:103], v[186:187], v[188:189], v[218:219] op_sel_hi:[1,0,1]
	v_pk_fma_f32 v[114:115], v[184:185], v[188:189], v[220:221] op_sel:[0,1,0]
	v_pk_fma_f32 v[116:117], v[186:187], v[188:189], v[222:223] op_sel:[0,1,0]
	ds_read_b128 v[154:157], v171 offset:10800
	ds_read_b128 v[60:63], v171 offset:2608
	ds_read_b128 v[184:187], v171 offset:6704
	ds_read_b64 v[188:189], v96 offset:2560
	s_waitcnt lgkmcnt(15)
; #define LAS __attribute__((address_space(3)))
; __device__ __forceinline__ float red4(float x) { x = DPP_ADD(x, 0xB1); x = DPP_ADD(x, 0x4E); return x; }
; __device__ __forceinline__ void phase_scan(const ScanArgs A, LAS unsigned char* lds) {
;     ...
;                 for (int t = 0; t < 16; ++t) {
;                     const LAS float* q = in + t * 64 + kq * 16;
;                     f32x4 Wv[4], KDv[4], Bv[4], ANv[4], Rv[4];
; #pragma unroll
;                     for (int j = 0; j < 4; ++j) { Wv[j] = *(const LAS f32x4*)(q + 4 * j); KDv[j] = *(const LAS f32x4*)(q + 1024 + 4 * j); Bv[j] = *(const LAS f32x4*)(q + 2048 + 4 * j);
;                                                   ANv[j] = *(const LAS f32x4*)(q + 3072 + 4 * j); Rv[j] = *(const LAS f32x4*)(q + 4096 + 4 * j); }
;                     const f32x2 v2 = *(const LAS f32x2*)(in + 5120 + t * 64 + half * 32 + rb * 2);
;     ...
;                     float sa[2], y[2];
; #pragma unroll
;                     for (int i = 0; i < 2; ++i) { f32x2 a0 = {0.f, 0.f}, a1 = {0.f, 0.f};
; #pragma unroll
;                         for (int p = 0; p < 8; p += 2) { a0 += S2[i][p] * PAIR(ANv, p); a1 += S2[i][p + 1] * PAIR(ANv, p + 1); }
;                         a0 += a1; sa[i] = red4(a0[0] + a0[1]); }
; #pragma unroll
;                     for (int i = 0; i < 2; ++i) { f32x2 y0 = {0.f, 0.f}, y1 = {0.f, 0.f}; const f32x2 sai = {sa[i], sa[i]}, vi = {v2[i], v2[i]};
; #pragma unroll
;                         for (int p = 0; p < 8; p += 2) {
;                             const f32x2 n0 = S2[i][p] * PAIR(Wv, p) + sai * PAIR(Bv, p) + vi * PAIR(KDv, p);
;                             const f32x2 n1 = S2[i][p + 1] * PAIR(Wv, p + 1) + sai * PAIR(Bv, p + 1) + vi * PAIR(KDv, p + 1);
;                             S2[i][p] = n0; S2[i][p + 1] = n1; y0 += n0 * PAIR(Rv, p); y1 += n1 * PAIR(Rv, p + 1); }
;                         y0 += y1; y[i] = red4(y0[0] + y0[1]); }
;     ...
;                     if (kq == 0) *(LAS f32x2*)(yb + t * 64 + half * 32 + rb * 2) = (f32x2){y[0], y[1]};
;                 }
	v_pk_fma_f32 v[248:249], v[200:201], v[84:85], 0 op_sel_hi:[1,1,0]
	v_pk_fma_f32 v[250:251], v[202:203], v[88:89], 0 op_sel_hi:[1,1,0]
	v_pk_fma_f32 v[194:195], v[200:201], v[100:101], 0 op_sel_hi:[1,1,0]
	v_pk_fma_f32 v[158:159], v[202:203], v[104:105], 0 op_sel_hi:[1,1,0]
	v_pk_fma_f32 v[248:249], v[204:205], v[86:87], v[248:249]
	v_pk_fma_f32 v[250:251], v[206:207], v[92:93], v[250:251]
	v_pk_fma_f32 v[194:195], v[204:205], v[106:107], v[194:195]
	v_pk_fma_f32 v[158:159], v[206:207], v[108:109], v[158:159]
	v_pk_fma_f32 v[248:249], v[208:209], v[90:91], v[248:249]
	v_pk_fma_f32 v[250:251], v[210:211], v[98:99], v[250:251]
	v_pk_fma_f32 v[194:195], v[208:209], v[110:111], v[194:195]
	v_pk_fma_f32 v[158:159], v[210:211], v[112:113], v[158:159]
	v_pk_fma_f32 v[248:249], v[212:213], v[94:95], v[248:249]
	v_pk_fma_f32 v[250:251], v[214:215], v[102:103], v[250:251]
	v_pk_fma_f32 v[194:195], v[212:213], v[114:115], v[194:195]
	v_pk_fma_f32 v[158:159], v[214:215], v[116:117], v[158:159]
	ds_read_b128 v[200:203], v171 offset:18944
	ds_read_b128 v[204:207], v171 offset:18960
	ds_read_b128 v[208:211], v171 offset:18976
	ds_read_b128 v[212:215], v171 offset:18992
	s_waitcnt lgkmcnt(15)
	v_pk_fma_f32 v[160:161], v[84:85], v[32:33], 0 op_sel_hi:[1,1,0]
	v_pk_fma_f32 v[162:163], v[88:89], v[34:35], 0 op_sel_hi:[1,1,0]
	v_pk_fma_f32 v[164:165], v[100:101], v[32:33], 0 op_sel_hi:[1,1,0]
	v_pk_fma_f32 v[166:167], v[104:105], v[34:35], 0 op_sel_hi:[1,1,0]
	v_pk_fma_f32 v[160:161], v[86:87], v[36:37], v[160:161]
	v_pk_fma_f32 v[162:163], v[92:93], v[38:39], v[162:163]
	v_pk_fma_f32 v[164:165], v[106:107], v[36:37], v[164:165]
	v_pk_fma_f32 v[166:167], v[108:109], v[38:39], v[166:167]
	v_pk_fma_f32 v[160:161], v[90:91], v[40:41], v[160:161]
	v_pk_fma_f32 v[162:163], v[98:99], v[42:43], v[162:163]
	v_pk_fma_f32 v[164:165], v[110:111], v[40:41], v[164:165]
	v_pk_fma_f32 v[166:167], v[112:113], v[42:43], v[166:167]
	v_pk_fma_f32 v[160:161], v[94:95], v[44:45], v[160:161]
	v_pk_fma_f32 v[162:163], v[102:103], v[46:47], v[162:163]
	v_pk_fma_f32 v[164:165], v[114:115], v[44:45], v[164:165]
	v_pk_fma_f32 v[166:167], v[116:117], v[46:47], v[166:167]
	ds_read_b128 v[32:35], v171 offset:15104
	ds_read_b128 v[36:39], v171 offset:15120
	ds_read_b128 v[40:43], v171 offset:15136
	ds_read_b128 v[44:47], v171 offset:15152
	v_pk_add_f32 v[160:161], v[162:163], v[160:161]
	v_pk_add_f32 v[164:165], v[166:167], v[164:165]
	v_pk_add_f32 v[248:249], v[250:251], v[248:249]
	v_pk_add_f32 v[194:195], v[158:159], v[194:195]
	v_add_f32_e32 v168, v160, v161
	v_add_f32_e32 v169, v164, v165
	v_add_f32_e32 v224, v248, v249
	v_add_f32_e32 v225, v194, v195
	v_add_f32_dpp v168, v168, v168 quad_perm:[1,0,3,2] row_mask:0xf bank_mask:0xf bound_ctrl:1
	v_add_f32_dpp v169, v169, v169 quad_perm:[1,0,3,2] row_mask:0xf bank_mask:0xf bound_ctrl:1
	v_add_f32_dpp v224, v224, v224 quad_perm:[1,0,3,2] row_mask:0xf bank_mask:0xf bound_ctrl:1
	v_add_f32_dpp v225, v225, v225 quad_perm:[1,0,3,2] row_mask:0xf bank_mask:0xf bound_ctrl:1
	v_add_f32_dpp v190, v168, v168 quad_perm:[2,3,0,1] row_mask:0xf bank_mask:0xf bound_ctrl:1
	v_add_f32_dpp v192, v169, v169 quad_perm:[2,3,0,1] row_mask:0xf bank_mask:0xf bound_ctrl:1
	v_add_f32_dpp v224, v224, v224 quad_perm:[2,3,0,1] row_mask:0xf bank_mask:0xf bound_ctrl:1
	v_add_f32_dpp v225, v225, v225 quad_perm:[2,3,0,1] row_mask:0xf bank_mask:0xf bound_ctrl:1
	s_and_saveexec_b64 s[34:35], s[8:9]
	ds_write_b64 v75, v[224:225] offset:2304
	s_or_b64 exec, exec, s[34:35]
	s_waitcnt lgkmcnt(9)
	v_pk_mul_f32 v[216:217], v[142:143], v[190:191] op_sel_hi:[1,0]
	v_pk_mul_f32 v[218:219], v[144:145], v[190:191] op_sel_hi:[1,0]
	v_pk_mul_f32 v[220:221], v[142:143], v[192:193] op_sel_hi:[1,0]
	v_pk_mul_f32 v[222:223], v[144:145], v[192:193] op_sel_hi:[1,0]
	v_pk_fma_f32 v[216:217], v[84:85], v[48:49], v[216:217]
	v_pk_fma_f32 v[218:219], v[88:89], v[50:51], v[218:219]
	v_pk_fma_f32 v[220:221], v[100:101], v[48:49], v[220:221]
	v_pk_fma_f32 v[222:223], v[104:105], v[50:51], v[222:223]
	v_pk_fma_f32 v[84:85], v[172:173], v[188:189], v[216:217] op_sel_hi:[1,0,1]
	v_pk_fma_f32 v[88:89], v[174:175], v[188:189], v[218:219] op_sel_hi:[1,0,1]
	v_pk_fma_f32 v[100:101], v[172:173], v[188:189], v[220:221] op_sel:[0,1,0]
	v_pk_fma_f32 v[104:105], v[174:175], v[188:189], v[222:223] op_sel:[0,1,0]
	ds_read_b128 v[142:145], v171 offset:11008
	ds_read_b128 v[48:51], v171 offset:2816
	ds_read_b128 v[172:175], v171 offset:6912
	v_pk_mul_f32 v[216:217], v[146:147], v[190:191] op_sel_hi:[1,0]
	v_pk_mul_f32 v[218:219], v[148:149], v[190:191] op_sel_hi:[1,0]
	v_pk_mul_f32 v[220:221], v[146:147], v[192:193] op_sel_hi:[1,0]
	v_pk_mul_f32 v[222:223], v[148:149], v[192:193] op_sel_hi:[1,0]
	v_pk_fma_f32 v[216:217], v[86:87], v[52:53], v[216:217]
	v_pk_fma_f32 v[218:219], v[92:93], v[54:55], v[218:219]
	v_pk_fma_f32 v[220:221], v[106:107], v[52:53], v[220:221]
	v_pk_fma_f32 v[222:223], v[108:109], v[54:55], v[222:223]
	v_pk_fma_f32 v[86:87], v[176:177], v[188:189], v[216:217] op_sel_hi:[1,0,1]
	v_pk_fma_f32 v[92:93], v[178:179], v[188:189], v[218:219] op_sel_hi:[1,0,1]
	v_pk_fma_f32 v[106:107], v[176:177], v[188:189], v[220:221] op_sel:[0,1,0]
	v_pk_fma_f32 v[108:109], v[178:179], v[188:189], v[222:223] op_sel:[0,1,0]
	ds_read_b128 v[146:149], v171 offset:11024
	ds_read_b128 v[52:55], v171 offset:2832
	ds_read_b128 v[176:179], v171 offset:6928
	v_pk_mul_f32 v[216:217], v[150:151], v[190:191] op_sel_hi:[1,0]
	v_pk_mul_f32 v[218:219], v[152:153], v[190:191] op_sel_hi:[1,0]
	v_pk_mul_f32 v[220:221], v[150:151], v[192:193] op_sel_hi:[1,0]
	v_pk_mul_f32 v[222:223], v[152:153], v[192:193] op_sel_hi:[1,0]
; #define LAS __attribute__((address_space(3)))
; __device__ __forceinline__ float red4(float x) { x = DPP_ADD(x, 0xB1); x = DPP_ADD(x, 0x4E); return x; }
; __device__ __forceinline__ void phase_scan(const ScanArgs A, LAS unsigned char* lds) {
;     ...
;                 for (int t = 0; t < 16; ++t) {
;                     const LAS float* q = in + t * 64 + kq * 16;
;                     f32x4 Wv[4], KDv[4], Bv[4], ANv[4], Rv[4];
; #pragma unroll
;                     for (int j = 0; j < 4; ++j) { Wv[j] = *(const LAS f32x4*)(q + 4 * j); KDv[j] = *(const LAS f32x4*)(q + 1024 + 4 * j); Bv[j] = *(const LAS f32x4*)(q + 2048 + 4 * j);
;                                                   ANv[j] = *(const LAS f32x4*)(q + 3072 + 4 * j); Rv[j] = *(const LAS f32x4*)(q + 4096 + 4 * j); }
;                     const f32x2 v2 = *(const LAS f32x2*)(in + 5120 + t * 64 + half * 32 + rb * 2);
;     ...
;                     float sa[2], y[2];
; #pragma unroll
;                     for (int i = 0; i < 2; ++i) { f32x2 a0 = {0.f, 0.f}, a1 = {0.f, 0.f};
; #pragma unroll
;                         for (int p = 0; p < 8; p += 2) { a0 += S2[i][p] * PAIR(ANv, p); a1 += S2[i][p + 1] * PAIR(ANv, p + 1); }
;                         a0 += a1; sa[i] = red4(a0[0] + a0[1]); }
; #pragma unroll
;                     for (int i = 0; i < 2; ++i) { f32x2 y0 = {0.f, 0.f}, y1 = {0.f, 0.f}; const f32x2 sai = {sa[i], sa[i]}, vi = {v2[i], v2[i]};
; #pragma unroll
;                         for (int p = 0; p < 8; p += 2) {
;                             const f32x2 n0 = S2[i][p] * PAIR(Wv, p) + sai * PAIR(Bv, p) + vi * PAIR(KDv, p);
;                             const f32x2 n1 = S2[i][p + 1] * PAIR(Wv, p + 1) + sai * PAIR(Bv, p + 1) + vi * PAIR(KDv, p + 1);
;                             S2[i][p] = n0; S2[i][p + 1] = n1; y0 += n0 * PAIR(Rv, p); y1 += n1 * PAIR(Rv, p + 1); }
;                         y0 += y1; y[i] = red4(y0[0] + y0[1]); }
;     ...
;                     if (kq == 0) *(LAS f32x2*)(yb + t * 64 + half * 32 + rb * 2) = (f32x2){y[0], y[1]};
;                 }
	v_pk_fma_f32 v[216:217], v[90:91], v[56:57], v[216:217]
	v_pk_fma_f32 v[218:219], v[98:99], v[58:59], v[218:219]
	v_pk_fma_f32 v[220:221], v[110:111], v[56:57], v[220:221]
	v_pk_fma_f32 v[222:223], v[112:113], v[58:59], v[222:223]
	v_pk_fma_f32 v[90:91], v[180:181], v[188:189], v[216:217] op_sel_hi:[1,0,1]
	v_pk_fma_f32 v[98:99], v[182:183], v[188:189], v[218:219] op_sel_hi:[1,0,1]
	v_pk_fma_f32 v[110:111], v[180:181], v[188:189], v[220:221] op_sel:[0,1,0]
	v_pk_fma_f32 v[112:113], v[182:183], v[188:189], v[222:223] op_sel:[0,1,0]
	ds_read_b128 v[150:153], v171 offset:11040
	ds_read_b128 v[56:59], v171 offset:2848
	ds_read_b128 v[180:183], v171 offset:6944
	v_pk_mul_f32 v[216:217], v[154:155], v[190:191] op_sel_hi:[1,0]
	v_pk_mul_f32 v[218:219], v[156:157], v[190:191] op_sel_hi:[1,0]
	v_pk_mul_f32 v[220:221], v[154:155], v[192:193] op_sel_hi:[1,0]
	v_pk_mul_f32 v[222:223], v[156:157], v[192:193] op_sel_hi:[1,0]
	v_pk_fma_f32 v[216:217], v[94:95], v[60:61], v[216:217]
	v_pk_fma_f32 v[218:219], v[102:103], v[62:63], v[218:219]
	v_pk_fma_f32 v[220:221], v[114:115], v[60:61], v[220:221]
	v_pk_fma_f32 v[222:223], v[116:117], v[62:63], v[222:223]
	v_pk_fma_f32 v[94:95], v[184:185], v[188:189], v[216:217] op_sel_hi:[1,0,1]
	v_pk_fma_f32 v[102:103], v[186:187], v[188:189], v[218:219] op_sel_hi:[1,0,1]
	v_pk_fma_f32 v[114:115], v[184:185], v[188:189], v[220:221] op_sel:[0,1,0]
	v_pk_fma_f32 v[116:117], v[186:187], v[188:189], v[222:223] op_sel:[0,1,0]
	ds_read_b128 v[154:157], v171 offset:11056
	ds_read_b128 v[60:63], v171 offset:2864
	ds_read_b128 v[184:187], v171 offset:6960
	ds_read_b64 v[188:189], v96 offset:2816
	s_waitcnt lgkmcnt(15)
	v_pk_fma_f32 v[248:249], v[200:201], v[84:85], 0 op_sel_hi:[1,1,0]
	v_pk_fma_f32 v[250:251], v[202:203], v[88:89], 0 op_sel_hi:[1,1,0]
	v_pk_fma_f32 v[194:195], v[200:201], v[100:101], 0 op_sel_hi:[1,1,0]
	v_pk_fma_f32 v[158:159], v[202:203], v[104:105], 0 op_sel_hi:[1,1,0]
	v_pk_fma_f32 v[248:249], v[204:205], v[86:87], v[248:249]
	v_pk_fma_f32 v[250:251], v[206:207], v[92:93], v[250:251]
	v_pk_fma_f32 v[194:195], v[204:205], v[106:107], v[194:195]
	v_pk_fma_f32 v[158:159], v[206:207], v[108:109], v[158:159]
	v_pk_fma_f32 v[248:249], v[208:209], v[90:91], v[248:249]
	v_pk_fma_f32 v[250:251], v[210:211], v[98:99], v[250:251]
	v_pk_fma_f32 v[194:195], v[208:209], v[110:111], v[194:195]
	v_pk_fma_f32 v[158:159], v[210:211], v[112:113], v[158:159]
	v_pk_fma_f32 v[248:249], v[212:213], v[94:95], v[248:249]
	v_pk_fma_f32 v[250:251], v[214:215], v[102:103], v[250:251]
	v_pk_fma_f32 v[194:195], v[212:213], v[114:115], v[194:195]
	v_pk_fma_f32 v[158:159], v[214:215], v[116:117], v[158:159]
	ds_read_b128 v[200:203], v171 offset:19200
	ds_read_b128 v[204:207], v171 offset:19216
	ds_read_b128 v[208:211], v171 offset:19232
	ds_read_b128 v[212:215], v171 offset:19248
	s_waitcnt lgkmcnt(15)
	v_pk_fma_f32 v[160:161], v[84:85], v[32:33], 0 op_sel_hi:[1,1,0]
	v_pk_fma_f32 v[162:163], v[88:89], v[34:35], 0 op_sel_hi:[1,1,0]
	v_pk_fma_f32 v[164:165], v[100:101], v[32:33], 0 op_sel_hi:[1,1,0]
	v_pk_fma_f32 v[166:167], v[104:105], v[34:35], 0 op_sel_hi:[1,1,0]
	v_pk_fma_f32 v[160:161], v[86:87], v[36:37], v[160:161]
	v_pk_fma_f32 v[162:163], v[92:93], v[38:39], v[162:163]
	v_pk_fma_f32 v[164:165], v[106:107], v[36:37], v[164:165]
	v_pk_fma_f32 v[166:167], v[108:109], v[38:39], v[166:167]
	v_pk_fma_f32 v[160:161], v[90:91], v[40:41], v[160:161]
	v_pk_fma_f32 v[162:163], v[98:99], v[42:43], v[162:163]
	v_pk_fma_f32 v[164:165], v[110:111], v[40:41], v[164:165]
	v_pk_fma_f32 v[166:167], v[112:113], v[42:43], v[166:167]
	v_pk_fma_f32 v[160:161], v[94:95], v[44:45], v[160:161]
	v_pk_fma_f32 v[162:163], v[102:103], v[46:47], v[162:163]
	v_pk_fma_f32 v[164:165], v[114:115], v[44:45], v[164:165]
	v_pk_fma_f32 v[166:167], v[116:117], v[46:47], v[166:167]
	ds_read_b128 v[32:35], v171 offset:15360
	ds_read_b128 v[36:39], v171 offset:15376
	ds_read_b128 v[40:43], v171 offset:15392
	ds_read_b128 v[44:47], v171 offset:15408
	v_pk_add_f32 v[160:161], v[162:163], v[160:161]
	v_pk_add_f32 v[164:165], v[166:167], v[164:165]
	v_pk_add_f32 v[248:249], v[250:251], v[248:249]
	v_pk_add_f32 v[194:195], v[158:159], v[194:195]
	v_add_f32_e32 v168, v160, v161
	v_add_f32_e32 v169, v164, v165
	v_add_f32_e32 v224, v248, v249
	v_add_f32_e32 v225, v194, v195
	v_add_f32_dpp v168, v168, v168 quad_perm:[1,0,3,2] row_mask:0xf bank_mask:0xf bound_ctrl:1
	v_add_f32_dpp v169, v169, v169 quad_perm:[1,0,3,2] row_mask:0xf bank_mask:0xf bound_ctrl:1
	v_add_f32_dpp v224, v224, v224 quad_perm:[1,0,3,2] row_mask:0xf bank_mask:0xf bound_ctrl:1
	v_add_f32_dpp v225, v225, v225 quad_perm:[1,0,3,2] row_mask:0xf bank_mask:0xf bound_ctrl:1
	v_add_f32_dpp v190, v168, v168 quad_perm:[2,3,0,1] row_mask:0xf bank_mask:0xf bound_ctrl:1
	v_add_f32_dpp v192, v169, v169 quad_perm:[2,3,0,1] row_mask:0xf bank_mask:0xf bound_ctrl:1
	v_add_f32_dpp v224, v224, v224 quad_perm:[2,3,0,1] row_mask:0xf bank_mask:0xf bound_ctrl:1
	v_add_f32_dpp v225, v225, v225 quad_perm:[2,3,0,1] row_mask:0xf bank_mask:0xf bound_ctrl:1
	s_and_saveexec_b64 s[34:35], s[8:9]
	ds_write_b64 v75, v[224:225] offset:2560
	s_or_b64 exec, exec, s[34:35]
	s_waitcnt lgkmcnt(9)
; #define LAS __attribute__((address_space(3)))
; __device__ __forceinline__ float red4(float x) { x = DPP_ADD(x, 0xB1); x = DPP_ADD(x, 0x4E); return x; }
; __device__ __forceinline__ void phase_scan(const ScanArgs A, LAS unsigned char* lds) {
;     ...
;                 for (int t = 0; t < 16; ++t) {
;                     const LAS float* q = in + t * 64 + kq * 16;
;                     f32x4 Wv[4], KDv[4], Bv[4], ANv[4], Rv[4];
; #pragma unroll
;                     for (int j = 0; j < 4; ++j) { Wv[j] = *(const LAS f32x4*)(q + 4 * j); KDv[j] = *(const LAS f32x4*)(q + 1024 + 4 * j); Bv[j] = *(const LAS f32x4*)(q + 2048 + 4 * j);
;                                                   ANv[j] = *(const LAS f32x4*)(q + 3072 + 4 * j); Rv[j] = *(const LAS f32x4*)(q + 4096 + 4 * j); }
;                     const f32x2 v2 = *(const LAS f32x2*)(in + 5120 + t * 64 + half * 32 + rb * 2);
;     ...
;                     float sa[2], y[2];
; #pragma unroll
;                     for (int i = 0; i < 2; ++i) { f32x2 a0 = {0.f, 0.f}, a1 = {0.f, 0.f};
; #pragma unroll
;                         for (int p = 0; p < 8; p += 2) { a0 += S2[i][p] * PAIR(ANv, p); a1 += S2[i][p + 1] * PAIR(ANv, p + 1); }
;                         a0 += a1; sa[i] = red4(a0[0] + a0[1]); }
; #pragma unroll
;                     for (int i = 0; i < 2; ++i) { f32x2 y0 = {0.f, 0.f}, y1 = {0.f, 0.f}; const f32x2 sai = {sa[i], sa[i]}, vi = {v2[i], v2[i]};
; #pragma unroll
;                         for (int p = 0; p < 8; p += 2) {
;                             const f32x2 n0 = S2[i][p] * PAIR(Wv, p) + sai * PAIR(Bv, p) + vi * PAIR(KDv, p);
;                             const f32x2 n1 = S2[i][p + 1] * PAIR(Wv, p + 1) + sai * PAIR(Bv, p + 1) + vi * PAIR(KDv, p + 1);
;                             S2[i][p] = n0; S2[i][p + 1] = n1; y0 += n0 * PAIR(Rv, p); y1 += n1 * PAIR(Rv, p + 1); }
;                         y0 += y1; y[i] = red4(y0[0] + y0[1]); }
;     ...
;                     if (kq == 0) *(LAS f32x2*)(yb + t * 64 + half * 32 + rb * 2) = (f32x2){y[0], y[1]};
;                 }
	v_pk_mul_f32 v[216:217], v[142:143], v[190:191] op_sel_hi:[1,0]
	v_pk_mul_f32 v[218:219], v[144:145], v[190:191] op_sel_hi:[1,0]
	v_pk_mul_f32 v[220:221], v[142:143], v[192:193] op_sel_hi:[1,0]
	v_pk_mul_f32 v[222:223], v[144:145], v[192:193] op_sel_hi:[1,0]
	v_pk_fma_f32 v[216:217], v[84:85], v[48:49], v[216:217]
	v_pk_fma_f32 v[218:219], v[88:89], v[50:51], v[218:219]
	v_pk_fma_f32 v[220:221], v[100:101], v[48:49], v[220:221]
	v_pk_fma_f32 v[222:223], v[104:105], v[50:51], v[222:223]
	v_pk_fma_f32 v[84:85], v[172:173], v[188:189], v[216:217] op_sel_hi:[1,0,1]
	v_pk_fma_f32 v[88:89], v[174:175], v[188:189], v[218:219] op_sel_hi:[1,0,1]
	v_pk_fma_f32 v[100:101], v[172:173], v[188:189], v[220:221] op_sel:[0,1,0]
	v_pk_fma_f32 v[104:105], v[174:175], v[188:189], v[222:223] op_sel:[0,1,0]
	ds_read_b128 v[142:145], v171 offset:11264
	ds_read_b128 v[48:51], v171 offset:3072
	ds_read_b128 v[172:175], v171 offset:7168
	v_pk_mul_f32 v[216:217], v[146:147], v[190:191] op_sel_hi:[1,0]
	v_pk_mul_f32 v[218:219], v[148:149], v[190:191] op_sel_hi:[1,0]
	v_pk_mul_f32 v[220:221], v[146:147], v[192:193] op_sel_hi:[1,0]
	v_pk_mul_f32 v[222:223], v[148:149], v[192:193] op_sel_hi:[1,0]
	v_pk_fma_f32 v[216:217], v[86:87], v[52:53], v[216:217]
	v_pk_fma_f32 v[218:219], v[92:93], v[54:55], v[218:219]
	v_pk_fma_f32 v[220:221], v[106:107], v[52:53], v[220:221]
	v_pk_fma_f32 v[222:223], v[108:109], v[54:55], v[222:223]
	v_pk_fma_f32 v[86:87], v[176:177], v[188:189], v[216:217] op_sel_hi:[1,0,1]
	v_pk_fma_f32 v[92:93], v[178:179], v[188:189], v[218:219] op_sel_hi:[1,0,1]
	v_pk_fma_f32 v[106:107], v[176:177], v[188:189], v[220:221] op_sel:[0,1,0]
	v_pk_fma_f32 v[108:109], v[178:179], v[188:189], v[222:223] op_sel:[0,1,0]
	ds_read_b128 v[146:149], v171 offset:11280
	ds_read_b128 v[52:55], v171 offset:3088
	ds_read_b128 v[176:179], v171 offset:7184
	v_pk_mul_f32 v[216:217], v[150:151], v[190:191] op_sel_hi:[1,0]
	v_pk_mul_f32 v[218:219], v[152:153], v[190:191] op_sel_hi:[1,0]
	v_pk_mul_f32 v[220:221], v[150:151], v[192:193] op_sel_hi:[1,0]
	v_pk_mul_f32 v[222:223], v[152:153], v[192:193] op_sel_hi:[1,0]
	v_pk_fma_f32 v[216:217], v[90:91], v[56:57], v[216:217]
	v_pk_fma_f32 v[218:219], v[98:99], v[58:59], v[218:219]
	v_pk_fma_f32 v[220:221], v[110:111], v[56:57], v[220:221]
	v_pk_fma_f32 v[222:223], v[112:113], v[58:59], v[222:223]
	v_pk_fma_f32 v[90:91], v[180:181], v[188:189], v[216:217] op_sel_hi:[1,0,1]
	v_pk_fma_f32 v[98:99], v[182:183], v[188:189], v[218:219] op_sel_hi:[1,0,1]
	v_pk_fma_f32 v[110:111], v[180:181], v[188:189], v[220:221] op_sel:[0,1,0]
	v_pk_fma_f32 v[112:113], v[182:183], v[188:189], v[222:223] op_sel:[0,1,0]
	ds_read_b128 v[150:153], v171 offset:11296
	ds_read_b128 v[56:59], v171 offset:3104
	ds_read_b128 v[180:183], v171 offset:7200
	v_pk_mul_f32 v[216:217], v[154:155], v[190:191] op_sel_hi:[1,0]
	v_pk_mul_f32 v[218:219], v[156:157], v[190:191] op_sel_hi:[1,0]
	v_pk_mul_f32 v[220:221], v[154:155], v[192:193] op_sel_hi:[1,0]
	v_pk_mul_f32 v[222:223], v[156:157], v[192:193] op_sel_hi:[1,0]
	v_pk_fma_f32 v[216:217], v[94:95], v[60:61], v[216:217]
	v_pk_fma_f32 v[218:219], v[102:103], v[62:63], v[218:219]
	v_pk_fma_f32 v[220:221], v[114:115], v[60:61], v[220:221]
	v_pk_fma_f32 v[222:223], v[116:117], v[62:63], v[222:223]
	v_pk_fma_f32 v[94:95], v[184:185], v[188:189], v[216:217] op_sel_hi:[1,0,1]
	v_pk_fma_f32 v[102:103], v[186:187], v[188:189], v[218:219] op_sel_hi:[1,0,1]
	v_pk_fma_f32 v[114:115], v[184:185], v[188:189], v[220:221] op_sel:[0,1,0]
	v_pk_fma_f32 v[116:117], v[186:187], v[188:189], v[222:223] op_sel:[0,1,0]
	ds_read_b128 v[154:157], v171 offset:11312
	ds_read_b128 v[60:63], v171 offset:3120
	ds_read_b128 v[184:187], v171 offset:7216
	ds_read_b64 v[188:189], v96 offset:3072
	s_waitcnt lgkmcnt(15)
	v_pk_fma_f32 v[248:249], v[200:201], v[84:85], 0 op_sel_hi:[1,1,0]
	v_pk_fma_f32 v[250:251], v[202:203], v[88:89], 0 op_sel_hi:[1,1,0]
	v_pk_fma_f32 v[194:195], v[200:201], v[100:101], 0 op_sel_hi:[1,1,0]
	v_pk_fma_f32 v[158:159], v[202:203], v[104:105], 0 op_sel_hi:[1,1,0]
	v_pk_fma_f32 v[248:249], v[204:205], v[86:87], v[248:249]
	v_pk_fma_f32 v[250:251], v[206:207], v[92:93], v[250:251]
	v_pk_fma_f32 v[194:195], v[204:205], v[106:107], v[194:195]
	v_pk_fma_f32 v[158:159], v[206:207], v[108:109], v[158:159]
	v_pk_fma_f32 v[248:249], v[208:209], v[90:91], v[248:249]
	v_pk_fma_f32 v[250:251], v[210:211], v[98:99], v[250:251]
	v_pk_fma_f32 v[194:195], v[208:209], v[110:111], v[194:195]
	v_pk_fma_f32 v[158:159], v[210:211], v[112:113], v[158:159]
	v_pk_fma_f32 v[248:249], v[212:213], v[94:95], v[248:249]
	v_pk_fma_f32 v[250:251], v[214:215], v[102:103], v[250:251]
	v_pk_fma_f32 v[194:195], v[212:213], v[114:115], v[194:195]
	v_pk_fma_f32 v[158:159], v[214:215], v[116:117], v[158:159]
	ds_read_b128 v[200:203], v171 offset:19456
	ds_read_b128 v[204:207], v171 offset:19472
	ds_read_b128 v[208:211], v171 offset:19488
	ds_read_b128 v[212:215], v171 offset:19504
	s_waitcnt lgkmcnt(15)
; #define LAS __attribute__((address_space(3)))
; __device__ __forceinline__ float red4(float x) { x = DPP_ADD(x, 0xB1); x = DPP_ADD(x, 0x4E); return x; }
; __device__ __forceinline__ void phase_scan(const ScanArgs A, LAS unsigned char* lds) {
;     ...
;                 for (int t = 0; t < 16; ++t) {
;                     const LAS float* q = in + t * 64 + kq * 16;
;                     f32x4 Wv[4], KDv[4], Bv[4], ANv[4], Rv[4];
; #pragma unroll
;                     for (int j = 0; j < 4; ++j) { Wv[j] = *(const LAS f32x4*)(q + 4 * j); KDv[j] = *(const LAS f32x4*)(q + 1024 + 4 * j); Bv[j] = *(const LAS f32x4*)(q + 2048 + 4 * j);
;                                                   ANv[j] = *(const LAS f32x4*)(q + 3072 + 4 * j); Rv[j] = *(const LAS f32x4*)(q + 4096 + 4 * j); }
;                     const f32x2 v2 = *(const LAS f32x2*)(in + 5120 + t * 64 + half * 32 + rb * 2);
;     ...
;                     float sa[2], y[2];
; #pragma unroll
;                     for (int i = 0; i < 2; ++i) { f32x2 a0 = {0.f, 0.f}, a1 = {0.f, 0.f};
; #pragma unroll
;                         for (int p = 0; p < 8; p += 2) { a0 += S2[i][p] * PAIR(ANv, p); a1 += S2[i][p + 1] * PAIR(ANv, p + 1); }
;                         a0 += a1; sa[i] = red4(a0[0] + a0[1]); }
; #pragma unroll
;                     for (int i = 0; i < 2; ++i) { f32x2 y0 = {0.f, 0.f}, y1 = {0.f, 0.f}; const f32x2 sai = {sa[i], sa[i]}, vi = {v2[i], v2[i]};
; #pragma unroll
;                         for (int p = 0; p < 8; p += 2) {
;                             const f32x2 n0 = S2[i][p] * PAIR(Wv, p) + sai * PAIR(Bv, p) + vi * PAIR(KDv, p);
;                             const f32x2 n1 = S2[i][p + 1] * PAIR(Wv, p + 1) + sai * PAIR(Bv, p + 1) + vi * PAIR(KDv, p + 1);
;                             S2[i][p] = n0; S2[i][p + 1] = n1; y0 += n0 * PAIR(Rv, p); y1 += n1 * PAIR(Rv, p + 1); }
;                         y0 += y1; y[i] = red4(y0[0] + y0[1]); }
;     ...
;                     if (kq == 0) *(LAS f32x2*)(yb + t * 64 + half * 32 + rb * 2) = (f32x2){y[0], y[1]};
;                 }
	v_pk_fma_f32 v[160:161], v[84:85], v[32:33], 0 op_sel_hi:[1,1,0]
	v_pk_fma_f32 v[162:163], v[88:89], v[34:35], 0 op_sel_hi:[1,1,0]
	v_pk_fma_f32 v[164:165], v[100:101], v[32:33], 0 op_sel_hi:[1,1,0]
	v_pk_fma_f32 v[166:167], v[104:105], v[34:35], 0 op_sel_hi:[1,1,0]
	v_pk_fma_f32 v[160:161], v[86:87], v[36:37], v[160:161]
	v_pk_fma_f32 v[162:163], v[92:93], v[38:39], v[162:163]
	v_pk_fma_f32 v[164:165], v[106:107], v[36:37], v[164:165]
	v_pk_fma_f32 v[166:167], v[108:109], v[38:39], v[166:167]
	v_pk_fma_f32 v[160:161], v[90:91], v[40:41], v[160:161]
	v_pk_fma_f32 v[162:163], v[98:99], v[42:43], v[162:163]
	v_pk_fma_f32 v[164:165], v[110:111], v[40:41], v[164:165]
	v_pk_fma_f32 v[166:167], v[112:113], v[42:43], v[166:167]
	v_pk_fma_f32 v[160:161], v[94:95], v[44:45], v[160:161]
	v_pk_fma_f32 v[162:163], v[102:103], v[46:47], v[162:163]
	v_pk_fma_f32 v[164:165], v[114:115], v[44:45], v[164:165]
	v_pk_fma_f32 v[166:167], v[116:117], v[46:47], v[166:167]
	ds_read_b128 v[32:35], v171 offset:15616
	ds_read_b128 v[36:39], v171 offset:15632
	ds_read_b128 v[40:43], v171 offset:15648
	ds_read_b128 v[44:47], v171 offset:15664
	v_pk_add_f32 v[160:161], v[162:163], v[160:161]
	v_pk_add_f32 v[164:165], v[166:167], v[164:165]
	v_pk_add_f32 v[248:249], v[250:251], v[248:249]
	v_pk_add_f32 v[194:195], v[158:159], v[194:195]
	v_add_f32_e32 v168, v160, v161
	v_add_f32_e32 v169, v164, v165
	v_add_f32_e32 v224, v248, v249
	v_add_f32_e32 v225, v194, v195
	v_add_f32_dpp v168, v168, v168 quad_perm:[1,0,3,2] row_mask:0xf bank_mask:0xf bound_ctrl:1
	v_add_f32_dpp v169, v169, v169 quad_perm:[1,0,3,2] row_mask:0xf bank_mask:0xf bound_ctrl:1
	v_add_f32_dpp v224, v224, v224 quad_perm:[1,0,3,2] row_mask:0xf bank_mask:0xf bound_ctrl:1
	v_add_f32_dpp v225, v225, v225 quad_perm:[1,0,3,2] row_mask:0xf bank_mask:0xf bound_ctrl:1
	v_add_f32_dpp v190, v168, v168 quad_perm:[2,3,0,1] row_mask:0xf bank_mask:0xf bound_ctrl:1
	v_add_f32_dpp v192, v169, v169 quad_perm:[2,3,0,1] row_mask:0xf bank_mask:0xf bound_ctrl:1
	v_add_f32_dpp v224, v224, v224 quad_perm:[2,3,0,1] row_mask:0xf bank_mask:0xf bound_ctrl:1
	v_add_f32_dpp v225, v225, v225 quad_perm:[2,3,0,1] row_mask:0xf bank_mask:0xf bound_ctrl:1
	s_and_saveexec_b64 s[34:35], s[8:9]
	ds_write_b64 v75, v[224:225] offset:2816
	s_or_b64 exec, exec, s[34:35]
	s_waitcnt lgkmcnt(9)
	v_pk_mul_f32 v[216:217], v[142:143], v[190:191] op_sel_hi:[1,0]
	v_pk_mul_f32 v[218:219], v[144:145], v[190:191] op_sel_hi:[1,0]
	v_pk_mul_f32 v[220:221], v[142:143], v[192:193] op_sel_hi:[1,0]
	v_pk_mul_f32 v[222:223], v[144:145], v[192:193] op_sel_hi:[1,0]
	v_pk_fma_f32 v[216:217], v[84:85], v[48:49], v[216:217]
	v_pk_fma_f32 v[218:219], v[88:89], v[50:51], v[218:219]
	v_pk_fma_f32 v[220:221], v[100:101], v[48:49], v[220:221]
	v_pk_fma_f32 v[222:223], v[104:105], v[50:51], v[222:223]
	v_pk_fma_f32 v[84:85], v[172:173], v[188:189], v[216:217] op_sel_hi:[1,0,1]
	v_pk_fma_f32 v[88:89], v[174:175], v[188:189], v[218:219] op_sel_hi:[1,0,1]
	v_pk_fma_f32 v[100:101], v[172:173], v[188:189], v[220:221] op_sel:[0,1,0]
	v_pk_fma_f32 v[104:105], v[174:175], v[188:189], v[222:223] op_sel:[0,1,0]
	ds_read_b128 v[142:145], v171 offset:11520
	ds_read_b128 v[48:51], v171 offset:3328
	ds_read_b128 v[172:175], v171 offset:7424
	v_pk_mul_f32 v[216:217], v[146:147], v[190:191] op_sel_hi:[1,0]
	v_pk_mul_f32 v[218:219], v[148:149], v[190:191] op_sel_hi:[1,0]
	v_pk_mul_f32 v[220:221], v[146:147], v[192:193] op_sel_hi:[1,0]
	v_pk_mul_f32 v[222:223], v[148:149], v[192:193] op_sel_hi:[1,0]
	v_pk_fma_f32 v[216:217], v[86:87], v[52:53], v[216:217]
	v_pk_fma_f32 v[218:219], v[92:93], v[54:55], v[218:219]
	v_pk_fma_f32 v[220:221], v[106:107], v[52:53], v[220:221]
	v_pk_fma_f32 v[222:223], v[108:109], v[54:55], v[222:223]
	v_pk_fma_f32 v[86:87], v[176:177], v[188:189], v[216:217] op_sel_hi:[1,0,1]
	v_pk_fma_f32 v[92:93], v[178:179], v[188:189], v[218:219] op_sel_hi:[1,0,1]
	v_pk_fma_f32 v[106:107], v[176:177], v[188:189], v[220:221] op_sel:[0,1,0]
	v_pk_fma_f32 v[108:109], v[178:179], v[188:189], v[222:223] op_sel:[0,1,0]
	ds_read_b128 v[146:149], v171 offset:11536
	ds_read_b128 v[52:55], v171 offset:3344
	ds_read_b128 v[176:179], v171 offset:7440
	v_pk_mul_f32 v[216:217], v[150:151], v[190:191] op_sel_hi:[1,0]
	v_pk_mul_f32 v[218:219], v[152:153], v[190:191] op_sel_hi:[1,0]
	v_pk_mul_f32 v[220:221], v[150:151], v[192:193] op_sel_hi:[1,0]
	v_pk_mul_f32 v[222:223], v[152:153], v[192:193] op_sel_hi:[1,0]
	v_pk_fma_f32 v[216:217], v[90:91], v[56:57], v[216:217]
	v_pk_fma_f32 v[218:219], v[98:99], v[58:59], v[218:219]
	v_pk_fma_f32 v[220:221], v[110:111], v[56:57], v[220:221]
	v_pk_fma_f32 v[222:223], v[112:113], v[58:59], v[222:223]
	v_pk_fma_f32 v[90:91], v[180:181], v[188:189], v[216:217] op_sel_hi:[1,0,1]
	v_pk_fma_f32 v[98:99], v[182:183], v[188:189], v[218:219] op_sel_hi:[1,0,1]
	v_pk_fma_f32 v[110:111], v[180:181], v[188:189], v[220:221] op_sel:[0,1,0]
	v_pk_fma_f32 v[112:113], v[182:183], v[188:189], v[222:223] op_sel:[0,1,0]
	ds_read_b128 v[150:153], v171 offset:11552
	ds_read_b128 v[56:59], v171 offset:3360
	ds_read_b128 v[180:183], v171 offset:7456
	v_pk_mul_f32 v[216:217], v[154:155], v[190:191] op_sel_hi:[1,0]
	v_pk_mul_f32 v[218:219], v[156:157], v[190:191] op_sel_hi:[1,0]
	v_pk_mul_f32 v[220:221], v[154:155], v[192:193] op_sel_hi:[1,0]
	v_pk_mul_f32 v[222:223], v[156:157], v[192:193] op_sel_hi:[1,0]
	v_pk_fma_f32 v[216:217], v[94:95], v[60:61], v[216:217]
	v_pk_fma_f32 v[218:219], v[102:103], v[62:63], v[218:219]
	v_pk_fma_f32 v[220:221], v[114:115], v[60:61], v[220:221]
	v_pk_fma_f32 v[222:223], v[116:117], v[62:63], v[222:223]
	v_pk_fma_f32 v[94:95], v[184:185], v[188:189], v[216:217] op_sel_hi:[1,0,1]
	v_pk_fma_f32 v[102:103], v[186:187], v[188:189], v[218:219] op_sel_hi:[1,0,1]
	v_pk_fma_f32 v[114:115], v[184:185], v[188:189], v[220:221] op_sel:[0,1,0]
	v_pk_fma_f32 v[116:117], v[186:187], v[188:189], v[222:223] op_sel:[0,1,0]
	ds_read_b128 v[154:157], v171 offset:11568
	ds_read_b128 v[60:63], v171 offset:3376
	ds_read_b128 v[184:187], v171 offset:7472
	ds_read_b64 v[188:189], v96 offset:3328
	s_waitcnt lgkmcnt(15)
; #define LAS __attribute__((address_space(3)))
; __device__ __forceinline__ float red4(float x) { x = DPP_ADD(x, 0xB1); x = DPP_ADD(x, 0x4E); return x; }
; __device__ __forceinline__ void phase_scan(const ScanArgs A, LAS unsigned char* lds) {
;     ...
;                 for (int t = 0; t < 16; ++t) {
;                     const LAS float* q = in + t * 64 + kq * 16;
;                     f32x4 Wv[4], KDv[4], Bv[4], ANv[4], Rv[4];
; #pragma unroll
;                     for (int j = 0; j < 4; ++j) { Wv[j] = *(const LAS f32x4*)(q + 4 * j); KDv[j] = *(const LAS f32x4*)(q + 1024 + 4 * j); Bv[j] = *(const LAS f32x4*)(q + 2048 + 4 * j);
;                                                   ANv[j] = *(const LAS f32x4*)(q + 3072 + 4 * j); Rv[j] = *(const LAS f32x4*)(q + 4096 + 4 * j); }
;                     const f32x2 v2 = *(const LAS f32x2*)(in + 5120 + t * 64 + half * 32 + rb * 2);
;     ...
;                     float sa[2], y[2];
; #pragma unroll
;                     for (int i = 0; i < 2; ++i) { f32x2 a0 = {0.f, 0.f}, a1 = {0.f, 0.f};
; #pragma unroll
;                         for (int p = 0; p < 8; p += 2) { a0 += S2[i][p] * PAIR(ANv, p); a1 += S2[i][p + 1] * PAIR(ANv, p + 1); }
;                         a0 += a1; sa[i] = red4(a0[0] + a0[1]); }
; #pragma unroll
;                     for (int i = 0; i < 2; ++i) { f32x2 y0 = {0.f, 0.f}, y1 = {0.f, 0.f}; const f32x2 sai = {sa[i], sa[i]}, vi = {v2[i], v2[i]};
; #pragma unroll
;                         for (int p = 0; p < 8; p += 2) {
;                             const f32x2 n0 = S2[i][p] * PAIR(Wv, p) + sai * PAIR(Bv, p) + vi * PAIR(KDv, p);
;                             const f32x2 n1 = S2[i][p + 1] * PAIR(Wv, p + 1) + sai * PAIR(Bv, p + 1) + vi * PAIR(KDv, p + 1);
;                             S2[i][p] = n0; S2[i][p + 1] = n1; y0 += n0 * PAIR(Rv, p); y1 += n1 * PAIR(Rv, p + 1); }
;                         y0 += y1; y[i] = red4(y0[0] + y0[1]); }
;     ...
;                     if (kq == 0) *(LAS f32x2*)(yb + t * 64 + half * 32 + rb * 2) = (f32x2){y[0], y[1]};
;                 }
	v_pk_fma_f32 v[248:249], v[200:201], v[84:85], 0 op_sel_hi:[1,1,0]
	v_pk_fma_f32 v[250:251], v[202:203], v[88:89], 0 op_sel_hi:[1,1,0]
	v_pk_fma_f32 v[194:195], v[200:201], v[100:101], 0 op_sel_hi:[1,1,0]
	v_pk_fma_f32 v[158:159], v[202:203], v[104:105], 0 op_sel_hi:[1,1,0]
	v_pk_fma_f32 v[248:249], v[204:205], v[86:87], v[248:249]
	v_pk_fma_f32 v[250:251], v[206:207], v[92:93], v[250:251]
	v_pk_fma_f32 v[194:195], v[204:205], v[106:107], v[194:195]
	v_pk_fma_f32 v[158:159], v[206:207], v[108:109], v[158:159]
	v_pk_fma_f32 v[248:249], v[208:209], v[90:91], v[248:249]
	v_pk_fma_f32 v[250:251], v[210:211], v[98:99], v[250:251]
	v_pk_fma_f32 v[194:195], v[208:209], v[110:111], v[194:195]
	v_pk_fma_f32 v[158:159], v[210:211], v[112:113], v[158:159]
	v_pk_fma_f32 v[248:249], v[212:213], v[94:95], v[248:249]
	v_pk_fma_f32 v[250:251], v[214:215], v[102:103], v[250:251]
	v_pk_fma_f32 v[194:195], v[212:213], v[114:115], v[194:195]
	v_pk_fma_f32 v[158:159], v[214:215], v[116:117], v[158:159]
	ds_read_b128 v[200:203], v171 offset:19712
	ds_read_b128 v[204:207], v171 offset:19728
	ds_read_b128 v[208:211], v171 offset:19744
	ds_read_b128 v[212:215], v171 offset:19760
	s_waitcnt lgkmcnt(15)
	v_pk_fma_f32 v[160:161], v[84:85], v[32:33], 0 op_sel_hi:[1,1,0]
	v_pk_fma_f32 v[162:163], v[88:89], v[34:35], 0 op_sel_hi:[1,1,0]
	v_pk_fma_f32 v[164:165], v[100:101], v[32:33], 0 op_sel_hi:[1,1,0]
	v_pk_fma_f32 v[166:167], v[104:105], v[34:35], 0 op_sel_hi:[1,1,0]
	v_pk_fma_f32 v[160:161], v[86:87], v[36:37], v[160:161]
	v_pk_fma_f32 v[162:163], v[92:93], v[38:39], v[162:163]
	v_pk_fma_f32 v[164:165], v[106:107], v[36:37], v[164:165]
	v_pk_fma_f32 v[166:167], v[108:109], v[38:39], v[166:167]
	v_pk_fma_f32 v[160:161], v[90:91], v[40:41], v[160:161]
	v_pk_fma_f32 v[162:163], v[98:99], v[42:43], v[162:163]
	v_pk_fma_f32 v[164:165], v[110:111], v[40:41], v[164:165]
	v_pk_fma_f32 v[166:167], v[112:113], v[42:43], v[166:167]
	v_pk_fma_f32 v[160:161], v[94:95], v[44:45], v[160:161]
	v_pk_fma_f32 v[162:163], v[102:103], v[46:47], v[162:163]
	v_pk_fma_f32 v[164:165], v[114:115], v[44:45], v[164:165]
	v_pk_fma_f32 v[166:167], v[116:117], v[46:47], v[166:167]
	ds_read_b128 v[32:35], v171 offset:15872
	ds_read_b128 v[36:39], v171 offset:15888
	ds_read_b128 v[40:43], v171 offset:15904
	ds_read_b128 v[44:47], v171 offset:15920
	v_pk_add_f32 v[160:161], v[162:163], v[160:161]
	v_pk_add_f32 v[164:165], v[166:167], v[164:165]
	v_pk_add_f32 v[248:249], v[250:251], v[248:249]
	v_pk_add_f32 v[194:195], v[158:159], v[194:195]
	v_add_f32_e32 v168, v160, v161
	v_add_f32_e32 v169, v164, v165
	v_add_f32_e32 v224, v248, v249
	v_add_f32_e32 v225, v194, v195
	v_add_f32_dpp v168, v168, v168 quad_perm:[1,0,3,2] row_mask:0xf bank_mask:0xf bound_ctrl:1
	v_add_f32_dpp v169, v169, v169 quad_perm:[1,0,3,2] row_mask:0xf bank_mask:0xf bound_ctrl:1
	v_add_f32_dpp v224, v224, v224 quad_perm:[1,0,3,2] row_mask:0xf bank_mask:0xf bound_ctrl:1
	v_add_f32_dpp v225, v225, v225 quad_perm:[1,0,3,2] row_mask:0xf bank_mask:0xf bound_ctrl:1
	v_add_f32_dpp v190, v168, v168 quad_perm:[2,3,0,1] row_mask:0xf bank_mask:0xf bound_ctrl:1
	v_add_f32_dpp v192, v169, v169 quad_perm:[2,3,0,1] row_mask:0xf bank_mask:0xf bound_ctrl:1
	v_add_f32_dpp v224, v224, v224 quad_perm:[2,3,0,1] row_mask:0xf bank_mask:0xf bound_ctrl:1
	v_add_f32_dpp v225, v225, v225 quad_perm:[2,3,0,1] row_mask:0xf bank_mask:0xf bound_ctrl:1
	s_and_saveexec_b64 s[34:35], s[8:9]
	ds_write_b64 v75, v[224:225] offset:3072
	s_or_b64 exec, exec, s[34:35]
	s_waitcnt lgkmcnt(9)
	v_pk_mul_f32 v[216:217], v[142:143], v[190:191] op_sel_hi:[1,0]
	v_pk_mul_f32 v[218:219], v[144:145], v[190:191] op_sel_hi:[1,0]
	v_pk_mul_f32 v[220:221], v[142:143], v[192:193] op_sel_hi:[1,0]
	v_pk_mul_f32 v[222:223], v[144:145], v[192:193] op_sel_hi:[1,0]
	v_pk_fma_f32 v[216:217], v[84:85], v[48:49], v[216:217]
	v_pk_fma_f32 v[218:219], v[88:89], v[50:51], v[218:219]
	v_pk_fma_f32 v[220:221], v[100:101], v[48:49], v[220:221]
	v_pk_fma_f32 v[222:223], v[104:105], v[50:51], v[222:223]
	v_pk_fma_f32 v[84:85], v[172:173], v[188:189], v[216:217] op_sel_hi:[1,0,1]
	v_pk_fma_f32 v[88:89], v[174:175], v[188:189], v[218:219] op_sel_hi:[1,0,1]
	v_pk_fma_f32 v[100:101], v[172:173], v[188:189], v[220:221] op_sel:[0,1,0]
	v_pk_fma_f32 v[104:105], v[174:175], v[188:189], v[222:223] op_sel:[0,1,0]
	ds_read_b128 v[142:145], v171 offset:11776
	ds_read_b128 v[48:51], v171 offset:3584
	ds_read_b128 v[172:175], v171 offset:7680
	v_pk_mul_f32 v[216:217], v[146:147], v[190:191] op_sel_hi:[1,0]
	v_pk_mul_f32 v[218:219], v[148:149], v[190:191] op_sel_hi:[1,0]
	v_pk_mul_f32 v[220:221], v[146:147], v[192:193] op_sel_hi:[1,0]
	v_pk_mul_f32 v[222:223], v[148:149], v[192:193] op_sel_hi:[1,0]
	v_pk_fma_f32 v[216:217], v[86:87], v[52:53], v[216:217]
	v_pk_fma_f32 v[218:219], v[92:93], v[54:55], v[218:219]
	v_pk_fma_f32 v[220:221], v[106:107], v[52:53], v[220:221]
	v_pk_fma_f32 v[222:223], v[108:109], v[54:55], v[222:223]
	v_pk_fma_f32 v[86:87], v[176:177], v[188:189], v[216:217] op_sel_hi:[1,0,1]
	v_pk_fma_f32 v[92:93], v[178:179], v[188:189], v[218:219] op_sel_hi:[1,0,1]
	v_pk_fma_f32 v[106:107], v[176:177], v[188:189], v[220:221] op_sel:[0,1,0]
	v_pk_fma_f32 v[108:109], v[178:179], v[188:189], v[222:223] op_sel:[0,1,0]
	ds_read_b128 v[146:149], v171 offset:11792
	ds_read_b128 v[52:55], v171 offset:3600
	ds_read_b128 v[176:179], v171 offset:7696
	v_pk_mul_f32 v[216:217], v[150:151], v[190:191] op_sel_hi:[1,0]
	v_pk_mul_f32 v[218:219], v[152:153], v[190:191] op_sel_hi:[1,0]
	v_pk_mul_f32 v[220:221], v[150:151], v[192:193] op_sel_hi:[1,0]
	v_pk_mul_f32 v[222:223], v[152:153], v[192:193] op_sel_hi:[1,0]
; #define LAS __attribute__((address_space(3)))
; __device__ __forceinline__ float red4(float x) { x = DPP_ADD(x, 0xB1); x = DPP_ADD(x, 0x4E); return x; }
; __device__ __forceinline__ void phase_scan(const ScanArgs A, LAS unsigned char* lds) {
;     ...
;                 for (int t = 0; t < 16; ++t) {
;                     const LAS float* q = in + t * 64 + kq * 16;
;                     f32x4 Wv[4], KDv[4], Bv[4], ANv[4], Rv[4];
; #pragma unroll
;                     for (int j = 0; j < 4; ++j) { Wv[j] = *(const LAS f32x4*)(q + 4 * j); KDv[j] = *(const LAS f32x4*)(q + 1024 + 4 * j); Bv[j] = *(const LAS f32x4*)(q + 2048 + 4 * j);
;                                                   ANv[j] = *(const LAS f32x4*)(q + 3072 + 4 * j); Rv[j] = *(const LAS f32x4*)(q + 4096 + 4 * j); }
;                     const f32x2 v2 = *(const LAS f32x2*)(in + 5120 + t * 64 + half * 32 + rb * 2);
;     ...
;                     float sa[2], y[2];
; #pragma unroll
;                     for (int i = 0; i < 2; ++i) { f32x2 a0 = {0.f, 0.f}, a1 = {0.f, 0.f};
; #pragma unroll
;                         for (int p = 0; p < 8; p += 2) { a0 += S2[i][p] * PAIR(ANv, p); a1 += S2[i][p + 1] * PAIR(ANv, p + 1); }
;                         a0 += a1; sa[i] = red4(a0[0] + a0[1]); }
; #pragma unroll
;                     for (int i = 0; i < 2; ++i) { f32x2 y0 = {0.f, 0.f}, y1 = {0.f, 0.f}; const f32x2 sai = {sa[i], sa[i]}, vi = {v2[i], v2[i]};
; #pragma unroll
;                         for (int p = 0; p < 8; p += 2) {
;                             const f32x2 n0 = S2[i][p] * PAIR(Wv, p) + sai * PAIR(Bv, p) + vi * PAIR(KDv, p);
;                             const f32x2 n1 = S2[i][p + 1] * PAIR(Wv, p + 1) + sai * PAIR(Bv, p + 1) + vi * PAIR(KDv, p + 1);
;                             S2[i][p] = n0; S2[i][p + 1] = n1; y0 += n0 * PAIR(Rv, p); y1 += n1 * PAIR(Rv, p + 1); }
;                         y0 += y1; y[i] = red4(y0[0] + y0[1]); }
;     ...
;                     if (kq == 0) *(LAS f32x2*)(yb + t * 64 + half * 32 + rb * 2) = (f32x2){y[0], y[1]};
;                 }
	v_pk_fma_f32 v[216:217], v[90:91], v[56:57], v[216:217]
	v_pk_fma_f32 v[218:219], v[98:99], v[58:59], v[218:219]
	v_pk_fma_f32 v[220:221], v[110:111], v[56:57], v[220:221]
	v_pk_fma_f32 v[222:223], v[112:113], v[58:59], v[222:223]
	v_pk_fma_f32 v[90:91], v[180:181], v[188:189], v[216:217] op_sel_hi:[1,0,1]
	v_pk_fma_f32 v[98:99], v[182:183], v[188:189], v[218:219] op_sel_hi:[1,0,1]
	v_pk_fma_f32 v[110:111], v[180:181], v[188:189], v[220:221] op_sel:[0,1,0]
	v_pk_fma_f32 v[112:113], v[182:183], v[188:189], v[222:223] op_sel:[0,1,0]
	ds_read_b128 v[150:153], v171 offset:11808
	ds_read_b128 v[56:59], v171 offset:3616
	ds_read_b128 v[180:183], v171 offset:7712
	v_pk_mul_f32 v[216:217], v[154:155], v[190:191] op_sel_hi:[1,0]
	v_pk_mul_f32 v[218:219], v[156:157], v[190:191] op_sel_hi:[1,0]
	v_pk_mul_f32 v[220:221], v[154:155], v[192:193] op_sel_hi:[1,0]
	v_pk_mul_f32 v[222:223], v[156:157], v[192:193] op_sel_hi:[1,0]
	v_pk_fma_f32 v[216:217], v[94:95], v[60:61], v[216:217]
	v_pk_fma_f32 v[218:219], v[102:103], v[62:63], v[218:219]
	v_pk_fma_f32 v[220:221], v[114:115], v[60:61], v[220:221]
	v_pk_fma_f32 v[222:223], v[116:117], v[62:63], v[222:223]
	v_pk_fma_f32 v[94:95], v[184:185], v[188:189], v[216:217] op_sel_hi:[1,0,1]
	v_pk_fma_f32 v[102:103], v[186:187], v[188:189], v[218:219] op_sel_hi:[1,0,1]
	v_pk_fma_f32 v[114:115], v[184:185], v[188:189], v[220:221] op_sel:[0,1,0]
	v_pk_fma_f32 v[116:117], v[186:187], v[188:189], v[222:223] op_sel:[0,1,0]
	ds_read_b128 v[154:157], v171 offset:11824
	ds_read_b128 v[60:63], v171 offset:3632
	ds_read_b128 v[184:187], v171 offset:7728
	ds_read_b64 v[188:189], v96 offset:3584
	s_waitcnt lgkmcnt(15)
	v_pk_fma_f32 v[248:249], v[200:201], v[84:85], 0 op_sel_hi:[1,1,0]
	v_pk_fma_f32 v[250:251], v[202:203], v[88:89], 0 op_sel_hi:[1,1,0]
	v_pk_fma_f32 v[194:195], v[200:201], v[100:101], 0 op_sel_hi:[1,1,0]
	v_pk_fma_f32 v[158:159], v[202:203], v[104:105], 0 op_sel_hi:[1,1,0]
	v_pk_fma_f32 v[248:249], v[204:205], v[86:87], v[248:249]
	v_pk_fma_f32 v[250:251], v[206:207], v[92:93], v[250:251]
	v_pk_fma_f32 v[194:195], v[204:205], v[106:107], v[194:195]
	v_pk_fma_f32 v[158:159], v[206:207], v[108:109], v[158:159]
	v_pk_fma_f32 v[248:249], v[208:209], v[90:91], v[248:249]
	v_pk_fma_f32 v[250:251], v[210:211], v[98:99], v[250:251]
	v_pk_fma_f32 v[194:195], v[208:209], v[110:111], v[194:195]
	v_pk_fma_f32 v[158:159], v[210:211], v[112:113], v[158:159]
	v_pk_fma_f32 v[248:249], v[212:213], v[94:95], v[248:249]
	v_pk_fma_f32 v[250:251], v[214:215], v[102:103], v[250:251]
	v_pk_fma_f32 v[194:195], v[212:213], v[114:115], v[194:195]
	v_pk_fma_f32 v[158:159], v[214:215], v[116:117], v[158:159]
	ds_read_b128 v[200:203], v171 offset:19968
	ds_read_b128 v[204:207], v171 offset:19984
	ds_read_b128 v[208:211], v171 offset:20000
	ds_read_b128 v[212:215], v171 offset:20016
	s_waitcnt lgkmcnt(15)
	v_pk_fma_f32 v[160:161], v[84:85], v[32:33], 0 op_sel_hi:[1,1,0]
	v_pk_fma_f32 v[162:163], v[88:89], v[34:35], 0 op_sel_hi:[1,1,0]
	v_pk_fma_f32 v[164:165], v[100:101], v[32:33], 0 op_sel_hi:[1,1,0]
	v_pk_fma_f32 v[166:167], v[104:105], v[34:35], 0 op_sel_hi:[1,1,0]
	v_pk_fma_f32 v[160:161], v[86:87], v[36:37], v[160:161]
	v_pk_fma_f32 v[162:163], v[92:93], v[38:39], v[162:163]
	v_pk_fma_f32 v[164:165], v[106:107], v[36:37], v[164:165]
	v_pk_fma_f32 v[166:167], v[108:109], v[38:39], v[166:167]
	v_pk_fma_f32 v[160:161], v[90:91], v[40:41], v[160:161]
	v_pk_fma_f32 v[162:163], v[98:99], v[42:43], v[162:163]
	v_pk_fma_f32 v[164:165], v[110:111], v[40:41], v[164:165]
	v_pk_fma_f32 v[166:167], v[112:113], v[42:43], v[166:167]
	v_pk_fma_f32 v[160:161], v[94:95], v[44:45], v[160:161]
	v_pk_fma_f32 v[162:163], v[102:103], v[46:47], v[162:163]
	v_pk_fma_f32 v[164:165], v[114:115], v[44:45], v[164:165]
	v_pk_fma_f32 v[166:167], v[116:117], v[46:47], v[166:167]
	ds_read_b128 v[32:35], v171 offset:16128
	ds_read_b128 v[36:39], v171 offset:16144
	ds_read_b128 v[40:43], v171 offset:16160
	ds_read_b128 v[44:47], v171 offset:16176
	v_pk_add_f32 v[160:161], v[162:163], v[160:161]
	v_pk_add_f32 v[164:165], v[166:167], v[164:165]
	v_pk_add_f32 v[248:249], v[250:251], v[248:249]
	v_pk_add_f32 v[194:195], v[158:159], v[194:195]
	v_add_f32_e32 v168, v160, v161
	v_add_f32_e32 v169, v164, v165
	v_add_f32_e32 v224, v248, v249
	v_add_f32_e32 v225, v194, v195
	v_add_f32_dpp v168, v168, v168 quad_perm:[1,0,3,2] row_mask:0xf bank_mask:0xf bound_ctrl:1
	v_add_f32_dpp v169, v169, v169 quad_perm:[1,0,3,2] row_mask:0xf bank_mask:0xf bound_ctrl:1
	v_add_f32_dpp v224, v224, v224 quad_perm:[1,0,3,2] row_mask:0xf bank_mask:0xf bound_ctrl:1
	v_add_f32_dpp v225, v225, v225 quad_perm:[1,0,3,2] row_mask:0xf bank_mask:0xf bound_ctrl:1
	v_add_f32_dpp v190, v168, v168 quad_perm:[2,3,0,1] row_mask:0xf bank_mask:0xf bound_ctrl:1
	v_add_f32_dpp v192, v169, v169 quad_perm:[2,3,0,1] row_mask:0xf bank_mask:0xf bound_ctrl:1
	v_add_f32_dpp v224, v224, v224 quad_perm:[2,3,0,1] row_mask:0xf bank_mask:0xf bound_ctrl:1
	v_add_f32_dpp v225, v225, v225 quad_perm:[2,3,0,1] row_mask:0xf bank_mask:0xf bound_ctrl:1
	s_and_saveexec_b64 s[34:35], s[8:9]
	ds_write_b64 v75, v[224:225] offset:3328
	s_or_b64 exec, exec, s[34:35]
	s_waitcnt lgkmcnt(9)
; #define LAS __attribute__((address_space(3)))
; __device__ __forceinline__ float red4(float x) { x = DPP_ADD(x, 0xB1); x = DPP_ADD(x, 0x4E); return x; }
; __device__ __forceinline__ void phase_scan(const ScanArgs A, LAS unsigned char* lds) {
;     ...
;                 for (int t = 0; t < 16; ++t) {
;                     const LAS float* q = in + t * 64 + kq * 16;
;                     f32x4 Wv[4], KDv[4], Bv[4], ANv[4], Rv[4];
; #pragma unroll
;                     for (int j = 0; j < 4; ++j) { Wv[j] = *(const LAS f32x4*)(q + 4 * j); KDv[j] = *(const LAS f32x4*)(q + 1024 + 4 * j); Bv[j] = *(const LAS f32x4*)(q + 2048 + 4 * j);
;                                                   ANv[j] = *(const LAS f32x4*)(q + 3072 + 4 * j); Rv[j] = *(const LAS f32x4*)(q + 4096 + 4 * j); }
;                     const f32x2 v2 = *(const LAS f32x2*)(in + 5120 + t * 64 + half * 32 + rb * 2);
;     ...
;                     float sa[2], y[2];
; #pragma unroll
;                     for (int i = 0; i < 2; ++i) { f32x2 a0 = {0.f, 0.f}, a1 = {0.f, 0.f};
; #pragma unroll
;                         for (int p = 0; p < 8; p += 2) { a0 += S2[i][p] * PAIR(ANv, p); a1 += S2[i][p + 1] * PAIR(ANv, p + 1); }
;                         a0 += a1; sa[i] = red4(a0[0] + a0[1]); }
; #pragma unroll
;                     for (int i = 0; i < 2; ++i) { f32x2 y0 = {0.f, 0.f}, y1 = {0.f, 0.f}; const f32x2 sai = {sa[i], sa[i]}, vi = {v2[i], v2[i]};
; #pragma unroll
;                         for (int p = 0; p < 8; p += 2) {
;                             const f32x2 n0 = S2[i][p] * PAIR(Wv, p) + sai * PAIR(Bv, p) + vi * PAIR(KDv, p);
;                             const f32x2 n1 = S2[i][p + 1] * PAIR(Wv, p + 1) + sai * PAIR(Bv, p + 1) + vi * PAIR(KDv, p + 1);
;                             S2[i][p] = n0; S2[i][p + 1] = n1; y0 += n0 * PAIR(Rv, p); y1 += n1 * PAIR(Rv, p + 1); }
;                         y0 += y1; y[i] = red4(y0[0] + y0[1]); }
;     ...
;                     if (kq == 0) *(LAS f32x2*)(yb + t * 64 + half * 32 + rb * 2) = (f32x2){y[0], y[1]};
;                 }
	v_pk_mul_f32 v[216:217], v[142:143], v[190:191] op_sel_hi:[1,0]
	v_pk_mul_f32 v[218:219], v[144:145], v[190:191] op_sel_hi:[1,0]
	v_pk_mul_f32 v[220:221], v[142:143], v[192:193] op_sel_hi:[1,0]
	v_pk_mul_f32 v[222:223], v[144:145], v[192:193] op_sel_hi:[1,0]
	v_pk_fma_f32 v[216:217], v[84:85], v[48:49], v[216:217]
	v_pk_fma_f32 v[218:219], v[88:89], v[50:51], v[218:219]
	v_pk_fma_f32 v[220:221], v[100:101], v[48:49], v[220:221]
	v_pk_fma_f32 v[222:223], v[104:105], v[50:51], v[222:223]
	v_pk_fma_f32 v[84:85], v[172:173], v[188:189], v[216:217] op_sel_hi:[1,0,1]
	v_pk_fma_f32 v[88:89], v[174:175], v[188:189], v[218:219] op_sel_hi:[1,0,1]
	v_pk_fma_f32 v[100:101], v[172:173], v[188:189], v[220:221] op_sel:[0,1,0]
	v_pk_fma_f32 v[104:105], v[174:175], v[188:189], v[222:223] op_sel:[0,1,0]
	ds_read_b128 v[142:145], v171 offset:12032
	ds_read_b128 v[48:51], v171 offset:3840
	ds_read_b128 v[172:175], v171 offset:7936
	v_pk_mul_f32 v[216:217], v[146:147], v[190:191] op_sel_hi:[1,0]
	v_pk_mul_f32 v[218:219], v[148:149], v[190:191] op_sel_hi:[1,0]
	v_pk_mul_f32 v[220:221], v[146:147], v[192:193] op_sel_hi:[1,0]
	v_pk_mul_f32 v[222:223], v[148:149], v[192:193] op_sel_hi:[1,0]
	v_pk_fma_f32 v[216:217], v[86:87], v[52:53], v[216:217]
	v_pk_fma_f32 v[218:219], v[92:93], v[54:55], v[218:219]
	v_pk_fma_f32 v[220:221], v[106:107], v[52:53], v[220:221]
	v_pk_fma_f32 v[222:223], v[108:109], v[54:55], v[222:223]
	v_pk_fma_f32 v[86:87], v[176:177], v[188:189], v[216:217] op_sel_hi:[1,0,1]
	v_pk_fma_f32 v[92:93], v[178:179], v[188:189], v[218:219] op_sel_hi:[1,0,1]
	v_pk_fma_f32 v[106:107], v[176:177], v[188:189], v[220:221] op_sel:[0,1,0]
	v_pk_fma_f32 v[108:109], v[178:179], v[188:189], v[222:223] op_sel:[0,1,0]
	ds_read_b128 v[146:149], v171 offset:12048
	ds_read_b128 v[52:55], v171 offset:3856
	ds_read_b128 v[176:179], v171 offset:7952
	v_pk_mul_f32 v[216:217], v[150:151], v[190:191] op_sel_hi:[1,0]
	v_pk_mul_f32 v[218:219], v[152:153], v[190:191] op_sel_hi:[1,0]
	v_pk_mul_f32 v[220:221], v[150:151], v[192:193] op_sel_hi:[1,0]
	v_pk_mul_f32 v[222:223], v[152:153], v[192:193] op_sel_hi:[1,0]
	v_pk_fma_f32 v[216:217], v[90:91], v[56:57], v[216:217]
	v_pk_fma_f32 v[218:219], v[98:99], v[58:59], v[218:219]
	v_pk_fma_f32 v[220:221], v[110:111], v[56:57], v[220:221]
	v_pk_fma_f32 v[222:223], v[112:113], v[58:59], v[222:223]
	v_pk_fma_f32 v[90:91], v[180:181], v[188:189], v[216:217] op_sel_hi:[1,0,1]
	v_pk_fma_f32 v[98:99], v[182:183], v[188:189], v[218:219] op_sel_hi:[1,0,1]
	v_pk_fma_f32 v[110:111], v[180:181], v[188:189], v[220:221] op_sel:[0,1,0]
	v_pk_fma_f32 v[112:113], v[182:183], v[188:189], v[222:223] op_sel:[0,1,0]
	ds_read_b128 v[150:153], v171 offset:12064
	ds_read_b128 v[56:59], v171 offset:3872
	ds_read_b128 v[180:183], v171 offset:7968
	v_pk_mul_f32 v[216:217], v[154:155], v[190:191] op_sel_hi:[1,0]
	v_pk_mul_f32 v[218:219], v[156:157], v[190:191] op_sel_hi:[1,0]
	v_pk_mul_f32 v[220:221], v[154:155], v[192:193] op_sel_hi:[1,0]
	v_pk_mul_f32 v[222:223], v[156:157], v[192:193] op_sel_hi:[1,0]
	v_pk_fma_f32 v[216:217], v[94:95], v[60:61], v[216:217]
	v_pk_fma_f32 v[218:219], v[102:103], v[62:63], v[218:219]
	v_pk_fma_f32 v[220:221], v[114:115], v[60:61], v[220:221]
	v_pk_fma_f32 v[222:223], v[116:117], v[62:63], v[222:223]
	v_pk_fma_f32 v[94:95], v[184:185], v[188:189], v[216:217] op_sel_hi:[1,0,1]
	v_pk_fma_f32 v[102:103], v[186:187], v[188:189], v[218:219] op_sel_hi:[1,0,1]
	v_pk_fma_f32 v[114:115], v[184:185], v[188:189], v[220:221] op_sel:[0,1,0]
	v_pk_fma_f32 v[116:117], v[186:187], v[188:189], v[222:223] op_sel:[0,1,0]
	ds_read_b128 v[154:157], v171 offset:12080
	ds_read_b128 v[60:63], v171 offset:3888
	ds_read_b128 v[184:187], v171 offset:7984
	ds_read_b64 v[188:189], v96 offset:3840
	s_waitcnt lgkmcnt(15)
	v_pk_fma_f32 v[248:249], v[200:201], v[84:85], 0 op_sel_hi:[1,1,0]
	v_pk_fma_f32 v[250:251], v[202:203], v[88:89], 0 op_sel_hi:[1,1,0]
	v_pk_fma_f32 v[194:195], v[200:201], v[100:101], 0 op_sel_hi:[1,1,0]
	v_pk_fma_f32 v[158:159], v[202:203], v[104:105], 0 op_sel_hi:[1,1,0]
	v_pk_fma_f32 v[248:249], v[204:205], v[86:87], v[248:249]
	v_pk_fma_f32 v[250:251], v[206:207], v[92:93], v[250:251]
	v_pk_fma_f32 v[194:195], v[204:205], v[106:107], v[194:195]
	v_pk_fma_f32 v[158:159], v[206:207], v[108:109], v[158:159]
	v_pk_fma_f32 v[248:249], v[208:209], v[90:91], v[248:249]
	v_pk_fma_f32 v[250:251], v[210:211], v[98:99], v[250:251]
	v_pk_fma_f32 v[194:195], v[208:209], v[110:111], v[194:195]
	v_pk_fma_f32 v[158:159], v[210:211], v[112:113], v[158:159]
	v_pk_fma_f32 v[248:249], v[212:213], v[94:95], v[248:249]
	v_pk_fma_f32 v[250:251], v[214:215], v[102:103], v[250:251]
	v_pk_fma_f32 v[194:195], v[212:213], v[114:115], v[194:195]
	v_pk_fma_f32 v[158:159], v[214:215], v[116:117], v[158:159]
	ds_read_b128 v[200:203], v171 offset:20224
	ds_read_b128 v[204:207], v171 offset:20240
	ds_read_b128 v[208:211], v171 offset:20256
	ds_read_b128 v[212:215], v171 offset:20272
	s_waitcnt lgkmcnt(15)
; #define LAS __attribute__((address_space(3)))
; __device__ __forceinline__ float red4(float x) { x = DPP_ADD(x, 0xB1); x = DPP_ADD(x, 0x4E); return x; }
; __device__ __forceinline__ void phase_scan(const ScanArgs A, LAS unsigned char* lds) {
;     ...
;                 for (int t = 0; t < 16; ++t) {
;                     const LAS float* q = in + t * 64 + kq * 16;
;                     f32x4 Wv[4], KDv[4], Bv[4], ANv[4], Rv[4];
; #pragma unroll
;                     for (int j = 0; j < 4; ++j) { Wv[j] = *(const LAS f32x4*)(q + 4 * j); KDv[j] = *(const LAS f32x4*)(q + 1024 + 4 * j); Bv[j] = *(const LAS f32x4*)(q + 2048 + 4 * j);
;                                                   ANv[j] = *(const LAS f32x4*)(q + 3072 + 4 * j); Rv[j] = *(const LAS f32x4*)(q + 4096 + 4 * j); }
;                     const f32x2 v2 = *(const LAS f32x2*)(in + 5120 + t * 64 + half * 32 + rb * 2);
;     ...
;                     float sa[2], y[2];
; #pragma unroll
;                     for (int i = 0; i < 2; ++i) { f32x2 a0 = {0.f, 0.f}, a1 = {0.f, 0.f};
; #pragma unroll
;                         for (int p = 0; p < 8; p += 2) { a0 += S2[i][p] * PAIR(ANv, p); a1 += S2[i][p + 1] * PAIR(ANv, p + 1); }
;                         a0 += a1; sa[i] = red4(a0[0] + a0[1]); }
; #pragma unroll
;                     for (int i = 0; i < 2; ++i) { f32x2 y0 = {0.f, 0.f}, y1 = {0.f, 0.f}; const f32x2 sai = {sa[i], sa[i]}, vi = {v2[i], v2[i]};
; #pragma unroll
;                         for (int p = 0; p < 8; p += 2) {
;                             const f32x2 n0 = S2[i][p] * PAIR(Wv, p) + sai * PAIR(Bv, p) + vi * PAIR(KDv, p);
;                             const f32x2 n1 = S2[i][p + 1] * PAIR(Wv, p + 1) + sai * PAIR(Bv, p + 1) + vi * PAIR(KDv, p + 1);
;                             S2[i][p] = n0; S2[i][p + 1] = n1; y0 += n0 * PAIR(Rv, p); y1 += n1 * PAIR(Rv, p + 1); }
;                         y0 += y1; y[i] = red4(y0[0] + y0[1]); }
;     ...
;                     if (kq == 0) *(LAS f32x2*)(yb + t * 64 + half * 32 + rb * 2) = (f32x2){y[0], y[1]};
;                 }
	v_pk_fma_f32 v[160:161], v[84:85], v[32:33], 0 op_sel_hi:[1,1,0]
	v_pk_fma_f32 v[162:163], v[88:89], v[34:35], 0 op_sel_hi:[1,1,0]
	v_pk_fma_f32 v[164:165], v[100:101], v[32:33], 0 op_sel_hi:[1,1,0]
	v_pk_fma_f32 v[166:167], v[104:105], v[34:35], 0 op_sel_hi:[1,1,0]
	v_pk_fma_f32 v[160:161], v[86:87], v[36:37], v[160:161]
	v_pk_fma_f32 v[162:163], v[92:93], v[38:39], v[162:163]
	v_pk_fma_f32 v[164:165], v[106:107], v[36:37], v[164:165]
	v_pk_fma_f32 v[166:167], v[108:109], v[38:39], v[166:167]
	v_pk_fma_f32 v[160:161], v[90:91], v[40:41], v[160:161]
	v_pk_fma_f32 v[162:163], v[98:99], v[42:43], v[162:163]
	v_pk_fma_f32 v[164:165], v[110:111], v[40:41], v[164:165]
	v_pk_fma_f32 v[166:167], v[112:113], v[42:43], v[166:167]
	v_pk_fma_f32 v[160:161], v[94:95], v[44:45], v[160:161]
	v_pk_fma_f32 v[162:163], v[102:103], v[46:47], v[162:163]
	v_pk_fma_f32 v[164:165], v[114:115], v[44:45], v[164:165]
	v_pk_fma_f32 v[166:167], v[116:117], v[46:47], v[166:167]
	v_pk_add_f32 v[160:161], v[162:163], v[160:161]
	v_pk_add_f32 v[164:165], v[166:167], v[164:165]
	v_pk_add_f32 v[248:249], v[250:251], v[248:249]
	v_pk_add_f32 v[194:195], v[158:159], v[194:195]
	v_add_f32_e32 v168, v160, v161
	v_add_f32_e32 v169, v164, v165
	v_add_f32_e32 v224, v248, v249
	v_add_f32_e32 v225, v194, v195
	v_add_f32_dpp v168, v168, v168 quad_perm:[1,0,3,2] row_mask:0xf bank_mask:0xf bound_ctrl:1
	v_add_f32_dpp v169, v169, v169 quad_perm:[1,0,3,2] row_mask:0xf bank_mask:0xf bound_ctrl:1
	v_add_f32_dpp v224, v224, v224 quad_perm:[1,0,3,2] row_mask:0xf bank_mask:0xf bound_ctrl:1
	v_add_f32_dpp v225, v225, v225 quad_perm:[1,0,3,2] row_mask:0xf bank_mask:0xf bound_ctrl:1
	v_add_f32_dpp v190, v168, v168 quad_perm:[2,3,0,1] row_mask:0xf bank_mask:0xf bound_ctrl:1
	v_add_f32_dpp v192, v169, v169 quad_perm:[2,3,0,1] row_mask:0xf bank_mask:0xf bound_ctrl:1
	v_add_f32_dpp v224, v224, v224 quad_perm:[2,3,0,1] row_mask:0xf bank_mask:0xf bound_ctrl:1
	v_add_f32_dpp v225, v225, v225 quad_perm:[2,3,0,1] row_mask:0xf bank_mask:0xf bound_ctrl:1
	s_and_saveexec_b64 s[34:35], s[8:9]
	ds_write_b64 v75, v[224:225] offset:3584
	s_or_b64 exec, exec, s[34:35]
	s_waitcnt lgkmcnt(5)
; #define LAS __attribute__((address_space(3)))
; __device__ __forceinline__ float red4(float x) { x = DPP_ADD(x, 0xB1); x = DPP_ADD(x, 0x4E); return x; }
; __device__ __forceinline__ void phase_scan(const ScanArgs A, LAS unsigned char* lds) {
;     ...
;                 for (int t = 0; t < 16; ++t) {
;                     const LAS float* q = in + t * 64 + kq * 16;
;                     f32x4 Wv[4], KDv[4], Bv[4], ANv[4], Rv[4];
; #pragma unroll
;                     for (int j = 0; j < 4; ++j) { Wv[j] = *(const LAS f32x4*)(q + 4 * j); KDv[j] = *(const LAS f32x4*)(q + 1024 + 4 * j); Bv[j] = *(const LAS f32x4*)(q + 2048 + 4 * j);
;                                                   ANv[j] = *(const LAS f32x4*)(q + 3072 + 4 * j); Rv[j] = *(const LAS f32x4*)(q + 4096 + 4 * j); }
;                     const f32x2 v2 = *(const LAS f32x2*)(in + 5120 + t * 64 + half * 32 + rb * 2);
;     ...
;                     float sa[2], y[2];
; #pragma unroll
;                     for (int i = 0; i < 2; ++i) { f32x2 a0 = {0.f, 0.f}, a1 = {0.f, 0.f};
; #pragma unroll
;                         for (int p = 0; p < 8; p += 2) { a0 += S2[i][p] * PAIR(ANv, p); a1 += S2[i][p + 1] * PAIR(ANv, p + 1); }
;                         a0 += a1; sa[i] = red4(a0[0] + a0[1]); }
; #pragma unroll
;                     for (int i = 0; i < 2; ++i) { f32x2 y0 = {0.f, 0.f}, y1 = {0.f, 0.f}; const f32x2 sai = {sa[i], sa[i]}, vi = {v2[i], v2[i]};
; #pragma unroll
;                         for (int p = 0; p < 8; p += 2) {
;                             const f32x2 n0 = S2[i][p] * PAIR(Wv, p) + sai * PAIR(Bv, p) + vi * PAIR(KDv, p);
;                             const f32x2 n1 = S2[i][p + 1] * PAIR(Wv, p + 1) + sai * PAIR(Bv, p + 1) + vi * PAIR(KDv, p + 1);
;                             S2[i][p] = n0; S2[i][p + 1] = n1; y0 += n0 * PAIR(Rv, p); y1 += n1 * PAIR(Rv, p + 1); }
;                         y0 += y1; y[i] = red4(y0[0] + y0[1]); }
;     ...
;                     if (kq == 0) *(LAS f32x2*)(yb + t * 64 + half * 32 + rb * 2) = (f32x2){y[0], y[1]};
;                 }
	v_pk_mul_f32 v[216:217], v[142:143], v[190:191] op_sel_hi:[1,0]
	v_pk_mul_f32 v[218:219], v[144:145], v[190:191] op_sel_hi:[1,0]
	v_pk_mul_f32 v[220:221], v[142:143], v[192:193] op_sel_hi:[1,0]
	v_pk_mul_f32 v[222:223], v[144:145], v[192:193] op_sel_hi:[1,0]
	v_pk_fma_f32 v[216:217], v[84:85], v[48:49], v[216:217]
	v_pk_fma_f32 v[218:219], v[88:89], v[50:51], v[218:219]
	v_pk_fma_f32 v[220:221], v[100:101], v[48:49], v[220:221]
	v_pk_fma_f32 v[222:223], v[104:105], v[50:51], v[222:223]
	v_pk_fma_f32 v[84:85], v[172:173], v[188:189], v[216:217] op_sel_hi:[1,0,1]
	v_pk_fma_f32 v[88:89], v[174:175], v[188:189], v[218:219] op_sel_hi:[1,0,1]
	v_pk_fma_f32 v[100:101], v[172:173], v[188:189], v[220:221] op_sel:[0,1,0]
	v_pk_fma_f32 v[104:105], v[174:175], v[188:189], v[222:223] op_sel:[0,1,0]
	v_pk_mul_f32 v[216:217], v[146:147], v[190:191] op_sel_hi:[1,0]
	v_pk_mul_f32 v[218:219], v[148:149], v[190:191] op_sel_hi:[1,0]
	v_pk_mul_f32 v[220:221], v[146:147], v[192:193] op_sel_hi:[1,0]
	v_pk_mul_f32 v[222:223], v[148:149], v[192:193] op_sel_hi:[1,0]
	v_pk_fma_f32 v[216:217], v[86:87], v[52:53], v[216:217]
	v_pk_fma_f32 v[218:219], v[92:93], v[54:55], v[218:219]
	v_pk_fma_f32 v[220:221], v[106:107], v[52:53], v[220:221]
	v_pk_fma_f32 v[222:223], v[108:109], v[54:55], v[222:223]
	v_pk_fma_f32 v[86:87], v[176:177], v[188:189], v[216:217] op_sel_hi:[1,0,1]
	v_pk_fma_f32 v[92:93], v[178:179], v[188:189], v[218:219] op_sel_hi:[1,0,1]
	v_pk_fma_f32 v[106:107], v[176:177], v[188:189], v[220:221] op_sel:[0,1,0]
	v_pk_fma_f32 v[108:109], v[178:179], v[188:189], v[222:223] op_sel:[0,1,0]
	v_pk_mul_f32 v[216:217], v[150:151], v[190:191] op_sel_hi:[1,0]
	v_pk_mul_f32 v[218:219], v[152:153], v[190:191] op_sel_hi:[1,0]
	v_pk_mul_f32 v[220:221], v[150:151], v[192:193] op_sel_hi:[1,0]
	v_pk_mul_f32 v[222:223], v[152:153], v[192:193] op_sel_hi:[1,0]
	v_pk_fma_f32 v[216:217], v[90:91], v[56:57], v[216:217]
	v_pk_fma_f32 v[218:219], v[98:99], v[58:59], v[218:219]
	v_pk_fma_f32 v[220:221], v[110:111], v[56:57], v[220:221]
	v_pk_fma_f32 v[222:223], v[112:113], v[58:59], v[222:223]
	v_pk_fma_f32 v[90:91], v[180:181], v[188:189], v[216:217] op_sel_hi:[1,0,1]
	v_pk_fma_f32 v[98:99], v[182:183], v[188:189], v[218:219] op_sel_hi:[1,0,1]
	v_pk_fma_f32 v[110:111], v[180:181], v[188:189], v[220:221] op_sel:[0,1,0]
	v_pk_fma_f32 v[112:113], v[182:183], v[188:189], v[222:223] op_sel:[0,1,0]
	v_pk_mul_f32 v[216:217], v[154:155], v[190:191] op_sel_hi:[1,0]
	v_pk_mul_f32 v[218:219], v[156:157], v[190:191] op_sel_hi:[1,0]
	v_pk_mul_f32 v[220:221], v[154:155], v[192:193] op_sel_hi:[1,0]
	v_pk_mul_f32 v[222:223], v[156:157], v[192:193] op_sel_hi:[1,0]
	v_pk_fma_f32 v[216:217], v[94:95], v[60:61], v[216:217]
	v_pk_fma_f32 v[218:219], v[102:103], v[62:63], v[218:219]
	v_pk_fma_f32 v[220:221], v[114:115], v[60:61], v[220:221]
	v_pk_fma_f32 v[222:223], v[116:117], v[62:63], v[222:223]
	v_pk_fma_f32 v[94:95], v[184:185], v[188:189], v[216:217] op_sel_hi:[1,0,1]
	v_pk_fma_f32 v[102:103], v[186:187], v[188:189], v[218:219] op_sel_hi:[1,0,1]
	v_pk_fma_f32 v[114:115], v[184:185], v[188:189], v[220:221] op_sel:[0,1,0]
	v_pk_fma_f32 v[116:117], v[186:187], v[188:189], v[222:223] op_sel:[0,1,0]
	s_waitcnt lgkmcnt(1)
	v_pk_fma_f32 v[248:249], v[200:201], v[84:85], 0 op_sel_hi:[1,1,0]
	v_pk_fma_f32 v[250:251], v[202:203], v[88:89], 0 op_sel_hi:[1,1,0]
	v_pk_fma_f32 v[194:195], v[200:201], v[100:101], 0 op_sel_hi:[1,1,0]
	v_pk_fma_f32 v[158:159], v[202:203], v[104:105], 0 op_sel_hi:[1,1,0]
	v_pk_fma_f32 v[248:249], v[204:205], v[86:87], v[248:249]
	v_pk_fma_f32 v[250:251], v[206:207], v[92:93], v[250:251]
	v_pk_fma_f32 v[194:195], v[204:205], v[106:107], v[194:195]
	v_pk_fma_f32 v[158:159], v[206:207], v[108:109], v[158:159]
	v_pk_fma_f32 v[248:249], v[208:209], v[90:91], v[248:249]
	v_pk_fma_f32 v[250:251], v[210:211], v[98:99], v[250:251]
	v_pk_fma_f32 v[194:195], v[208:209], v[110:111], v[194:195]
	v_pk_fma_f32 v[158:159], v[210:211], v[112:113], v[158:159]
	v_pk_fma_f32 v[248:249], v[212:213], v[94:95], v[248:249]
	v_pk_fma_f32 v[250:251], v[214:215], v[102:103], v[250:251]
	v_pk_fma_f32 v[194:195], v[212:213], v[114:115], v[194:195]
	v_pk_fma_f32 v[158:159], v[214:215], v[116:117], v[158:159]
	v_pk_add_f32 v[248:249], v[250:251], v[248:249]
	v_pk_add_f32 v[194:195], v[158:159], v[194:195]
	v_add_f32_e32 v224, v248, v249
	v_add_f32_e32 v225, v194, v195
	s_nop 0
	v_add_f32_dpp v224, v224, v224 quad_perm:[1,0,3,2] row_mask:0xf bank_mask:0xf bound_ctrl:1
	v_add_f32_dpp v225, v225, v225 quad_perm:[1,0,3,2] row_mask:0xf bank_mask:0xf bound_ctrl:1
	s_nop 0
	v_add_f32_dpp v224, v224, v224 quad_perm:[2,3,0,1] row_mask:0xf bank_mask:0xf bound_ctrl:1
	v_add_f32_dpp v225, v225, v225 quad_perm:[2,3,0,1] row_mask:0xf bank_mask:0xf bound_ctrl:1
	s_and_saveexec_b64 s[34:35], s[8:9]
	ds_write_b64 v75, v[224:225] offset:3840
	s_or_b64 exec, exec, s[34:35]
	s_branch .LBB0_162

; __device__ __forceinline__ void finishSM(f32x16& p0, f32x16& p1, float alpha, float& l_reg, bf16x8& pa0, bf16x8& pa1, bf16x8& pa2, bf16x8& pa3) {
; #pragma unroll
;     for (int r = 0; r < 16; ++r) p1[r] = __builtin_amdgcn_exp2f(p1[r]);
;     float ps = 0;
; #pragma unroll
;     for (int r = 0; r < 16; ++r) ps += p0[r];
; #pragma unroll
;     for (int r = 0; r < 16; ++r) ps += p1[r];
;     { auto rr = __builtin_amdgcn_permlane32_swap(__float_as_uint(ps), __float_as_uint(ps), false, false);
;       ps = __uint_as_float(rr[0]) + __uint_as_float(rr[1]); }
;     l_reg = l_reg * alpha + ps;
;     ...
;     PK4(p0, 0, pa0); PK4(p0, 8, pa1); PK4(p1, 0, pa2); PK4(p1, 8, pa3);
;     ...
; }
; __device__ __forceinline__ void qkt(f32x16& p0, f32x16& p1, const char* Ks, const bf16x8* qr, int r32, int hi, int comp) {
;     p0 = f32x16{}; p1 = f32x16{};
; #pragma unroll
;     for (int d0 = 0; d0 < 4; ++d0) { const int cb = (comp * 64 + d0 * 16 + hi * 8) * 2;
;         const bf16x8 b0 = *reinterpret_cast<const bf16x8*>(Ks + KSWZ(r32, cb));
;         const bf16x8 b1 = *reinterpret_cast<const bf16x8*>(Ks + KSWZ(32 + r32, cb));
;         p0 = __builtin_amdgcn_mfma_f32_32x32x16_bf16(b0, qr[d0], p0, 0, 0, 0);
;         p1 = __builtin_amdgcn_mfma_f32_32x32x16_bf16(b1, qr[d0], p1, 0, 0, 0); }
; }
; __device__ __forceinline__ int v_st(int k, int c) { const int kk = (k & ~0xC) | ((k & 4) << 1) | ((k & 8) >> 1); return ((kk >> 3) * 4 + (c >> 5)) * 512 + ((kk & 7) * 32 + (c & 31)) * 2; }
; __device__ __forceinline__ int v_rd_base(int lane) { return ((lane & 3) << 3) | (((lane >> 2) & 3) << 6) | (((lane >> 4) & 1) << 5) | (((lane >> 5) & 1) << 8); }
; template <int OFF> __device__ __forceinline__ s16x4 tr_read(int vb) {
;     s16x4 r; asm volatile("ds_read_b64_tr_b16 %0, %1 offset:%2" : "=&v"(r) : "v"(vb), "i"(OFF) : "memory"); return r;
; }
; template <int D0> __device__ __forceinline__ void pv_one(f32x16& od, int vb, bf16x8 pa0, bf16x8 pa1, bf16x8 pa2, bf16x8 pa3) {
;     const s16x4 l0 = tr_read<v_rd_off(D0, 0, 0)>(vb), h0 = tr_read<v_rd_off(D0, 0, 1)>(vb), l1 = tr_read<v_rd_off(D0, 1, 0)>(vb), h1 = tr_read<v_rd_off(D0, 1, 1)>(vb);
;     const s16x4 l2 = tr_read<v_rd_off(D0, 2, 0)>(vb), h2 = tr_read<v_rd_off(D0, 2, 1)>(vb), l3 = tr_read<v_rd_off(D0, 3, 0)>(vb), h3 = tr_read<v_rd_off(D0, 3, 1)>(vb);
;     asm volatile("s_waitcnt lgkmcnt(0)" ::: "memory"); SBAR();
.LBB0_262:
	ds_read_b128 v[64:67], v170 offset:49152
	ds_read_b128 v[68:71], v170 offset:57344
	v_add_f32_e32 v177, 0, v212
	v_add_f32_e32 v177, v216, v177
	v_add_f32_e32 v177, v213, v177
	s_waitcnt lgkmcnt(1)
	v_mfma_f32_32x32x16_bf16 v[80:95], v[64:67], v[110:113], 0
	v_add_f32_e32 v177, v217, v177
	v_add_f32_e32 v177, v214, v177
	ds_read_b128 v[178:181], v171 offset:49152
	ds_read_b128 v[220:223], v171 offset:57344
	v_add_f32_e32 v177, v218, v177
	v_add_f32_e32 v177, v215, v177
	v_add_f32_e32 v177, v219, v177
	v_add_f32_e32 v177, v183, v177
	s_waitcnt lgkmcnt(2)
	v_mfma_f32_32x32x16_bf16 v[64:79], v[68:71], v[110:113], 0
	v_add_f32_e32 v177, v187, v177
	v_add_f32_e32 v177, v184, v177
	v_add_f32_e32 v177, v188, v177
	v_exp_f32_e32 v128, v128
	v_add_f32_e32 v177, v185, v177
	v_exp_f32_e32 v129, v129
	v_add_f32_e32 v177, v189, v177
	s_waitcnt lgkmcnt(1)
	v_mfma_f32_32x32x16_bf16 v[80:95], v[178:181], v[106:109], v[80:95]
	v_exp_f32_e32 v126, v126
	v_add_f32_e32 v177, v186, v177
	v_exp_f32_e32 v127, v127
	v_add_f32_e32 v177, v211, v177
	v_exp_f32_e32 v122, v122
	v_add_f32_e32 v177, v128, v177
	v_exp_f32_e32 v123, v123
	s_waitcnt lgkmcnt(0)
	v_mfma_f32_32x32x16_bf16 v[64:79], v[220:223], v[106:109], v[64:79]
	ds_read_b128 v[178:181], v173 offset:49152
	ds_read_b128 v[220:223], v173 offset:57344
	v_add_f32_e32 v177, v129, v177
	v_exp_f32_e32 v118, v118
	v_add_f32_e32 v177, v126, v177
	v_exp_f32_e32 v119, v119
	v_add_f32_e32 v177, v127, v177
	v_exp_f32_e32 v116, v116
	s_waitcnt lgkmcnt(1)
	v_mfma_f32_32x32x16_bf16 v[80:95], v[178:181], v[102:105], v[80:95]
	v_add_f32_e32 v177, v122, v177
	v_exp_f32_e32 v117, v117
	v_add_f32_e32 v177, v123, v177
	v_exp_f32_e32 v124, v124
	v_add_f32_e32 v177, v118, v177
	v_exp_f32_e32 v125, v125
	v_add_f32_e32 v177, v119, v177
	s_waitcnt lgkmcnt(0)
	v_mfma_f32_32x32x16_bf16 v[64:79], v[220:223], v[102:105], v[64:79]
	ds_read_b128 v[178:181], v172 offset:49152
	ds_read_b128 v[220:223], v172 offset:57344
	v_exp_f32_e32 v120, v120
	v_add_f32_e32 v177, v116, v177
	v_exp_f32_e32 v121, v121
	v_add_f32_e32 v177, v117, v177
	v_exp_f32_e32 v114, v114
	v_add_f32_e32 v177, v124, v177
	s_waitcnt lgkmcnt(1)
	v_mfma_f32_32x32x16_bf16 v[80:95], v[178:181], v[98:101], v[80:95]
	v_exp_f32_e32 v115, v115
	v_add_f32_e32 v177, v125, v177
	v_add_f32_e32 v177, v120, v177
	v_add_f32_e32 v177, v121, v177
	v_add_f32_e32 v177, v114, v177
	v_add_f32_e32 v177, v115, v177
	v_mov_b32_e32 v178, v177
	s_waitcnt lgkmcnt(0)
	v_mfma_f32_32x32x16_bf16 v[64:79], v[220:223], v[98:101], v[64:79]
	v_cvt_pk_bf16_f32 v212, v212, v216
	v_cvt_pk_bf16_f32 v213, v213, v217
	v_cvt_pk_bf16_f32 v214, v214, v218
	v_cvt_pk_bf16_f32 v215, v215, v219
	v_cvt_pk_bf16_f32 v180, v183, v187
	v_cvt_pk_bf16_f32 v181, v184, v188
	v_cvt_pk_bf16_f32 v182, v185, v189
	v_permlane32_swap_b32_e32 v177, v178
	v_cvt_pk_bf16_f32 v183, v186, v211
	v_permlane32_swap_b32_e32 v180, v182
	v_cvt_pk_bf16_f32 v184, v128, v129
	v_cvt_pk_bf16_f32 v185, v126, v127
	v_cvt_pk_bf16_f32 v186, v122, v123
	v_cvt_pk_bf16_f32 v187, v118, v119
	v_cvt_pk_bf16_f32 v216, v116, v117
	v_cvt_pk_bf16_f32 v217, v124, v125
	v_cvt_pk_bf16_f32 v218, v120, v121
	v_cvt_pk_bf16_f32 v219, v114, v115
	v_permlane32_swap_b32_e32 v212, v214
	v_permlane32_swap_b32_e32 v213, v215
	v_permlane32_swap_b32_e32 v181, v183
	v_permlane32_swap_b32_e32 v184, v186
	v_permlane32_swap_b32_e32 v185, v187
	v_permlane32_swap_b32_e32 v216, v218
	v_permlane32_swap_b32_e32 v217, v219
	v_add_u32_e32 v122, 0x10000, v176
	global_load_dwordx4 v[240:243], v176, s[58:59]
	global_load_dwordx4 v[244:247], v176, s[28:29]
	global_load_dwordx4 v[206:209], v122, s[58:59]
	s_nop 0
	global_load_dwordx4 v[248:251], v122, s[28:29]
	ds_read_b64_tr_b16 v[220:221], v160 offset:0
	ds_read_b64_tr_b16 v[222:223], v160 offset:0x800
	ds_read_b64_tr_b16 v[224:225], v160 offset:0x1000
	ds_read_b64_tr_b16 v[226:227], v160 offset:0x1800
	ds_read_b64_tr_b16 v[228:229], v160 offset:0x2000
	ds_read_b64_tr_b16 v[230:231], v160 offset:0x2800
	ds_read_b64_tr_b16 v[232:233], v160 offset:0x3000
	ds_read_b64_tr_b16 v[234:235], v160 offset:0x3800
	s_waitcnt lgkmcnt(0)
	s_nop 0
	v_mfma_f32_32x32x16_bf16 v[48:63], v[212:215], v[220:223], v[48:63]
	ds_read_b64_tr_b16 v[220:221], v160 offset:0x200
	ds_read_b64_tr_b16 v[222:223], v160 offset:0xa00
	v_max_f32_e32 v179, v81, v81
	v_max_f32_e32 v255, v80, v80
	v_max_f32_e32 v179, v255, v179
	v_max3_f32 v179, v179, v82, v83
	v_max3_f32 v179, v179, v84, v85
	v_mfma_f32_32x32x16_bf16 v[48:63], v[180:183], v[224:227], v[48:63]
	ds_read_b64_tr_b16 v[224:225], v160 offset:0x1200
	ds_read_b64_tr_b16 v[226:227], v160 offset:0x1a00
	v_max3_f32 v179, v179, v86, v87
	v_max3_f32 v179, v179, v88, v89
	v_max3_f32 v179, v179, v90, v91
	v_max3_f32 v179, v179, v92, v93
	v_max3_f32 v179, v179, v94, v95
	v_mfma_f32_32x32x16_bf16 v[48:63], v[184:187], v[228:231], v[48:63]
	ds_read_b64_tr_b16 v[228:229], v160 offset:0x2200
	ds_read_b64_tr_b16 v[230:231], v160 offset:0x2a00
	v_max3_f32 v179, v179, v64, v65
	v_max3_f32 v179, v179, v66, v67
	v_max3_f32 v179, v179, v68, v69
	v_max3_f32 v179, v179, v70, v71
	v_max3_f32 v179, v179, v72, v73
	v_mfma_f32_32x32x16_bf16 v[48:63], v[216:219], v[232:235], v[48:63]
	ds_read_b64_tr_b16 v[232:233], v160 offset:0x3200
	ds_read_b64_tr_b16 v[234:235], v160 offset:0x3a00
	v_max3_f32 v179, v179, v74, v75
	v_max3_f32 v179, v179, v76, v77
	v_max3_f32 v179, v179, v78, v79
	v_mov_b32_e32 v255, v179
	s_nop 1
	v_permlane32_swap_b32_e32 v179, v255
	s_waitcnt lgkmcnt(0)
; #define SBAR() __builtin_amdgcn_sched_barrier(0)
; #define SWAIT() asm volatile("s_waitcnt vmcnt(0)" ::: "memory")
; __device__ __forceinline__ void partialSM(f32x16& p0, f32x16& p1, float& m_reg, float& mn, float& alpha) {
;     constexpr float C = SCALE * 1.4426950408889634f;
;     float pmax = p0[0];
; #pragma unroll
;     for (int r = 1; r < 16; ++r) pmax = fmaxf(pmax, p0[r]);
; #pragma unroll
;     for (int r = 0; r < 16; ++r) pmax = fmaxf(pmax, p1[r]);
;     { auto rr = __builtin_amdgcn_permlane32_swap(__float_as_uint(pmax), __float_as_uint(pmax), false, false);
;       pmax = fmaxf(__uint_as_float(rr[0]), __uint_as_float(rr[1])); }
;     if (__builtin_expect(__all(pmax - m_reg <= THR / SCALE), 1)) { mn = m_reg; alpha = 1.f; }
;     else { mn = fmaxf(m_reg, pmax); alpha = __builtin_amdgcn_exp2f((m_reg - mn) * C); m_reg = mn; }
;     const float mnC = -mn * C;
; #pragma unroll
;     for (int r = 0; r < 16; ++r) p0[r] = fmaf(p0[r], C, mnC);
; #pragma unroll
;     for (int r = 0; r < 16; ++r) p1[r] = fmaf(p1[r], C, mnC);
; #pragma unroll
;     for (int r = 0; r < 16; ++r) p0[r] = __builtin_amdgcn_exp2f(p0[r]);
; }
; __device__ __forceinline__ void attn_unit(const bf16_t* Qb, const bf16_t* Kh, const bf16_t* Vh, bf16_t* Ob, float* scr, int seq, float lam, float onemli, const float* subg, char* lds) {
;     ...
;         f32x16 pA0, pA1, pB0, pB1; float mnA, mnB, alA, alB; bf16x8 pa0, pa1, pa2, pa3;
;         constexpr int SE = 0, SO = 0;
;         __syncthreads();
;         SLOAD(SE, 0); asm volatile("s_waitcnt vmcnt(0)" ::: "memory"); SWRITE(0, SE); __syncthreads();
;         qkt(pA0, pA1, K_lds, qr, r32, hi, comp); partialSM(pA0, pA1, m_reg, mnA, alA);
;         SLOAD(SO, KVBLK);
;         SWAIT(); SWRITE(1, SO); __syncthreads();
;         for (int j = 1; j + 1 < NT; j += 2) {
;             SBAR(); qkt(pB0, pB1, K_lds + SHM_K, qr, r32, hi, comp);
;             finishSM(pA0, pA1, alA, l_reg, pa0, pa1, pa2, pa3); SBAR();
;             SLOAD(SO, (j + 1) * KVBLK); SBAR();
;             pv_d0(o, vb0, pa0, pa1, pa2, pa3); partialSM(pB0, pB1, m_reg, mnB, alB);
;             __syncthreads(); SWAIT(); SWRITE(0, SE);
;             RESC(alB); __syncthreads();
	v_mfma_f32_32x32x16_bf16 v[32:47], v[212:215], v[220:223], v[32:47]
	ds_read_b64_tr_b16 v[220:221], v160 offset:0x400
	ds_read_b64_tr_b16 v[222:223], v160 offset:0xc00
	v_max_f32_e32 v255, v255, v255
	v_max_f32_e32 v179, v179, v179
	v_max_f32_e32 v179, v179, v255
	v_sub_f32_e32 v255, v179, v175
	v_cmp_ge_f32_e32 vcc, s65, v255
	v_mfma_f32_32x32x16_bf16 v[32:47], v[180:183], v[224:227], v[32:47]
	ds_read_b64_tr_b16 v[224:225], v160 offset:0x1400
	ds_read_b64_tr_b16 v[226:227], v160 offset:0x1c00
	v_max_f32_e32 v255, v175, v175
	v_max_f32_e32 v179, v255, v179
	v_sub_f32_e32 v255, v175, v179
	v_mul_f32_e32 v255, 0x3e38aa3b, v255
	v_exp_f32_e32 v255, v255
	v_mfma_f32_32x32x16_bf16 v[32:47], v[184:187], v[228:231], v[32:47]
	ds_read_b64_tr_b16 v[228:229], v160 offset:0x2400
	ds_read_b64_tr_b16 v[230:231], v160 offset:0x2c00
	s_cmp_eq_u64 vcc, exec
	s_cselect_b64 s[8:9], -1, 0
	v_cndmask_b32_e64 v255, v255, 1.0, s[8:9]
	v_cndmask_b32_e64 v175, v179, v175, s[8:9]
	v_mul_f32_e32 v179, 0xbe38aa3b, v175
	v_mfma_f32_32x32x16_bf16 v[32:47], v[216:219], v[232:235], v[32:47]
	ds_read_b64_tr_b16 v[232:233], v160 offset:0x3400
	ds_read_b64_tr_b16 v[234:235], v160 offset:0x3c00
	v_fmamk_f32 v80, v80, 0x3e38aa3b, v179
	v_fmamk_f32 v81, v81, 0x3e38aa3b, v179
	v_fmamk_f32 v82, v82, 0x3e38aa3b, v179
	v_fmamk_f32 v83, v83, 0x3e38aa3b, v179
	v_fmamk_f32 v84, v84, 0x3e38aa3b, v179
	s_waitcnt lgkmcnt(0)
	v_mfma_f32_32x32x16_bf16 v[16:31], v[212:215], v[220:223], v[16:31]
	ds_read_b64_tr_b16 v[220:221], v160 offset:0x600
	ds_read_b64_tr_b16 v[222:223], v160 offset:0xe00
	v_fmamk_f32 v85, v85, 0x3e38aa3b, v179
	v_fmamk_f32 v86, v86, 0x3e38aa3b, v179
	v_fmamk_f32 v87, v87, 0x3e38aa3b, v179
	v_fmamk_f32 v88, v88, 0x3e38aa3b, v179
	v_fmamk_f32 v89, v89, 0x3e38aa3b, v179
	v_mfma_f32_32x32x16_bf16 v[16:31], v[180:183], v[224:227], v[16:31]
	ds_read_b64_tr_b16 v[224:225], v160 offset:0x1600
	ds_read_b64_tr_b16 v[226:227], v160 offset:0x1e00
	v_fmamk_f32 v90, v90, 0x3e38aa3b, v179
	v_fmamk_f32 v91, v91, 0x3e38aa3b, v179
	v_fmamk_f32 v92, v92, 0x3e38aa3b, v179
	v_fmamk_f32 v93, v93, 0x3e38aa3b, v179
	v_fmamk_f32 v94, v94, 0x3e38aa3b, v179
	v_mfma_f32_32x32x16_bf16 v[16:31], v[184:187], v[228:231], v[16:31]
	ds_read_b64_tr_b16 v[228:229], v160 offset:0x2600
	ds_read_b64_tr_b16 v[230:231], v160 offset:0x2e00
	v_fmamk_f32 v95, v95, 0x3e38aa3b, v179
	v_exp_f32_e32 v127, v80
	v_exp_f32_e32 v129, v81
	v_mfma_f32_32x32x16_bf16 v[16:31], v[216:219], v[232:235], v[16:31]
	ds_read_b64_tr_b16 v[232:233], v160 offset:0x3600
	ds_read_b64_tr_b16 v[234:235], v160 offset:0x3e00
	v_exp_f32_e32 v125, v82
	v_exp_f32_e32 v128, v83
	v_exp_f32_e32 v123, v84
	s_waitcnt lgkmcnt(0)
	v_mfma_f32_32x32x16_bf16 v[0:15], v[212:215], v[220:223], v[0:15]
	s_barrier
	s_waitcnt vmcnt(0)
	s_waitcnt vmcnt(3)
	ds_write_b128 v163, v[240:243]
	s_waitcnt vmcnt(1)
	ds_write_b128 v164, v[206:209]
	ds_write_b128 v161, v[244:247] offset:32768
	s_waitcnt vmcnt(0)
	ds_write_b128 v162, v[248:251] offset:32768
	v_exp_f32_e32 v126, v85
	v_exp_f32_e32 v122, v86
	v_exp_f32_e32 v124, v87
	v_mfma_f32_32x32x16_bf16 v[0:15], v[180:183], v[224:227], v[0:15]
	v_exp_f32_e32 v119, v88
	v_exp_f32_e32 v121, v89
	v_exp_f32_e32 v117, v90
	v_mfma_f32_32x32x16_bf16 v[0:15], v[184:187], v[228:231], v[0:15]
	v_exp_f32_e32 v120, v91
	v_exp_f32_e32 v115, v92
	v_exp_f32_e32 v118, v93
	v_mfma_f32_32x32x16_bf16 v[0:15], v[216:219], v[232:235], v[0:15]
	v_exp_f32_e32 v114, v94
	v_exp_f32_e32 v116, v95
	v_mov_b32_e32 v180, v255
	v_cmp_gt_f32_e32 vcc, 1.0, v180
	s_cbranch_vccz .LBB0_266
	s_and_saveexec_b64 s[2:3], s[6:7]
	ds_write_b32 v157, v180 offset:128
	s_or_b64 exec, exec, s[2:3]
	s_waitcnt lgkmcnt(0)
	ds_read_b128 v[240:243], v158 offset:224
	ds_read_b128 v[244:247], v158 offset:192
	ds_read_b128 v[248:251], v158 offset:160
	ds_read_b128 v[206:209], v158 offset:128
	s_waitcnt lgkmcnt(3)
	v_pk_mul_f32 v[62:63], v[62:63], v[242:243]
	s_waitcnt lgkmcnt(2)
	v_pk_mul_f32 v[58:59], v[58:59], v[246:247]
	s_waitcnt lgkmcnt(1)
	v_pk_mul_f32 v[54:55], v[54:55], v[250:251]
	s_waitcnt lgkmcnt(0)
	v_pk_mul_f32 v[50:51], v[50:51], v[208:209]
	v_pk_mul_f32 v[60:61], v[60:61], v[240:241]
	v_pk_mul_f32 v[56:57], v[56:57], v[244:245]
	v_pk_mul_f32 v[52:53], v[52:53], v[248:249]
	v_pk_mul_f32 v[48:49], v[48:49], v[206:207]
	v_pk_mul_f32 v[46:47], v[46:47], v[242:243]
	v_pk_mul_f32 v[42:43], v[42:43], v[246:247]
	v_pk_mul_f32 v[38:39], v[38:39], v[250:251]
	v_pk_mul_f32 v[34:35], v[34:35], v[208:209]
	v_pk_mul_f32 v[44:45], v[44:45], v[240:241]
	v_pk_mul_f32 v[40:41], v[40:41], v[244:245]
	v_pk_mul_f32 v[36:37], v[36:37], v[248:249]
	v_pk_mul_f32 v[32:33], v[32:33], v[206:207]
	v_pk_mul_f32 v[30:31], v[30:31], v[242:243]
	v_pk_mul_f32 v[26:27], v[26:27], v[246:247]
	v_pk_mul_f32 v[22:23], v[22:23], v[250:251]
	v_pk_mul_f32 v[18:19], v[18:19], v[208:209]
	v_pk_mul_f32 v[28:29], v[28:29], v[240:241]
	v_pk_mul_f32 v[24:25], v[24:25], v[244:245]
	v_pk_mul_f32 v[20:21], v[20:21], v[248:249]
	v_pk_mul_f32 v[16:17], v[16:17], v[206:207]
	v_pk_mul_f32 v[14:15], v[14:15], v[242:243]
	v_pk_mul_f32 v[10:11], v[10:11], v[246:247]
	v_pk_mul_f32 v[6:7], v[6:7], v[250:251]
	v_pk_mul_f32 v[2:3], v[2:3], v[208:209]
	v_pk_mul_f32 v[12:13], v[12:13], v[240:241]
	v_pk_mul_f32 v[8:9], v[8:9], v[244:245]
	v_pk_mul_f32 v[4:5], v[4:5], v[248:249]
	v_pk_mul_f32 v[0:1], v[0:1], v[206:207]
; #define SBAR() __builtin_amdgcn_sched_barrier(0)
; __device__ __forceinline__ void partialSM(f32x16& p0, f32x16& p1, float& m_reg, float& mn, float& alpha) {
;     ...
;     for (int r = 0; r < 16; ++r) p0[r] = fmaf(p0[r], C, mnC);
; #pragma unroll
;     for (int r = 0; r < 16; ++r) p1[r] = fmaf(p1[r], C, mnC);
; #pragma unroll
;     for (int r = 0; r < 16; ++r) p0[r] = __builtin_amdgcn_exp2f(p0[r]);
; }
; __device__ __forceinline__ void finishSM(f32x16& p0, f32x16& p1, float alpha, float& l_reg, bf16x8& pa0, bf16x8& pa1, bf16x8& pa2, bf16x8& pa3) {
; #pragma unroll
;     for (int r = 0; r < 16; ++r) p1[r] = __builtin_amdgcn_exp2f(p1[r]);
;     float ps = 0;
; #pragma unroll
;     for (int r = 0; r < 16; ++r) ps += p0[r];
; #pragma unroll
;     for (int r = 0; r < 16; ++r) ps += p1[r];
;     { auto rr = __builtin_amdgcn_permlane32_swap(__float_as_uint(ps), __float_as_uint(ps), false, false);
;       ps = __uint_as_float(rr[0]) + __uint_as_float(rr[1]); }
;     l_reg = l_reg * alpha + ps;
;     ...
;     PK4(p0, 0, pa0); PK4(p0, 8, pa1); PK4(p1, 0, pa2); PK4(p1, 8, pa3);
;     ...
; }
; __device__ __forceinline__ void qkt(f32x16& p0, f32x16& p1, const char* Ks, const bf16x8* qr, int r32, int hi, int comp) {
;     p0 = f32x16{}; p1 = f32x16{};
; #pragma unroll
;     for (int d0 = 0; d0 < 4; ++d0) { const int cb = (comp * 64 + d0 * 16 + hi * 8) * 2;
;         const bf16x8 b0 = *reinterpret_cast<const bf16x8*>(Ks + KSWZ(r32, cb));
;         const bf16x8 b1 = *reinterpret_cast<const bf16x8*>(Ks + KSWZ(32 + r32, cb));
;         p0 = __builtin_amdgcn_mfma_f32_32x32x16_bf16(b0, qr[d0], p0, 0, 0, 0);
;         p1 = __builtin_amdgcn_mfma_f32_32x32x16_bf16(b1, qr[d0], p1, 0, 0, 0); }
; }
; __device__ __forceinline__ void attn_unit(const bf16_t* Qb, const bf16_t* Kh, const bf16_t* Vh, bf16_t* Ob, float* scr, int seq, float lam, float onemli, const float* subg, char* lds) {
;     ...
;             RESC(alB); __syncthreads();
;             SBAR(); qkt(pA0, pA1, K_lds, qr, r32, hi, comp);
;             finishSM(pB0, pB1, alB, l_reg, pa0, pa1, pa2, pa3); SBAR();
;             SLOAD(SE, (j + 2) * KVBLK); SBAR();
;             pv_d0(o, vb0 + (int)SHM_V, pa0, pa1, pa2, pa3); partialSM(pA0, pA1, m_reg, mnA, alA);
.LBB0_266:
	v_fmamk_f32 v189, v64, 0x3e38aa3b, v179
	v_fmamk_f32 v211, v65, 0x3e38aa3b, v179
	v_fmamk_f32 v212, v66, 0x3e38aa3b, v179
	v_fmamk_f32 v213, v67, 0x3e38aa3b, v179
	v_fmamk_f32 v214, v68, 0x3e38aa3b, v179
	v_fmamk_f32 v182, v69, 0x3e38aa3b, v179
	v_fmamk_f32 v183, v70, 0x3e38aa3b, v179
	v_fmamk_f32 v184, v71, 0x3e38aa3b, v179
	v_fmamk_f32 v185, v72, 0x3e38aa3b, v179
	v_fmamk_f32 v186, v73, 0x3e38aa3b, v179
	v_fmamk_f32 v187, v74, 0x3e38aa3b, v179
	v_fmamk_f32 v188, v75, 0x3e38aa3b, v179
	v_fmamk_f32 v181, v76, 0x3e38aa3b, v179
	v_fmamk_f32 v215, v77, 0x3e38aa3b, v179
	v_fmamk_f32 v216, v78, 0x3e38aa3b, v179
	v_fmac_f32_e32 v179, 0x3e38aa3b, v79
	s_waitcnt lgkmcnt(0)
	s_barrier
	ds_read_b128 v[64:67], v170 offset:32768
	ds_read_b128 v[68:71], v170 offset:40960
	v_exp_f32_e32 v203, v181
	v_add_f32_e32 v181, 0, v127
	v_add_f32_e32 v181, v129, v181
	s_waitcnt lgkmcnt(1)
	v_mfma_f32_32x32x16_bf16 v[80:95], v[64:67], v[110:113], 0
	v_add_f32_e32 v181, v125, v181
	v_add_f32_e32 v181, v128, v181
	v_add_f32_e32 v181, v123, v181
	ds_read_b128 v[218:221], v171 offset:32768
	ds_read_b128 v[222:225], v171 offset:40960
	v_add_f32_e32 v181, v126, v181
	v_add_f32_e32 v181, v122, v181
	v_add_f32_e32 v181, v124, v181
	s_waitcnt lgkmcnt(2)
	v_mfma_f32_32x32x16_bf16 v[64:79], v[68:71], v[110:113], 0
	v_add_f32_e32 v181, v119, v181
	v_add_f32_e32 v181, v121, v181
	v_add_f32_e32 v181, v117, v181
	v_add_f32_e32 v181, v120, v181
	v_exp_f32_e32 v189, v189
	v_add_f32_e32 v181, v115, v181
	v_exp_f32_e32 v190, v211
	s_waitcnt lgkmcnt(1)
	v_mfma_f32_32x32x16_bf16 v[80:95], v[218:221], v[106:109], v[80:95]
	v_add_f32_e32 v181, v118, v181
	v_exp_f32_e32 v191, v212
	v_add_f32_e32 v181, v114, v181
	v_exp_f32_e32 v192, v213
	v_add_f32_e32 v181, v116, v181
	v_exp_f32_e32 v193, v214
	v_add_f32_e32 v181, v189, v181
	s_waitcnt lgkmcnt(0)
	v_mfma_f32_32x32x16_bf16 v[64:79], v[222:225], v[106:109], v[64:79]
	ds_read_b128 v[218:221], v173 offset:32768
	ds_read_b128 v[222:225], v173 offset:40960
	v_exp_f32_e32 v194, v182
	v_add_f32_e32 v181, v190, v181
	v_exp_f32_e32 v183, v183
	v_add_f32_e32 v181, v191, v181
	v_exp_f32_e32 v195, v184
	v_add_f32_e32 v181, v192, v181
	s_waitcnt lgkmcnt(1)
	v_mfma_f32_32x32x16_bf16 v[80:95], v[218:221], v[102:105], v[80:95]
	v_exp_f32_e32 v200, v185
	v_add_f32_e32 v181, v193, v181
	v_exp_f32_e32 v201, v186
	v_add_f32_e32 v181, v194, v181
	v_exp_f32_e32 v202, v187
	v_add_f32_e32 v181, v183, v181
	v_exp_f32_e32 v188, v188
	s_waitcnt lgkmcnt(0)
	v_mfma_f32_32x32x16_bf16 v[64:79], v[222:225], v[102:105], v[64:79]
	ds_read_b128 v[218:221], v172 offset:32768
	ds_read_b128 v[222:225], v172 offset:40960
	v_add_f32_e32 v181, v195, v181
	v_add_f32_e32 v181, v200, v181
	v_exp_f32_e32 v204, v215
	v_add_f32_e32 v181, v201, v181
	v_exp_f32_e32 v205, v216
	v_add_f32_e32 v181, v202, v181
	s_waitcnt lgkmcnt(1)
	v_mfma_f32_32x32x16_bf16 v[80:95], v[218:221], v[98:101], v[80:95]
	v_exp_f32_e32 v179, v179
	v_add_f32_e32 v181, v188, v181
	v_add_f32_e32 v181, v203, v181
	v_add_f32_e32 v181, v204, v181
	v_add_f32_e32 v181, v205, v181
	v_add_f32_e32 v181, v179, v181
	v_mov_b32_e32 v182, v181
	s_waitcnt lgkmcnt(0)
	v_mfma_f32_32x32x16_bf16 v[64:79], v[222:225], v[98:101], v[64:79]
	v_permlane32_swap_b32_e32 v181, v182
	v_cvt_pk_bf16_f32 v184, v127, v129
	v_cvt_pk_bf16_f32 v185, v125, v128
	v_cvt_pk_bf16_f32 v186, v123, v126
	v_cvt_pk_bf16_f32 v187, v122, v124
	v_cvt_pk_bf16_f32 v212, v119, v121
	v_cvt_pk_bf16_f32 v213, v117, v120
	v_cvt_pk_bf16_f32 v214, v115, v118
	v_cvt_pk_bf16_f32 v215, v114, v116
	v_cvt_pk_bf16_f32 v216, v189, v190
	v_cvt_pk_bf16_f32 v217, v191, v192
	v_cvt_pk_bf16_f32 v218, v193, v194
	v_cvt_pk_bf16_f32 v219, v183, v195
	v_cvt_pk_bf16_f32 v220, v200, v201
	v_cvt_pk_bf16_f32 v221, v202, v188
	v_cvt_pk_bf16_f32 v222, v203, v204
	v_cvt_pk_bf16_f32 v223, v205, v179
	s_nop 0
	v_permlane32_swap_b32_e32 v184, v186
	v_permlane32_swap_b32_e32 v185, v187
	v_permlane32_swap_b32_e32 v212, v214
	v_permlane32_swap_b32_e32 v213, v215
	v_permlane32_swap_b32_e32 v216, v218
	v_permlane32_swap_b32_e32 v217, v219
	v_permlane32_swap_b32_e32 v220, v222
	v_permlane32_swap_b32_e32 v221, v223
	v_add_u32_e32 v118, 0x20000, v176
	v_add_u32_e32 v122, 0x30000, v176
	global_load_dwordx4 v[114:117], v118, s[58:59]
	s_nop 0
	global_load_dwordx4 v[118:121], v118, s[28:29]
	s_nop 0
	global_load_dwordx4 v[126:129], v122, s[58:59]
	s_nop 0
	global_load_dwordx4 v[122:125], v122, s[28:29]
	ds_read_b64_tr_b16 v[224:225], v159 offset:0
	ds_read_b64_tr_b16 v[226:227], v159 offset:0x800
	ds_read_b64_tr_b16 v[228:229], v159 offset:0x1000
	ds_read_b64_tr_b16 v[230:231], v159 offset:0x1800
	ds_read_b64_tr_b16 v[232:233], v159 offset:0x2000
	ds_read_b64_tr_b16 v[234:235], v159 offset:0x2800
	ds_read_b64_tr_b16 v[236:237], v159 offset:0x3000
	ds_read_b64_tr_b16 v[238:239], v159 offset:0x3800
	s_waitcnt lgkmcnt(0)
	s_nop 0
	v_mfma_f32_32x32x16_bf16 v[48:63], v[184:187], v[224:227], v[48:63]
	ds_read_b64_tr_b16 v[224:225], v159 offset:0x200
	ds_read_b64_tr_b16 v[226:227], v159 offset:0xa00
	v_mfma_f32_32x32x16_bf16 v[48:63], v[212:215], v[228:231], v[48:63]
	ds_read_b64_tr_b16 v[228:229], v159 offset:0x1200
	ds_read_b64_tr_b16 v[230:231], v159 offset:0x1a00
	v_mfma_f32_32x32x16_bf16 v[48:63], v[216:219], v[232:235], v[48:63]
	ds_read_b64_tr_b16 v[232:233], v159 offset:0x2200
	ds_read_b64_tr_b16 v[234:235], v159 offset:0x2a00
	v_mfma_f32_32x32x16_bf16 v[48:63], v[220:223], v[236:239], v[48:63]
	ds_read_b64_tr_b16 v[236:237], v159 offset:0x3200
	ds_read_b64_tr_b16 v[238:239], v159 offset:0x3a00
	s_waitcnt lgkmcnt(0)
; __device__ __forceinline__ void partialSM(f32x16& p0, f32x16& p1, float& m_reg, float& mn, float& alpha) {
;     constexpr float C = SCALE * 1.4426950408889634f;
;     float pmax = p0[0];
; #pragma unroll
;     for (int r = 1; r < 16; ++r) pmax = fmaxf(pmax, p0[r]);
; #pragma unroll
;     for (int r = 0; r < 16; ++r) pmax = fmaxf(pmax, p1[r]);
;     { auto rr = __builtin_amdgcn_permlane32_swap(__float_as_uint(pmax), __float_as_uint(pmax), false, false);
;       pmax = fmaxf(__uint_as_float(rr[0]), __uint_as_float(rr[1])); }
;     if (__builtin_expect(__all(pmax - m_reg <= THR / SCALE), 1)) { mn = m_reg; alpha = 1.f; }
;     else { mn = fmaxf(m_reg, pmax); alpha = __builtin_amdgcn_exp2f((m_reg - mn) * C); m_reg = mn; }
;     const float mnC = -mn * C;
; #pragma unroll
;     for (int r = 0; r < 16; ++r) p0[r] = fmaf(p0[r], C, mnC);
; #pragma unroll
;     for (int r = 0; r < 16; ++r) p1[r] = fmaf(p1[r], C, mnC);
; #pragma unroll
;     for (int r = 0; r < 16; ++r) p0[r] = __builtin_amdgcn_exp2f(p0[r]);
; }
; __device__ __forceinline__ void attn_unit(const bf16_t* Qb, const bf16_t* Kh, const bf16_t* Vh, bf16_t* Ob, float* scr, int seq, float lam, float onemli, const float* subg, char* lds) {
;     ...
;         f32x16 pA0, pA1, pB0, pB1; float mnA, mnB, alA, alB; bf16x8 pa0, pa1, pa2, pa3;
;         constexpr int SE = 0, SO = 0;
;         __syncthreads();
;         SLOAD(SE, 0); asm volatile("s_waitcnt vmcnt(0)" ::: "memory"); SWRITE(0, SE); __syncthreads();
;         qkt(pA0, pA1, K_lds, qr, r32, hi, comp); partialSM(pA0, pA1, m_reg, mnA, alA);
;         SLOAD(SO, KVBLK);
;         SWAIT(); SWRITE(1, SO); __syncthreads();
;         for (int j = 1; j + 1 < NT; j += 2) {
;             SBAR(); qkt(pB0, pB1, K_lds + SHM_K, qr, r32, hi, comp);
;             finishSM(pA0, pA1, alA, l_reg, pa0, pa1, pa2, pa3); SBAR();
;             SLOAD(SO, (j + 1) * KVBLK); SBAR();
;             pv_d0(o, vb0, pa0, pa1, pa2, pa3); partialSM(pB0, pB1, m_reg, mnB, alB);
;             __syncthreads(); SWAIT(); SWRITE(0, SE);
;             RESC(alB); __syncthreads();
;             SBAR(); qkt(pA0, pA1, K_lds, qr, r32, hi, comp);
;             finishSM(pB0, pB1, alB, l_reg, pa0, pa1, pa2, pa3); SBAR();
;             SLOAD(SE, (j + 2) * KVBLK); SBAR();
;             pv_d0(o, vb0 + (int)SHM_V, pa0, pa1, pa2, pa3); partialSM(pA0, pA1, m_reg, mnA, alA);
	v_mfma_f32_32x32x16_bf16 v[32:47], v[184:187], v[224:227], v[32:47]
	ds_read_b64_tr_b16 v[224:225], v159 offset:0x400
	ds_read_b64_tr_b16 v[226:227], v159 offset:0xc00
	v_mfma_f32_32x32x16_bf16 v[32:47], v[212:215], v[228:231], v[32:47]
	ds_read_b64_tr_b16 v[228:229], v159 offset:0x1400
	ds_read_b64_tr_b16 v[230:231], v159 offset:0x1c00
	v_mfma_f32_32x32x16_bf16 v[32:47], v[216:219], v[232:235], v[32:47]
	ds_read_b64_tr_b16 v[232:233], v159 offset:0x2400
	ds_read_b64_tr_b16 v[234:235], v159 offset:0x2c00
	v_mfma_f32_32x32x16_bf16 v[32:47], v[220:223], v[236:239], v[32:47]
	ds_read_b64_tr_b16 v[236:237], v159 offset:0x3400
	ds_read_b64_tr_b16 v[238:239], v159 offset:0x3c00
	s_waitcnt lgkmcnt(0)
	v_mfma_f32_32x32x16_bf16 v[16:31], v[184:187], v[224:227], v[16:31]
	ds_read_b64_tr_b16 v[224:225], v159 offset:0x600
	ds_read_b64_tr_b16 v[226:227], v159 offset:0xe00
	v_mfma_f32_32x32x16_bf16 v[16:31], v[212:215], v[228:231], v[16:31]
	ds_read_b64_tr_b16 v[228:229], v159 offset:0x1600
	ds_read_b64_tr_b16 v[230:231], v159 offset:0x1e00
	v_mfma_f32_32x32x16_bf16 v[16:31], v[216:219], v[232:235], v[16:31]
	ds_read_b64_tr_b16 v[232:233], v159 offset:0x2600
	ds_read_b64_tr_b16 v[234:235], v159 offset:0x2e00
	v_mfma_f32_32x32x16_bf16 v[16:31], v[220:223], v[236:239], v[16:31]
	ds_read_b64_tr_b16 v[236:237], v159 offset:0x3600
	ds_read_b64_tr_b16 v[238:239], v159 offset:0x3e00
	s_waitcnt lgkmcnt(0)
	v_mfma_f32_32x32x16_bf16 v[0:15], v[184:187], v[224:227], v[0:15]
	v_max_f32_e32 v179, v81, v81
	v_max_f32_e32 v183, v80, v80
	v_max_f32_e32 v179, v183, v179
	v_max3_f32 v179, v179, v82, v83
	v_max3_f32 v179, v179, v84, v85
	v_max3_f32 v179, v179, v86, v87
	v_max3_f32 v179, v179, v88, v89
	v_max3_f32 v179, v179, v90, v91
	v_max3_f32 v179, v179, v92, v93
	v_mfma_f32_32x32x16_bf16 v[0:15], v[212:215], v[228:231], v[0:15]
	v_max3_f32 v179, v179, v94, v95
	v_max3_f32 v179, v179, v64, v65
	v_max3_f32 v179, v179, v66, v67
	v_max3_f32 v179, v179, v68, v69
	v_max3_f32 v179, v179, v70, v71
	v_max3_f32 v179, v179, v72, v73
	v_max3_f32 v179, v179, v74, v75
	v_max3_f32 v179, v179, v76, v77
	v_mfma_f32_32x32x16_bf16 v[0:15], v[216:219], v[232:235], v[0:15]
	v_max3_f32 v179, v179, v78, v79
	v_mov_b32_e32 v183, v179
	s_nop 1
	v_permlane32_swap_b32_e32 v179, v183
	v_max_f32_e32 v183, v183, v183
	v_max_f32_e32 v179, v179, v179
	v_max_f32_e32 v179, v179, v183
	v_sub_f32_e32 v183, v179, v175
	v_cmp_ge_f32_e32 vcc, s65, v183
	v_max_f32_e32 v183, v175, v175
	v_max_f32_e32 v183, v183, v179
	v_mfma_f32_32x32x16_bf16 v[0:15], v[220:223], v[236:239], v[0:15]
	v_sub_f32_e32 v179, v175, v183
	v_mul_f32_e32 v179, 0x3e38aa3b, v179
	v_exp_f32_e32 v179, v179
	s_cmp_eq_u64 vcc, exec
	s_cselect_b64 s[8:9], -1, 0
	s_barrier
	s_waitcnt vmcnt(0)
	v_cndmask_b32_e64 v179, v179, 1.0, s[8:9]
	v_cmp_gt_f32_e32 vcc, 1.0, v179
	s_waitcnt vmcnt(3)
	ds_write_b128 v163, v[114:117] offset:16384
	s_waitcnt vmcnt(1)
	ds_write_b128 v164, v[126:129] offset:16384
	ds_write_b128 v161, v[118:121] offset:49152
	s_waitcnt vmcnt(0)
	ds_write_b128 v162, v[122:125] offset:49152
	s_cbranch_vccz .LBB0_270
	s_and_saveexec_b64 s[2:3], s[6:7]
	ds_write_b32 v157, v179 offset:128
	s_or_b64 exec, exec, s[2:3]
	s_waitcnt lgkmcnt(0)
	ds_read_b128 v[114:117], v158 offset:224
	ds_read_b128 v[118:121], v158 offset:192
	ds_read_b128 v[122:125], v158 offset:160
	ds_read_b128 v[126:129], v158 offset:128
	s_waitcnt lgkmcnt(3)
	v_pk_mul_f32 v[62:63], v[62:63], v[116:117]
	s_waitcnt lgkmcnt(2)
	v_pk_mul_f32 v[58:59], v[58:59], v[120:121]
	s_waitcnt lgkmcnt(1)
	v_pk_mul_f32 v[54:55], v[54:55], v[124:125]
	s_waitcnt lgkmcnt(0)
	v_pk_mul_f32 v[50:51], v[50:51], v[128:129]
	v_pk_mul_f32 v[60:61], v[60:61], v[114:115]
	v_pk_mul_f32 v[56:57], v[56:57], v[118:119]
	v_pk_mul_f32 v[52:53], v[52:53], v[122:123]
	v_pk_mul_f32 v[48:49], v[48:49], v[126:127]
	v_pk_mul_f32 v[46:47], v[46:47], v[116:117]
	v_pk_mul_f32 v[42:43], v[42:43], v[120:121]
	v_pk_mul_f32 v[38:39], v[38:39], v[124:125]
	v_pk_mul_f32 v[34:35], v[34:35], v[128:129]
	v_pk_mul_f32 v[44:45], v[44:45], v[114:115]
	v_pk_mul_f32 v[40:41], v[40:41], v[118:119]
	v_pk_mul_f32 v[36:37], v[36:37], v[122:123]
	v_pk_mul_f32 v[32:33], v[32:33], v[126:127]
	v_pk_mul_f32 v[30:31], v[30:31], v[116:117]
	v_pk_mul_f32 v[26:27], v[26:27], v[120:121]
	v_pk_mul_f32 v[22:23], v[22:23], v[124:125]
	v_pk_mul_f32 v[18:19], v[18:19], v[128:129]
	v_pk_mul_f32 v[28:29], v[28:29], v[114:115]
	v_pk_mul_f32 v[24:25], v[24:25], v[118:119]
	v_pk_mul_f32 v[20:21], v[20:21], v[122:123]
	v_pk_mul_f32 v[16:17], v[16:17], v[126:127]
	v_pk_mul_f32 v[14:15], v[14:15], v[116:117]
	v_pk_mul_f32 v[10:11], v[10:11], v[120:121]
	v_pk_mul_f32 v[6:7], v[6:7], v[124:125]
	v_pk_mul_f32 v[2:3], v[2:3], v[128:129]
	v_pk_mul_f32 v[12:13], v[12:13], v[114:115]
	v_pk_mul_f32 v[8:9], v[8:9], v[118:119]
	v_pk_mul_f32 v[4:5], v[4:5], v[122:123]
	v_pk_mul_f32 v[0:1], v[0:1], v[126:127]

; __device__ __forceinline__ void finishSM(f32x16& p0, f32x16& p1, float alpha, float& l_reg, bf16x8& pa0, bf16x8& pa1, bf16x8& pa2, bf16x8& pa3) {
; #pragma unroll
;     for (int r = 0; r < 16; ++r) p1[r] = __builtin_amdgcn_exp2f(p1[r]);
;     float ps = 0;
; #pragma unroll
;     for (int r = 0; r < 16; ++r) ps += p0[r];
; #pragma unroll
;     for (int r = 0; r < 16; ++r) ps += p1[r];
;     { auto rr = __builtin_amdgcn_permlane32_swap(__float_as_uint(ps), __float_as_uint(ps), false, false);
;       ps = __uint_as_float(rr[0]) + __uint_as_float(rr[1]); }
;     l_reg = l_reg * alpha + ps;
;     ...
;     PK4(p0, 0, pa0); PK4(p0, 8, pa1); PK4(p1, 0, pa2); PK4(p1, 8, pa3);
;     ...
; }
; __device__ __forceinline__ void qkt(f32x16& p0, f32x16& p1, const char* Ks, const bf16x8* qr, int r32, int hi, int comp) {
;     p0 = f32x16{}; p1 = f32x16{};
; #pragma unroll
;     for (int d0 = 0; d0 < 4; ++d0) { const int cb = (comp * 64 + d0 * 16 + hi * 8) * 2;
;         const bf16x8 b0 = *reinterpret_cast<const bf16x8*>(Ks + KSWZ(r32, cb));
;         const bf16x8 b1 = *reinterpret_cast<const bf16x8*>(Ks + KSWZ(32 + r32, cb));
;         p0 = __builtin_amdgcn_mfma_f32_32x32x16_bf16(b0, qr[d0], p0, 0, 0, 0);
;         p1 = __builtin_amdgcn_mfma_f32_32x32x16_bf16(b1, qr[d0], p1, 0, 0, 0); }
; }
; __device__ __forceinline__ int v_st(int k, int c) { const int kk = (k & ~0xC) | ((k & 4) << 1) | ((k & 8) >> 1); return ((kk >> 3) * 4 + (c >> 5)) * 512 + ((kk & 7) * 32 + (c & 31)) * 2; }
; __device__ __forceinline__ int v_rd_base(int lane) { return ((lane & 3) << 3) | (((lane >> 2) & 3) << 6) | (((lane >> 4) & 1) << 5) | (((lane >> 5) & 1) << 8); }
; template <int OFF> __device__ __forceinline__ s16x4 tr_read(int vb) {
;     s16x4 r; asm volatile("ds_read_b64_tr_b16 %0, %1 offset:%2" : "=&v"(r) : "v"(vb), "i"(OFF) : "memory"); return r;
; }
; template <int D0> __device__ __forceinline__ void pv_one(f32x16& od, int vb, bf16x8 pa0, bf16x8 pa1, bf16x8 pa2, bf16x8 pa3) {
;     const s16x4 l0 = tr_read<v_rd_off(D0, 0, 0)>(vb), h0 = tr_read<v_rd_off(D0, 0, 1)>(vb), l1 = tr_read<v_rd_off(D0, 1, 0)>(vb), h1 = tr_read<v_rd_off(D0, 1, 1)>(vb);
;     const s16x4 l2 = tr_read<v_rd_off(D0, 2, 0)>(vb), h2 = tr_read<v_rd_off(D0, 2, 1)>(vb), l3 = tr_read<v_rd_off(D0, 3, 0)>(vb), h3 = tr_read<v_rd_off(D0, 3, 1)>(vb);
;     asm volatile("s_waitcnt lgkmcnt(0)" ::: "memory"); SBAR();
.LBB0_280:
	ds_read_b128 v[64:67], v140 offset:49152
	ds_read_b128 v[68:71], v140 offset:57344
	v_add_f32_e32 v135, 0, v169
	v_add_f32_e32 v135, v173, v135
	v_add_f32_e32 v135, v170, v135
	s_waitcnt lgkmcnt(1)
	v_mfma_f32_32x32x16_bf16 v[80:95], v[64:67], v[110:113], 0
	v_add_f32_e32 v135, v174, v135
	v_add_f32_e32 v135, v171, v135
	ds_read_b128 v[136:139], v143 offset:49152
	ds_read_b128 v[178:181], v143 offset:57344
	v_add_f32_e32 v135, v175, v135
	v_add_f32_e32 v135, v172, v135
	v_add_f32_e32 v135, v176, v135
	v_add_f32_e32 v135, v145, v135
	s_waitcnt lgkmcnt(2)
	v_mfma_f32_32x32x16_bf16 v[64:79], v[68:71], v[110:113], 0
	v_add_f32_e32 v135, v149, v135
	v_add_f32_e32 v135, v146, v135
	v_add_f32_e32 v135, v166, v135
	v_exp_f32_e32 v128, v128
	v_add_f32_e32 v135, v147, v135
	v_exp_f32_e32 v129, v129
	v_add_f32_e32 v135, v167, v135
	s_waitcnt lgkmcnt(1)
	v_mfma_f32_32x32x16_bf16 v[80:95], v[136:139], v[106:109], v[80:95]
	v_exp_f32_e32 v126, v126
	v_add_f32_e32 v135, v148, v135
	v_exp_f32_e32 v127, v127
	v_add_f32_e32 v135, v168, v135
	v_exp_f32_e32 v122, v122
	v_add_f32_e32 v135, v128, v135
	v_exp_f32_e32 v123, v123
	s_waitcnt lgkmcnt(0)
	v_mfma_f32_32x32x16_bf16 v[64:79], v[178:181], v[106:109], v[64:79]
	ds_read_b128 v[136:139], v142 offset:49152
	ds_read_b128 v[178:181], v142 offset:57344
	v_add_f32_e32 v135, v129, v135
	v_exp_f32_e32 v118, v118
	v_add_f32_e32 v135, v126, v135
	v_exp_f32_e32 v119, v119
	v_add_f32_e32 v135, v127, v135
	v_exp_f32_e32 v116, v116
	s_waitcnt lgkmcnt(1)
	v_mfma_f32_32x32x16_bf16 v[80:95], v[136:139], v[102:105], v[80:95]
	v_add_f32_e32 v135, v122, v135
	v_exp_f32_e32 v117, v117
	v_add_f32_e32 v135, v123, v135
	v_exp_f32_e32 v124, v124
	v_add_f32_e32 v135, v118, v135
	v_exp_f32_e32 v125, v125
	v_add_f32_e32 v135, v119, v135
	s_waitcnt lgkmcnt(0)
	v_mfma_f32_32x32x16_bf16 v[64:79], v[178:181], v[102:105], v[64:79]
	ds_read_b128 v[136:139], v141 offset:49152
	ds_read_b128 v[178:181], v141 offset:57344
	v_exp_f32_e32 v120, v120
	v_add_f32_e32 v135, v116, v135
	v_exp_f32_e32 v121, v121
	v_add_f32_e32 v135, v117, v135
	v_exp_f32_e32 v114, v114
	v_add_f32_e32 v135, v124, v135
	s_waitcnt lgkmcnt(1)
	v_mfma_f32_32x32x16_bf16 v[80:95], v[136:139], v[98:101], v[80:95]
	v_exp_f32_e32 v115, v115
	v_add_f32_e32 v135, v125, v135
	v_add_f32_e32 v135, v120, v135
	v_add_f32_e32 v135, v121, v135
	v_add_f32_e32 v135, v114, v135
	v_add_f32_e32 v135, v115, v135
	v_mov_b32_e32 v136, v135
	s_waitcnt lgkmcnt(0)
	v_mfma_f32_32x32x16_bf16 v[64:79], v[178:181], v[98:101], v[64:79]
	v_permlane32_swap_b32_e32 v135, v136
	v_cvt_pk_bf16_f32 v178, v169, v173
	v_cvt_pk_bf16_f32 v179, v170, v174
	v_cvt_pk_bf16_f32 v180, v171, v175
	v_cvt_pk_bf16_f32 v181, v172, v176
	v_cvt_pk_bf16_f32 v144, v145, v149
	v_cvt_pk_bf16_f32 v145, v146, v166
	v_cvt_pk_bf16_f32 v146, v147, v167
	v_cvt_pk_bf16_f32 v147, v148, v168
	v_cvt_pk_bf16_f32 v166, v128, v129
	v_cvt_pk_bf16_f32 v167, v126, v127
	v_cvt_pk_bf16_f32 v168, v122, v123
	v_cvt_pk_bf16_f32 v169, v118, v119
	v_cvt_pk_bf16_f32 v170, v116, v117
	v_cvt_pk_bf16_f32 v171, v124, v125
	v_cvt_pk_bf16_f32 v172, v120, v121
	v_cvt_pk_bf16_f32 v173, v114, v115
	s_nop 0
	v_permlane32_swap_b32_e32 v178, v180
	v_permlane32_swap_b32_e32 v179, v181
	v_permlane32_swap_b32_e32 v144, v146
	v_permlane32_swap_b32_e32 v145, v147
	v_permlane32_swap_b32_e32 v166, v168
	v_permlane32_swap_b32_e32 v167, v169
	v_permlane32_swap_b32_e32 v170, v172
	v_permlane32_swap_b32_e32 v171, v173
	v_add_u32_e32 v122, 0x10000, v96
	global_load_dwordx4 v[240:243], v96, s[58:59]
	global_load_dwordx4 v[244:247], v96, s[28:29]
	global_load_dwordx4 v[206:209], v122, s[58:59]
	s_nop 0
	global_load_dwordx4 v[248:251], v122, s[28:29]
	ds_read_b64_tr_b16 v[174:175], v160 offset:0
	ds_read_b64_tr_b16 v[176:177], v160 offset:0x800
	ds_read_b64_tr_b16 v[182:183], v160 offset:0x1000
	ds_read_b64_tr_b16 v[184:185], v160 offset:0x1800
	ds_read_b64_tr_b16 v[186:187], v160 offset:0x2000
	ds_read_b64_tr_b16 v[188:189], v160 offset:0x2800
	ds_read_b64_tr_b16 v[212:213], v160 offset:0x3000
	ds_read_b64_tr_b16 v[214:215], v160 offset:0x3800
	s_waitcnt lgkmcnt(0)
	s_nop 0
	v_mfma_f32_32x32x16_bf16 v[48:63], v[178:181], v[174:177], v[48:63]
	ds_read_b64_tr_b16 v[174:175], v160 offset:0x200
	ds_read_b64_tr_b16 v[176:177], v160 offset:0xa00
	v_max_f32_e32 v137, v81, v81
	v_max_f32_e32 v138, v80, v80
	v_max_f32_e32 v137, v138, v137
	v_max3_f32 v137, v137, v82, v83
	v_max3_f32 v137, v137, v84, v85
	v_mfma_f32_32x32x16_bf16 v[48:63], v[144:147], v[182:185], v[48:63]
	ds_read_b64_tr_b16 v[182:183], v160 offset:0x1200
	ds_read_b64_tr_b16 v[184:185], v160 offset:0x1a00
	v_max3_f32 v137, v137, v86, v87
	v_max3_f32 v137, v137, v88, v89
	v_max3_f32 v137, v137, v90, v91
	v_max3_f32 v137, v137, v92, v93
	v_max3_f32 v137, v137, v94, v95
	v_mfma_f32_32x32x16_bf16 v[48:63], v[166:169], v[186:189], v[48:63]
	ds_read_b64_tr_b16 v[186:187], v160 offset:0x2200
	ds_read_b64_tr_b16 v[188:189], v160 offset:0x2a00
	v_max3_f32 v137, v137, v64, v65
	v_max3_f32 v137, v137, v66, v67
	v_max3_f32 v137, v137, v68, v69
	v_max3_f32 v137, v137, v70, v71
	v_max3_f32 v137, v137, v72, v73
	v_mfma_f32_32x32x16_bf16 v[48:63], v[170:173], v[212:215], v[48:63]
	ds_read_b64_tr_b16 v[212:213], v160 offset:0x3200
	ds_read_b64_tr_b16 v[214:215], v160 offset:0x3a00
	v_max3_f32 v137, v137, v74, v75
	v_max3_f32 v137, v137, v76, v77
	v_max3_f32 v137, v137, v78, v79
	v_mov_b32_e32 v138, v137
	s_nop 1
	v_permlane32_swap_b32_e32 v137, v138
	s_waitcnt lgkmcnt(0)
; #define SBAR() __builtin_amdgcn_sched_barrier(0)
; #define SWAIT() asm volatile("s_waitcnt vmcnt(0)" ::: "memory")
; __device__ __forceinline__ void partialSM(f32x16& p0, f32x16& p1, float& m_reg, float& mn, float& alpha) {
;     constexpr float C = SCALE * 1.4426950408889634f;
;     float pmax = p0[0];
; #pragma unroll
;     for (int r = 1; r < 16; ++r) pmax = fmaxf(pmax, p0[r]);
; #pragma unroll
;     for (int r = 0; r < 16; ++r) pmax = fmaxf(pmax, p1[r]);
;     { auto rr = __builtin_amdgcn_permlane32_swap(__float_as_uint(pmax), __float_as_uint(pmax), false, false);
;       pmax = fmaxf(__uint_as_float(rr[0]), __uint_as_float(rr[1])); }
;     if (__builtin_expect(__all(pmax - m_reg <= THR / SCALE), 1)) { mn = m_reg; alpha = 1.f; }
;     else { mn = fmaxf(m_reg, pmax); alpha = __builtin_amdgcn_exp2f((m_reg - mn) * C); m_reg = mn; }
;     const float mnC = -mn * C;
; #pragma unroll
;     for (int r = 0; r < 16; ++r) p0[r] = fmaf(p0[r], C, mnC);
; #pragma unroll
;     for (int r = 0; r < 16; ++r) p1[r] = fmaf(p1[r], C, mnC);
; #pragma unroll
;     for (int r = 0; r < 16; ++r) p0[r] = __builtin_amdgcn_exp2f(p0[r]);
; }
; __device__ __forceinline__ void attn_unit(const bf16_t* Qb, const bf16_t* Kh, const bf16_t* Vh, bf16_t* Ob, float* scr, int seq, float lam, float onemli, const float* subg, char* lds) {
;     ...
;         f32x16 pA0, pA1, pB0, pB1; float mnA, mnB, alA, alB; bf16x8 pa0, pa1, pa2, pa3;
;         constexpr int SE = 0, SO = 0;
;         __syncthreads();
;         SLOAD(SE, 0); asm volatile("s_waitcnt vmcnt(0)" ::: "memory"); SWRITE(0, SE); __syncthreads();
;         qkt(pA0, pA1, K_lds, qr, r32, hi, comp); partialSM(pA0, pA1, m_reg, mnA, alA);
;         SLOAD(SO, KVBLK);
;         SWAIT(); SWRITE(1, SO); __syncthreads();
;         for (int j = 1; j + 1 < NT; j += 2) {
;             SBAR(); qkt(pB0, pB1, K_lds + SHM_K, qr, r32, hi, comp);
;             finishSM(pA0, pA1, alA, l_reg, pa0, pa1, pa2, pa3); SBAR();
;             SLOAD(SO, (j + 1) * KVBLK); SBAR();
;             pv_d0(o, vb0, pa0, pa1, pa2, pa3); partialSM(pB0, pB1, m_reg, mnB, alB);
;             __syncthreads(); SWAIT(); SWRITE(0, SE);
;             RESC(alB); __syncthreads();
	v_mfma_f32_32x32x16_bf16 v[32:47], v[178:181], v[174:177], v[32:47]
	ds_read_b64_tr_b16 v[174:175], v160 offset:0x400
	ds_read_b64_tr_b16 v[176:177], v160 offset:0xc00
	v_max_f32_e32 v138, v138, v138
	v_max_f32_e32 v137, v137, v137
	v_max_f32_e32 v137, v137, v138
	v_sub_f32_e32 v138, v137, v134
	v_cmp_ge_f32_e32 vcc, s65, v138
	v_mfma_f32_32x32x16_bf16 v[32:47], v[144:147], v[182:185], v[32:47]
	ds_read_b64_tr_b16 v[182:183], v160 offset:0x1400
	ds_read_b64_tr_b16 v[184:185], v160 offset:0x1c00
	v_max_f32_e32 v138, v134, v134
	v_max_f32_e32 v137, v138, v137
	v_sub_f32_e32 v138, v134, v137
	v_mul_f32_e32 v138, 0x3e38aa3b, v138
	v_exp_f32_e32 v138, v138
	v_mfma_f32_32x32x16_bf16 v[32:47], v[166:169], v[186:189], v[32:47]
	ds_read_b64_tr_b16 v[186:187], v160 offset:0x2400
	ds_read_b64_tr_b16 v[188:189], v160 offset:0x2c00
	s_cmp_eq_u64 vcc, exec
	s_cselect_b64 s[8:9], -1, 0
	v_cndmask_b32_e64 v138, v138, 1.0, s[8:9]
	v_cndmask_b32_e64 v134, v137, v134, s[8:9]
	v_mul_f32_e32 v137, 0xbe38aa3b, v134
	v_mfma_f32_32x32x16_bf16 v[32:47], v[170:173], v[212:215], v[32:47]
	ds_read_b64_tr_b16 v[212:213], v160 offset:0x3400
	ds_read_b64_tr_b16 v[214:215], v160 offset:0x3c00
	v_fmamk_f32 v80, v80, 0x3e38aa3b, v137
	v_fmamk_f32 v81, v81, 0x3e38aa3b, v137
	v_fmamk_f32 v82, v82, 0x3e38aa3b, v137
	v_fmamk_f32 v83, v83, 0x3e38aa3b, v137
	v_fmamk_f32 v84, v84, 0x3e38aa3b, v137
	s_waitcnt lgkmcnt(0)
	v_mfma_f32_32x32x16_bf16 v[16:31], v[178:181], v[174:177], v[16:31]
	ds_read_b64_tr_b16 v[174:175], v160 offset:0x600
	ds_read_b64_tr_b16 v[176:177], v160 offset:0xe00
	v_fmamk_f32 v85, v85, 0x3e38aa3b, v137
	v_fmamk_f32 v86, v86, 0x3e38aa3b, v137
	v_fmamk_f32 v87, v87, 0x3e38aa3b, v137
	v_fmamk_f32 v88, v88, 0x3e38aa3b, v137
	v_fmamk_f32 v89, v89, 0x3e38aa3b, v137
	v_mfma_f32_32x32x16_bf16 v[16:31], v[144:147], v[182:185], v[16:31]
	ds_read_b64_tr_b16 v[182:183], v160 offset:0x1600
	ds_read_b64_tr_b16 v[184:185], v160 offset:0x1e00
	v_fmamk_f32 v90, v90, 0x3e38aa3b, v137
	v_fmamk_f32 v91, v91, 0x3e38aa3b, v137
	v_fmamk_f32 v92, v92, 0x3e38aa3b, v137
	v_fmamk_f32 v93, v93, 0x3e38aa3b, v137
	v_fmamk_f32 v94, v94, 0x3e38aa3b, v137
	v_mfma_f32_32x32x16_bf16 v[16:31], v[166:169], v[186:189], v[16:31]
	ds_read_b64_tr_b16 v[186:187], v160 offset:0x2600
	ds_read_b64_tr_b16 v[188:189], v160 offset:0x2e00
	v_fmamk_f32 v95, v95, 0x3e38aa3b, v137
	v_exp_f32_e32 v127, v80
	v_exp_f32_e32 v129, v81
	v_mfma_f32_32x32x16_bf16 v[16:31], v[170:173], v[212:215], v[16:31]
	ds_read_b64_tr_b16 v[212:213], v160 offset:0x3600
	ds_read_b64_tr_b16 v[214:215], v160 offset:0x3e00
	v_exp_f32_e32 v125, v82
	v_exp_f32_e32 v128, v83
	v_exp_f32_e32 v123, v84
	s_waitcnt lgkmcnt(0)
	v_mfma_f32_32x32x16_bf16 v[0:15], v[178:181], v[174:177], v[0:15]
	s_barrier
	s_waitcnt vmcnt(0)
	s_waitcnt vmcnt(3)
	ds_write_b128 v163, v[240:243]
	s_waitcnt vmcnt(1)
	ds_write_b128 v164, v[206:209]
	ds_write_b128 v161, v[244:247] offset:32768
	s_waitcnt vmcnt(0)
	ds_write_b128 v162, v[248:251] offset:32768
	v_exp_f32_e32 v126, v85
	v_exp_f32_e32 v122, v86
	v_exp_f32_e32 v124, v87
	v_mfma_f32_32x32x16_bf16 v[0:15], v[144:147], v[182:185], v[0:15]
	v_exp_f32_e32 v119, v88
	v_exp_f32_e32 v121, v89
	v_exp_f32_e32 v117, v90
	v_mfma_f32_32x32x16_bf16 v[0:15], v[166:169], v[186:189], v[0:15]
	v_exp_f32_e32 v120, v91
	v_exp_f32_e32 v115, v92
	v_exp_f32_e32 v118, v93
	v_mfma_f32_32x32x16_bf16 v[0:15], v[170:173], v[212:215], v[0:15]
	v_exp_f32_e32 v114, v94
	v_exp_f32_e32 v116, v95
	v_cmp_gt_f32_e32 vcc, 1.0, v138
	s_cbranch_vccz .LBB0_284
	s_and_saveexec_b64 s[2:3], s[6:7]
	ds_write_b32 v157, v138 offset:128
	s_or_b64 exec, exec, s[2:3]
	s_waitcnt lgkmcnt(0)
	ds_read_b128 v[240:243], v158 offset:224
	ds_read_b128 v[244:247], v158 offset:192
	ds_read_b128 v[248:251], v158 offset:160
	ds_read_b128 v[206:209], v158 offset:128
	s_waitcnt lgkmcnt(3)
	v_pk_mul_f32 v[62:63], v[62:63], v[242:243]
	s_waitcnt lgkmcnt(2)
	v_pk_mul_f32 v[58:59], v[58:59], v[246:247]
	s_waitcnt lgkmcnt(1)
	v_pk_mul_f32 v[54:55], v[54:55], v[250:251]
	s_waitcnt lgkmcnt(0)
	v_pk_mul_f32 v[50:51], v[50:51], v[208:209]
	v_pk_mul_f32 v[60:61], v[60:61], v[240:241]
	v_pk_mul_f32 v[56:57], v[56:57], v[244:245]
	v_pk_mul_f32 v[52:53], v[52:53], v[248:249]
	v_pk_mul_f32 v[48:49], v[48:49], v[206:207]
	v_pk_mul_f32 v[46:47], v[46:47], v[242:243]
	v_pk_mul_f32 v[42:43], v[42:43], v[246:247]
	v_pk_mul_f32 v[38:39], v[38:39], v[250:251]
	v_pk_mul_f32 v[34:35], v[34:35], v[208:209]
	v_pk_mul_f32 v[44:45], v[44:45], v[240:241]
	v_pk_mul_f32 v[40:41], v[40:41], v[244:245]
	v_pk_mul_f32 v[36:37], v[36:37], v[248:249]
	v_pk_mul_f32 v[32:33], v[32:33], v[206:207]
	v_pk_mul_f32 v[30:31], v[30:31], v[242:243]
	v_pk_mul_f32 v[26:27], v[26:27], v[246:247]
	v_pk_mul_f32 v[22:23], v[22:23], v[250:251]
	v_pk_mul_f32 v[18:19], v[18:19], v[208:209]
	v_pk_mul_f32 v[28:29], v[28:29], v[240:241]
	v_pk_mul_f32 v[24:25], v[24:25], v[244:245]
	v_pk_mul_f32 v[20:21], v[20:21], v[248:249]
	v_pk_mul_f32 v[16:17], v[16:17], v[206:207]
	v_pk_mul_f32 v[14:15], v[14:15], v[242:243]
	v_pk_mul_f32 v[10:11], v[10:11], v[246:247]
	v_pk_mul_f32 v[6:7], v[6:7], v[250:251]
	v_pk_mul_f32 v[2:3], v[2:3], v[208:209]
	v_pk_mul_f32 v[12:13], v[12:13], v[240:241]
	v_pk_mul_f32 v[8:9], v[8:9], v[244:245]
	v_pk_mul_f32 v[4:5], v[4:5], v[248:249]
	v_pk_mul_f32 v[0:1], v[0:1], v[206:207]
; #define SBAR() __builtin_amdgcn_sched_barrier(0)
; __device__ __forceinline__ void partialSM(f32x16& p0, f32x16& p1, float& m_reg, float& mn, float& alpha) {
;     ...
;     for (int r = 0; r < 16; ++r) p0[r] = fmaf(p0[r], C, mnC);
; #pragma unroll
;     for (int r = 0; r < 16; ++r) p1[r] = fmaf(p1[r], C, mnC);
; #pragma unroll
;     for (int r = 0; r < 16; ++r) p0[r] = __builtin_amdgcn_exp2f(p0[r]);
; }
; __device__ __forceinline__ void finishSM(f32x16& p0, f32x16& p1, float alpha, float& l_reg, bf16x8& pa0, bf16x8& pa1, bf16x8& pa2, bf16x8& pa3) {
; #pragma unroll
;     for (int r = 0; r < 16; ++r) p1[r] = __builtin_amdgcn_exp2f(p1[r]);
;     float ps = 0;
; #pragma unroll
;     for (int r = 0; r < 16; ++r) ps += p0[r];
; #pragma unroll
;     for (int r = 0; r < 16; ++r) ps += p1[r];
;     { auto rr = __builtin_amdgcn_permlane32_swap(__float_as_uint(ps), __float_as_uint(ps), false, false);
;       ps = __uint_as_float(rr[0]) + __uint_as_float(rr[1]); }
;     l_reg = l_reg * alpha + ps;
;     ...
;     PK4(p0, 0, pa0); PK4(p0, 8, pa1); PK4(p1, 0, pa2); PK4(p1, 8, pa3);
;     ...
; }
; __device__ __forceinline__ void qkt(f32x16& p0, f32x16& p1, const char* Ks, const bf16x8* qr, int r32, int hi, int comp) {
;     p0 = f32x16{}; p1 = f32x16{};
; #pragma unroll
;     for (int d0 = 0; d0 < 4; ++d0) { const int cb = (comp * 64 + d0 * 16 + hi * 8) * 2;
;         const bf16x8 b0 = *reinterpret_cast<const bf16x8*>(Ks + KSWZ(r32, cb));
;         const bf16x8 b1 = *reinterpret_cast<const bf16x8*>(Ks + KSWZ(32 + r32, cb));
;         p0 = __builtin_amdgcn_mfma_f32_32x32x16_bf16(b0, qr[d0], p0, 0, 0, 0);
;         p1 = __builtin_amdgcn_mfma_f32_32x32x16_bf16(b1, qr[d0], p1, 0, 0, 0); }
; }
; __device__ __forceinline__ void attn_unit(const bf16_t* Qb, const bf16_t* Kh, const bf16_t* Vh, bf16_t* Ob, float* scr, int seq, float lam, float onemli, const float* subg, char* lds) {
;     ...
;             RESC(alB); __syncthreads();
;             SBAR(); qkt(pA0, pA1, K_lds, qr, r32, hi, comp);
;             finishSM(pB0, pB1, alB, l_reg, pa0, pa1, pa2, pa3); SBAR();
;             SLOAD(SE, (j + 2) * KVBLK); SBAR();
;             pv_d0(o, vb0 + (int)SHM_V, pa0, pa1, pa2, pa3); partialSM(pA0, pA1, m_reg, mnA, alA);
.LBB0_284:
	v_fmamk_f32 v167, v64, 0x3e38aa3b, v137
	v_fmamk_f32 v168, v65, 0x3e38aa3b, v137
	v_fmamk_f32 v169, v66, 0x3e38aa3b, v137
	v_fmamk_f32 v170, v67, 0x3e38aa3b, v137
	v_fmamk_f32 v171, v68, 0x3e38aa3b, v137
	v_fmamk_f32 v144, v69, 0x3e38aa3b, v137
	v_fmamk_f32 v145, v70, 0x3e38aa3b, v137
	v_fmamk_f32 v146, v71, 0x3e38aa3b, v137
	v_fmamk_f32 v147, v72, 0x3e38aa3b, v137
	v_fmamk_f32 v148, v73, 0x3e38aa3b, v137
	v_fmamk_f32 v149, v74, 0x3e38aa3b, v137
	v_fmamk_f32 v166, v75, 0x3e38aa3b, v137
	v_fmamk_f32 v139, v76, 0x3e38aa3b, v137
	v_fmamk_f32 v172, v77, 0x3e38aa3b, v137
	v_fmamk_f32 v173, v78, 0x3e38aa3b, v137
	v_fmac_f32_e32 v137, 0x3e38aa3b, v79
	s_waitcnt lgkmcnt(0)
	s_barrier
	ds_read_b128 v[64:67], v140 offset:32768
	ds_read_b128 v[68:71], v140 offset:40960
	ds_read_b128 v[174:177], v143 offset:32768
	ds_read_b128 v[178:181], v143 offset:40960
	v_exp_f32_e32 v185, v139
	v_add_f32_e32 v139, 0, v127
	s_waitcnt lgkmcnt(3)
	v_mfma_f32_32x32x16_bf16 v[80:95], v[64:67], v[110:113], 0
	v_add_f32_e32 v139, v129, v139
	v_add_f32_e32 v139, v125, v139
	v_add_f32_e32 v139, v128, v139
	v_add_f32_e32 v139, v123, v139
	v_add_f32_e32 v139, v126, v139
	v_add_f32_e32 v139, v122, v139
	v_add_f32_e32 v139, v124, v139
	s_waitcnt lgkmcnt(2)
	v_mfma_f32_32x32x16_bf16 v[64:79], v[68:71], v[110:113], 0
	v_add_f32_e32 v139, v119, v139
	v_add_f32_e32 v139, v121, v139
	v_add_f32_e32 v139, v117, v139
	v_add_f32_e32 v139, v120, v139
	v_add_f32_e32 v139, v115, v139
	v_add_f32_e32 v139, v118, v139
	v_add_f32_e32 v139, v114, v139
	s_waitcnt lgkmcnt(1)
	v_mfma_f32_32x32x16_bf16 v[80:95], v[174:177], v[106:109], v[80:95]
	v_add_f32_e32 v139, v116, v139
	v_exp_f32_e32 v145, v145
	v_exp_f32_e32 v182, v148
	v_exp_f32_e32 v183, v149
	v_exp_f32_e32 v184, v166
	v_exp_f32_e32 v186, v172
	v_exp_f32_e32 v187, v173
	s_waitcnt lgkmcnt(0)
	v_mfma_f32_32x32x16_bf16 v[64:79], v[178:181], v[106:109], v[64:79]
	ds_read_b128 v[174:177], v142 offset:32768
	ds_read_b128 v[178:181], v142 offset:40960
	v_exp_f32_e32 v137, v137
	s_waitcnt lgkmcnt(1)
	v_mfma_f32_32x32x16_bf16 v[80:95], v[174:177], v[102:105], v[80:95]
	s_waitcnt lgkmcnt(0)
	v_mfma_f32_32x32x16_bf16 v[64:79], v[178:181], v[102:105], v[64:79]
	ds_read_b128 v[174:177], v141 offset:32768
	ds_read_b128 v[178:181], v141 offset:40960
	s_waitcnt lgkmcnt(1)
	v_mfma_f32_32x32x16_bf16 v[80:95], v[174:177], v[98:101], v[80:95]
	v_exp_f32_e32 v174, v167
	v_exp_f32_e32 v175, v168
	v_exp_f32_e32 v176, v169
	v_exp_f32_e32 v177, v170
	v_add_f32_e32 v139, v174, v139
	v_add_f32_e32 v139, v175, v139
	v_add_f32_e32 v139, v176, v139
	s_waitcnt lgkmcnt(0)
	v_mfma_f32_32x32x16_bf16 v[64:79], v[178:181], v[98:101], v[64:79]
	v_exp_f32_e32 v178, v171
	v_exp_f32_e32 v179, v144
	v_exp_f32_e32 v180, v146
	v_add_f32_e32 v139, v177, v139
	v_exp_f32_e32 v181, v147
	v_add_f32_e32 v139, v178, v139
	v_add_f32_e32 v139, v179, v139
	v_add_f32_e32 v139, v145, v139
	v_add_f32_e32 v139, v180, v139
	v_add_f32_e32 v139, v181, v139
	v_add_f32_e32 v139, v182, v139
	v_add_f32_e32 v139, v183, v139
	v_add_f32_e32 v139, v184, v139
	v_add_f32_e32 v139, v185, v139
	v_add_f32_e32 v139, v186, v139
	v_add_f32_e32 v139, v187, v139
	v_add_f32_e32 v139, v137, v139
	v_mov_b32_e32 v144, v139
	s_nop 1
	v_permlane32_swap_b32_e32 v139, v144
	v_cvt_pk_bf16_f32 v146, v127, v129
	v_cvt_pk_bf16_f32 v147, v125, v128
	v_cvt_pk_bf16_f32 v148, v123, v126
	v_cvt_pk_bf16_f32 v149, v122, v124
	v_cvt_pk_bf16_f32 v166, v119, v121
	v_cvt_pk_bf16_f32 v167, v117, v120
	v_cvt_pk_bf16_f32 v168, v115, v118
	v_cvt_pk_bf16_f32 v169, v114, v116
	v_cvt_pk_bf16_f32 v170, v174, v175
	v_cvt_pk_bf16_f32 v171, v176, v177
	v_cvt_pk_bf16_f32 v172, v178, v179
	v_cvt_pk_bf16_f32 v173, v145, v180
	v_cvt_pk_bf16_f32 v174, v181, v182
	v_cvt_pk_bf16_f32 v175, v183, v184
	v_cvt_pk_bf16_f32 v176, v185, v186
	v_cvt_pk_bf16_f32 v177, v187, v137
	s_nop 0
	v_permlane32_swap_b32_e32 v146, v148
	v_permlane32_swap_b32_e32 v147, v149
	v_permlane32_swap_b32_e32 v166, v168
	v_permlane32_swap_b32_e32 v167, v169
	v_permlane32_swap_b32_e32 v170, v172
	v_permlane32_swap_b32_e32 v171, v173
	v_permlane32_swap_b32_e32 v174, v176
	v_permlane32_swap_b32_e32 v175, v177
	v_add_u32_e32 v118, 0x20000, v96
	v_add_u32_e32 v122, 0x30000, v96
	global_load_dwordx4 v[114:117], v118, s[58:59]
	s_nop 0
	global_load_dwordx4 v[118:121], v118, s[28:29]
	s_nop 0
	global_load_dwordx4 v[126:129], v122, s[58:59]
	s_nop 0
	global_load_dwordx4 v[122:125], v122, s[28:29]
	ds_read_b64_tr_b16 v[178:179], v159 offset:0
	ds_read_b64_tr_b16 v[180:181], v159 offset:0x800
	ds_read_b64_tr_b16 v[182:183], v159 offset:0x1000
	ds_read_b64_tr_b16 v[184:185], v159 offset:0x1800
	ds_read_b64_tr_b16 v[186:187], v159 offset:0x2000
	ds_read_b64_tr_b16 v[188:189], v159 offset:0x2800
	ds_read_b64_tr_b16 v[212:213], v159 offset:0x3000
	ds_read_b64_tr_b16 v[214:215], v159 offset:0x3800
	s_waitcnt lgkmcnt(0)
	s_nop 0
	v_mfma_f32_32x32x16_bf16 v[48:63], v[146:149], v[178:181], v[48:63]
	ds_read_b64_tr_b16 v[178:179], v159 offset:0x200
	ds_read_b64_tr_b16 v[180:181], v159 offset:0xa00
	v_mfma_f32_32x32x16_bf16 v[48:63], v[166:169], v[182:185], v[48:63]
	ds_read_b64_tr_b16 v[182:183], v159 offset:0x1200
	ds_read_b64_tr_b16 v[184:185], v159 offset:0x1a00
	v_mfma_f32_32x32x16_bf16 v[48:63], v[170:173], v[186:189], v[48:63]
	ds_read_b64_tr_b16 v[186:187], v159 offset:0x2200
	ds_read_b64_tr_b16 v[188:189], v159 offset:0x2a00
	v_mfma_f32_32x32x16_bf16 v[48:63], v[174:177], v[212:215], v[48:63]
	ds_read_b64_tr_b16 v[212:213], v159 offset:0x3200
	ds_read_b64_tr_b16 v[214:215], v159 offset:0x3a00
	s_waitcnt lgkmcnt(0)
; __device__ __forceinline__ void partialSM(f32x16& p0, f32x16& p1, float& m_reg, float& mn, float& alpha) {
;     constexpr float C = SCALE * 1.4426950408889634f;
;     float pmax = p0[0];
; #pragma unroll
;     for (int r = 1; r < 16; ++r) pmax = fmaxf(pmax, p0[r]);
; #pragma unroll
;     for (int r = 0; r < 16; ++r) pmax = fmaxf(pmax, p1[r]);
;     { auto rr = __builtin_amdgcn_permlane32_swap(__float_as_uint(pmax), __float_as_uint(pmax), false, false);
;       pmax = fmaxf(__uint_as_float(rr[0]), __uint_as_float(rr[1])); }
;     if (__builtin_expect(__all(pmax - m_reg <= THR / SCALE), 1)) { mn = m_reg; alpha = 1.f; }
;     else { mn = fmaxf(m_reg, pmax); alpha = __builtin_amdgcn_exp2f((m_reg - mn) * C); m_reg = mn; }
;     const float mnC = -mn * C;
; #pragma unroll
;     for (int r = 0; r < 16; ++r) p0[r] = fmaf(p0[r], C, mnC);
; #pragma unroll
;     for (int r = 0; r < 16; ++r) p1[r] = fmaf(p1[r], C, mnC);
; #pragma unroll
;     for (int r = 0; r < 16; ++r) p0[r] = __builtin_amdgcn_exp2f(p0[r]);
; }
; __device__ __forceinline__ void attn_unit(const bf16_t* Qb, const bf16_t* Kh, const bf16_t* Vh, bf16_t* Ob, float* scr, int seq, float lam, float onemli, const float* subg, char* lds) {
;     ...
;         f32x16 pA0, pA1, pB0, pB1; float mnA, mnB, alA, alB; bf16x8 pa0, pa1, pa2, pa3;
;         constexpr int SE = 0, SO = 0;
;         __syncthreads();
;         SLOAD(SE, 0); asm volatile("s_waitcnt vmcnt(0)" ::: "memory"); SWRITE(0, SE); __syncthreads();
;         qkt(pA0, pA1, K_lds, qr, r32, hi, comp); partialSM(pA0, pA1, m_reg, mnA, alA);
;         SLOAD(SO, KVBLK);
;         SWAIT(); SWRITE(1, SO); __syncthreads();
;         for (int j = 1; j + 1 < NT; j += 2) {
;             SBAR(); qkt(pB0, pB1, K_lds + SHM_K, qr, r32, hi, comp);
;             finishSM(pA0, pA1, alA, l_reg, pa0, pa1, pa2, pa3); SBAR();
;             SLOAD(SO, (j + 1) * KVBLK); SBAR();
;             pv_d0(o, vb0, pa0, pa1, pa2, pa3); partialSM(pB0, pB1, m_reg, mnB, alB);
;             __syncthreads(); SWAIT(); SWRITE(0, SE);
;             RESC(alB); __syncthreads();
;             SBAR(); qkt(pA0, pA1, K_lds, qr, r32, hi, comp);
;             finishSM(pB0, pB1, alB, l_reg, pa0, pa1, pa2, pa3); SBAR();
;             SLOAD(SE, (j + 2) * KVBLK); SBAR();
;             pv_d0(o, vb0 + (int)SHM_V, pa0, pa1, pa2, pa3); partialSM(pA0, pA1, m_reg, mnA, alA);
	v_mfma_f32_32x32x16_bf16 v[32:47], v[146:149], v[178:181], v[32:47]
	ds_read_b64_tr_b16 v[178:179], v159 offset:0x400
	ds_read_b64_tr_b16 v[180:181], v159 offset:0xc00
	v_mfma_f32_32x32x16_bf16 v[32:47], v[166:169], v[182:185], v[32:47]
	ds_read_b64_tr_b16 v[182:183], v159 offset:0x1400
	ds_read_b64_tr_b16 v[184:185], v159 offset:0x1c00
	v_mfma_f32_32x32x16_bf16 v[32:47], v[170:173], v[186:189], v[32:47]
	ds_read_b64_tr_b16 v[186:187], v159 offset:0x2400
	ds_read_b64_tr_b16 v[188:189], v159 offset:0x2c00
	v_mfma_f32_32x32x16_bf16 v[32:47], v[174:177], v[212:215], v[32:47]
	ds_read_b64_tr_b16 v[212:213], v159 offset:0x3400
	ds_read_b64_tr_b16 v[214:215], v159 offset:0x3c00
	s_waitcnt lgkmcnt(0)
	v_mfma_f32_32x32x16_bf16 v[16:31], v[146:149], v[178:181], v[16:31]
	ds_read_b64_tr_b16 v[178:179], v159 offset:0x600
	ds_read_b64_tr_b16 v[180:181], v159 offset:0xe00
	v_mfma_f32_32x32x16_bf16 v[16:31], v[166:169], v[182:185], v[16:31]
	ds_read_b64_tr_b16 v[182:183], v159 offset:0x1600
	ds_read_b64_tr_b16 v[184:185], v159 offset:0x1e00
	v_mfma_f32_32x32x16_bf16 v[16:31], v[170:173], v[186:189], v[16:31]
	ds_read_b64_tr_b16 v[186:187], v159 offset:0x2600
	ds_read_b64_tr_b16 v[188:189], v159 offset:0x2e00
	v_mfma_f32_32x32x16_bf16 v[16:31], v[174:177], v[212:215], v[16:31]
	ds_read_b64_tr_b16 v[212:213], v159 offset:0x3600
	ds_read_b64_tr_b16 v[214:215], v159 offset:0x3e00
	s_waitcnt lgkmcnt(0)
	v_mfma_f32_32x32x16_bf16 v[0:15], v[146:149], v[178:181], v[0:15]
	v_max_f32_e32 v137, v81, v81
	v_max_f32_e32 v145, v80, v80
	v_max_f32_e32 v137, v145, v137
	v_max3_f32 v137, v137, v82, v83
	v_max3_f32 v137, v137, v84, v85
	v_max3_f32 v137, v137, v86, v87
	v_max3_f32 v137, v137, v88, v89
	v_max3_f32 v137, v137, v90, v91
	v_max3_f32 v137, v137, v92, v93
	v_mfma_f32_32x32x16_bf16 v[0:15], v[166:169], v[182:185], v[0:15]
	v_max3_f32 v137, v137, v94, v95
	v_max3_f32 v137, v137, v64, v65
	v_max3_f32 v137, v137, v66, v67
	v_max3_f32 v137, v137, v68, v69
	v_max3_f32 v137, v137, v70, v71
	v_max3_f32 v137, v137, v72, v73
	v_max3_f32 v137, v137, v74, v75
	v_max3_f32 v137, v137, v76, v77
	v_mfma_f32_32x32x16_bf16 v[0:15], v[170:173], v[186:189], v[0:15]
	v_max3_f32 v137, v137, v78, v79
	v_mov_b32_e32 v145, v137
	s_nop 1
	v_permlane32_swap_b32_e32 v137, v145
	v_max_f32_e32 v145, v145, v145
	v_max_f32_e32 v137, v137, v137
	v_max_f32_e32 v137, v137, v145
	v_sub_f32_e32 v145, v137, v134
	v_cmp_ge_f32_e32 vcc, s65, v145
	v_max_f32_e32 v145, v134, v134
	v_max_f32_e32 v145, v145, v137
	v_mfma_f32_32x32x16_bf16 v[0:15], v[174:177], v[212:215], v[0:15]
	v_sub_f32_e32 v137, v134, v145
	v_mul_f32_e32 v137, 0x3e38aa3b, v137
	v_exp_f32_e32 v137, v137
	s_cmp_eq_u64 vcc, exec
	s_cselect_b64 s[8:9], -1, 0
	s_barrier
	s_waitcnt vmcnt(0)
	v_cndmask_b32_e64 v137, v137, 1.0, s[8:9]
	v_cmp_gt_f32_e32 vcc, 1.0, v137
	s_waitcnt vmcnt(3)
	ds_write_b128 v163, v[114:117] offset:16384
	s_waitcnt vmcnt(1)
	ds_write_b128 v164, v[126:129] offset:16384
	ds_write_b128 v161, v[118:121] offset:49152
	s_waitcnt vmcnt(0)
	ds_write_b128 v162, v[122:125] offset:49152
	s_cbranch_vccz .LBB0_288
	s_and_saveexec_b64 s[2:3], s[6:7]
	ds_write_b32 v157, v137 offset:128
	s_or_b64 exec, exec, s[2:3]
	s_waitcnt lgkmcnt(0)
	ds_read_b128 v[114:117], v158 offset:224
	ds_read_b128 v[118:121], v158 offset:192
	ds_read_b128 v[122:125], v158 offset:160
	ds_read_b128 v[126:129], v158 offset:128
	s_waitcnt lgkmcnt(3)
	v_pk_mul_f32 v[62:63], v[62:63], v[116:117]
	s_waitcnt lgkmcnt(2)
	v_pk_mul_f32 v[58:59], v[58:59], v[120:121]
	s_waitcnt lgkmcnt(1)
	v_pk_mul_f32 v[54:55], v[54:55], v[124:125]
	s_waitcnt lgkmcnt(0)
	v_pk_mul_f32 v[50:51], v[50:51], v[128:129]
	v_pk_mul_f32 v[60:61], v[60:61], v[114:115]
	v_pk_mul_f32 v[56:57], v[56:57], v[118:119]
	v_pk_mul_f32 v[52:53], v[52:53], v[122:123]
	v_pk_mul_f32 v[48:49], v[48:49], v[126:127]
	v_pk_mul_f32 v[46:47], v[46:47], v[116:117]
	v_pk_mul_f32 v[42:43], v[42:43], v[120:121]
	v_pk_mul_f32 v[38:39], v[38:39], v[124:125]
	v_pk_mul_f32 v[34:35], v[34:35], v[128:129]
	v_pk_mul_f32 v[44:45], v[44:45], v[114:115]
	v_pk_mul_f32 v[40:41], v[40:41], v[118:119]
	v_pk_mul_f32 v[36:37], v[36:37], v[122:123]
	v_pk_mul_f32 v[32:33], v[32:33], v[126:127]
	v_pk_mul_f32 v[30:31], v[30:31], v[116:117]
	v_pk_mul_f32 v[26:27], v[26:27], v[120:121]
	v_pk_mul_f32 v[22:23], v[22:23], v[124:125]
	v_pk_mul_f32 v[18:19], v[18:19], v[128:129]
	v_pk_mul_f32 v[28:29], v[28:29], v[114:115]
	v_pk_mul_f32 v[24:25], v[24:25], v[118:119]
	v_pk_mul_f32 v[20:21], v[20:21], v[122:123]
	v_pk_mul_f32 v[16:17], v[16:17], v[126:127]
	v_pk_mul_f32 v[14:15], v[14:15], v[116:117]
	v_pk_mul_f32 v[10:11], v[10:11], v[120:121]
	v_pk_mul_f32 v[6:7], v[6:7], v[124:125]
	v_pk_mul_f32 v[2:3], v[2:3], v[128:129]
	v_pk_mul_f32 v[12:13], v[12:13], v[114:115]
	v_pk_mul_f32 v[8:9], v[8:9], v[118:119]
	v_pk_mul_f32 v[4:5], v[4:5], v[122:123]
	v_pk_mul_f32 v[0:1], v[0:1], v[126:127]
